# v80 + HGRN pass-C forward-direction start-state loads: the 12 loads that waited on the first 4 (address register reused as a load destination) issued together with them via a spare address pair
# baseline (speedup 1.0000x reference)
.LBB0_372:
	s_andn2_b64 vcc, exec, s[2:3]
	s_cbranch_vccnz .LBB0_339
	s_mul_i32 s3, s4, 9
	s_ashr_i32 s2, s3, 1
	s_add_i32 s3, s3, 9
	s_ashr_i32 s3, s3, 1
	v_ashrrev_i32_e32 v0, 6, v205
	s_sub_i32 s3, s3, s2
	v_cmp_gt_i32_e32 vcc, s3, v0
	s_and_saveexec_b64 s[38:39], vcc
	s_cbranch_execz .LBB0_338
	v_add_u32_e32 v0, s2, v0
	s_mov_b32 s2, 0x38e38e39
	v_mul_hi_i32 v2, v0, s2
	v_lshrrev_b32_e32 v3, 31, v2
	v_ashrrev_i32_e32 v2, 3, v2
	v_add_u32_e32 v2, v2, v3
	v_mul_lo_u32 v3, v2, 36
	v_sub_u32_e32 v96, v0, v3
	v_cmp_gt_i32_e64 s[40:41], 4, v96
	s_and_b64 s[2:3], s[18:19], s[40:41]
	v_mov_b32_e32 v1, v236
	s_xor_b64 s[2:3], s[2:3], -1
	s_and_b64 exec, exec, s[2:3]
	s_cbranch_execz .LBB0_338
	v_lshrrev_b32_e32 v0, 6, v1
	s_movk_i32 s2, 0x4d00
	v_mul_lo_u32 v0, v0, s2
	v_add_u32_e32 v92, 16, v0
	v_lshlrev_b32_e32 v0, 6, v2
	v_and_b32_e32 v94, 63, v1
	v_and_b32_e32 v0, 0xc0, v0
	v_or_b32_e32 v3, v94, v0
	v_readlane_b32 s0, v255, 20
	v_lshlrev_b32_e32 v160, 2, v3
	v_readlane_b32 s1, v255, 21
	s_nop 4
	global_load_dword v3, v160, s[0:1]
	global_load_dword v6, v160, s[0:1] offset:2048
	v_lshl_add_u64 v[4:5], s[0:1], 0, v[160:161]
	v_add_co_u32_e32 v4, vcc, 0x1000, v4
	s_mov_b32 s0, 0xf149f2ca
	s_nop 0
	v_addc_co_u32_e32 v5, vcc, 0, v5, vcc
	global_load_dword v8, v[4:5], off
	s_nop 0
	global_load_dword v4, v[4:5], off offset:2048
	v_lshlrev_b32_e32 v148, 1, v2
	v_ashrrev_i32_e32 v97, 31, v96
	v_mov_b32_e32 v99, v161
	v_mov_b32_e32 v101, v161
	v_readlane_b32 s44, v254, 28
	v_readlane_b32 s45, v254, 29
	v_mov_b32_e32 v16, v94
	s_waitcnt vmcnt(2)
	v_max3_f32 v7, v3, s0, v6
	v_readlane_b32 s0, v255, 1
	v_readlane_b32 s1, v255, 2
	s_waitcnt vmcnt(0)
	v_max3_f32 v5, v7, v8, v4
	v_sub_f32_e32 v6, v6, v5
	v_mul_f32_e32 v6, 0x3fb8aa3b, v6
	v_sub_f32_e32 v3, v3, v5
	v_exp_f32_e32 v6, v6
	v_sub_f32_e32 v7, v8, v5
	v_mul_f32_e32 v3, 0x3fb8aa3b, v3
	v_mul_f32_e32 v7, 0x3fb8aa3b, v7
	v_exp_f32_e32 v3, v3
	v_exp_f32_e32 v7, v7
	v_sub_f32_e32 v4, v4, v5
	v_mul_f32_e32 v4, 0x3fb8aa3b, v4
	v_exp_f32_e32 v4, v4
	v_add_f32_e32 v5, 0, v6
	v_cndmask_b32_e64 v5, v5, 0, s[0:1]
	v_readlane_b32 s0, v255, 3
	v_add_f32_e32 v8, v7, v5
	v_readlane_b32 s1, v255, 4
	v_add_f32_e32 v3, 0, v3
	v_add_f32_e32 v3, v6, v3
	v_cndmask_b32_e64 v5, v8, v5, s[0:1]
	v_readlane_b32 s0, v255, 5
	v_add_f32_e32 v8, v4, v5
	v_readlane_b32 s1, v255, 6
	v_add_f32_e32 v3, v7, v3
	v_add_f32_e32 v3, v4, v3
	v_cndmask_b32_e64 v5, v8, v5, s[0:1]
	v_div_scale_f32 v4, s[2:3], v3, v3, v5
	v_rcp_f32_e32 v6, v4
	v_readlane_b32 s0, v255, 22
	v_readlane_b32 s1, v255, 23
	v_fma_f32 v7, -v4, v6, 1.0
	v_fmac_f32_e32 v6, v7, v6
	v_div_scale_f32 v7, vcc, v5, v3, v5
	v_mul_f32_e32 v8, v7, v6
	v_fma_f32 v9, -v4, v8, v7
	v_fmac_f32_e32 v8, v9, v6
	v_fma_f32 v4, -v4, v8, v7
	v_div_fmas_f32 v4, v4, v6, v8
	v_div_fixup_f32 v149, v4, v3, v5
	v_ashrrev_i32_e32 v6, 2, v2
	v_mad_i64_i32 v[2:3], s[2:3], v148, 36, v[96:97]
	v_lshlrev_b64 v[2:3], 13, v[2:3]
	v_lshlrev_b32_e32 v4, 7, v1
	v_lshl_add_u64 v[2:3], s[0:1], 0, v[2:3]
	v_and_b32_e32 v98, 0xf80, v4
	v_lshrrev_b32_e32 v1, 2, v1
	v_lshl_add_u64 v[2:3], v[2:3], 0, v[98:99]
	v_and_b32_e32 v100, 8, v1
	v_lshl_add_u64 v[2:3], v[2:3], 0, v[100:101]
	global_load_dwordx2 v[42:43], v[2:3], off
	global_load_dwordx2 v[36:37], v[2:3], off offset:16
	global_load_dwordx2 v[34:35], v[2:3], off offset:32
	global_load_dwordx2 v[4:5], v[2:3], off offset:48
	s_movk_i32 s0, 0x1000
	v_add_co_u32_e32 v206, vcc, s0, v2
	s_nop 1
	v_addc_co_u32_e32 v207, vcc, 0, v3, vcc
	global_load_dwordx2 v[52:53], v[206:207], off
	global_load_dwordx2 v[50:51], v[206:207], off offset:16
	global_load_dwordx2 v[48:49], v[206:207], off offset:32
	global_load_dwordx2 v[38:39], v[206:207], off offset:48
	global_load_dwordx2 v[60:61], v[2:3], off offset:64
	global_load_dwordx2 v[58:59], v[2:3], off offset:80
	global_load_dwordx2 v[56:57], v[2:3], off offset:96
	global_load_dwordx2 v[54:55], v[2:3], off offset:112
	global_load_dwordx2 v[26:27], v[206:207], off offset:64
	global_load_dwordx2 v[28:29], v[206:207], off offset:80
	global_load_dwordx2 v[30:31], v[206:207], off offset:96
	global_load_dwordx2 v[32:33], v[206:207], off offset:112
	v_mov_b32_e32 v1, 0xffffff00
	v_lshl_add_u32 v1, v6, 11, v1
	s_mov_b64 s[2:3], s[44:45]
	v_sub_f32_e32 v80, 1.0, v149
	s_waitcnt vmcnt(13)
	v_lshlrev_b32_e32 v40, 16, v35
	s_waitcnt vmcnt(12)
	v_lshlrev_b32_e32 v44, 16, v4
	v_and_b32_e32 v45, 0xffff0000, v4
	v_add_co_u32_e32 v4, vcc, s0, v2
	v_lshlrev_b32_e32 v46, 16, v5
	v_and_b32_e32 v47, 0xffff0000, v5
	v_addc_co_u32_e32 v5, vcc, 0, v3, vcc
	v_mov_b32_e32 v2, 0x4000
	v_lshl_add_u32 v2, v6, 8, v2
	v_cndmask_b32_e64 v1, v1, v2, s[40:41]
	v_lshl_add_u32 v93, v96, 6, v1
	v_and_b32_e32 v41, 0xffff0000, v35
	v_ashrrev_i32_e32 v89, 31, v93
	v_and_b32_e32 v35, 31, v16
	v_ashrrev_i32_e32 v81, 5, v16
	v_mov_b64_e32 v[2:3], s[2:3]
	s_movk_i32 s0, 0x1200
	v_mad_i64_i32 v[2:3], s[4:5], v93, s0, v[2:3]
	v_lshlrev_b32_e32 v90, 1, v0
	v_mov_b32_e32 v91, v161
	v_ashrrev_i32_e32 v17, 31, v16
	v_lshl_add_u64 v[0:1], v[2:3], 0, v[90:91]
	v_lshl_add_u64 v[18:19], v[16:17], 1, v[0:1]
	s_mov_b64 s[0:1], 0xb200000
	v_lshl_add_u64 v[0:1], v[18:19], 0, s[0:1]
	global_load_ushort v15, v[0:1], off offset:3072
	global_load_ushort v66, v[0:1], off offset:2048
	s_mov_b32 s7, 0xb202000
	v_add_co_u32_e32 v2, vcc, s7, v18
	s_mov_b32 s11, 0xb205000
	s_nop 0
	v_addc_co_u32_e32 v3, vcc, 0, v19, vcc
	v_add_co_u32_e32 v4, vcc, s11, v18
	s_mov_b32 s12, 0xb207000
	s_nop 0
	v_addc_co_u32_e32 v5, vcc, 0, v19, vcc
	v_add_co_u32_e32 v6, vcc, s12, v18
	s_mov_b32 s13, 0xb209000
	s_nop 0
	v_addc_co_u32_e32 v7, vcc, 0, v19, vcc
	v_add_co_u32_e32 v8, vcc, s13, v18
	s_mov_b32 s14, 0xb20b000
	s_nop 0
	v_addc_co_u32_e32 v9, vcc, 0, v19, vcc
	v_add_co_u32_e32 v10, vcc, s14, v18
	s_mov_b32 s15, 0xb20e000
	s_nop 0
	v_addc_co_u32_e32 v11, vcc, 0, v19, vcc
	v_add_co_u32_e32 v62, vcc, s15, v18
	s_mov_b32 s18, 0xb210000
	s_nop 0
	v_addc_co_u32_e32 v63, vcc, 0, v19, vcc
	v_add_co_u32_e32 v64, vcc, s18, v18
	s_mov_b32 s19, 0xb212000
	s_nop 0
	v_addc_co_u32_e32 v65, vcc, 0, v19, vcc
	v_add_co_u32_e32 v76, vcc, s19, v18
	s_mov_b32 s21, 0xb214000
	s_nop 0
	v_addc_co_u32_e32 v77, vcc, 0, v19, vcc
	v_add_co_u32_e32 v102, vcc, s21, v18
	s_mov_b32 s30, 0xb217000
	s_nop 0
	v_addc_co_u32_e32 v103, vcc, 0, v19, vcc
	global_load_ushort v88, v[4:5], off offset:1024
	global_load_ushort v95, v[4:5], off
	global_load_ushort v104, v[2:3], off offset:3072
	global_load_ushort v14, v[4:5], off offset:512
	global_load_ushort v13, v[2:3], off offset:3584
	global_load_ushort v12, v[0:1], off offset:2560
	v_add_co_u32_e32 v78, vcc, s30, v18
	s_mov_b32 s9, 0xc1f00000
	s_nop 0
	v_addc_co_u32_e32 v79, vcc, 0, v19, vcc
	s_mov_b32 s31, 0xb219000
	v_add_co_u32_e32 v82, vcc, s31, v18
	s_mov_b32 s34, 0xb21b000
	s_nop 0
	v_addc_co_u32_e32 v83, vcc, 0, v19, vcc
	v_add_co_u32_e32 v20, vcc, s34, v18
	s_mov_b32 s35, 0xb21d000
	s_nop 0
	v_addc_co_u32_e32 v21, vcc, 0, v19, vcc
	v_add_co_u32_e32 v68, vcc, s35, v18
	s_mov_b32 s36, 0xb220000
	s_nop 0
	v_addc_co_u32_e32 v69, vcc, 0, v19, vcc
	v_add_co_u32_e32 v22, vcc, s36, v18
	s_mov_b32 s37, 0xb222000
	s_nop 0
	v_addc_co_u32_e32 v23, vcc, 0, v19, vcc
	v_add_co_u32_e32 v24, vcc, s37, v18
	s_mov_b32 s40, 0xb201000
	s_nop 0
	v_addc_co_u32_e32 v25, vcc, 0, v19, vcc
	s_waitcnt vmcnt(7)
	v_lshlrev_b32_e32 v0, 16, v15
	v_max_f32_e32 v0, v0, v0
	v_med3_f32 v0, v0, s9, v244
	v_mul_f32_e32 v0, 0xbfb8aa3b, v0
	v_exp_f32_e32 v86, v0
	v_add_co_u32_e32 v0, vcc, s40, v18
	s_mov_b32 s41, 0xb203000
	v_add_f32_e32 v2, 1.0, v86
	v_rcp_f32_e32 v118, v2
	v_addc_co_u32_e32 v1, vcc, 0, v19, vcc
	s_waitcnt vmcnt(6)
	v_lshlrev_b32_e32 v4, 16, v66
	v_fma_f32 v5, v80, v118, v149
	v_max_f32_e32 v15, 0xda24260, v5
	v_add_co_u32_e32 v2, vcc, s41, v18
	v_mul_f32_e32 v4, v15, v4
	s_nop 0
	v_addc_co_u32_e32 v3, vcc, 0, v19, vcc
	v_bfe_u32 v5, v4, 16, 1
	s_movk_i32 s10, 0x7fff
	s_mov_b32 s46, 0xb204000
	v_add3_u32 v105, v4, v5, s10
	v_add_co_u32_e32 v4, vcc, s46, v18
	s_mov_b32 s28, 0xb206000
	s_nop 0
	v_addc_co_u32_e32 v5, vcc, 0, v19, vcc
	global_load_ushort v106, v[4:5], off offset:-4096
	global_load_ushort v107, v[4:5], off offset:512
	global_load_ushort v87, v[0:1], off offset:3584
	global_load_ushort v110, v[0:1], off offset:2560
	global_load_ushort v111, v[2:3], off offset:3584
	v_add_co_u32_e32 v2, vcc, s28, v18
	s_mov_b32 s29, 0xb208000
	s_nop 0
	v_addc_co_u32_e32 v3, vcc, 0, v19, vcc
	global_load_ushort v156, v[6:7], off offset:1536
	global_load_ushort v157, v[8:9], off offset:2560
	global_load_ushort v158, v[10:11], off offset:3584
	global_load_ushort v116, v[6:7], off offset:2048
	global_load_ushort v117, v[8:9], off offset:3072
	global_load_ushort v121, v[10:11], off offset:3072
	global_load_ushort v120, v[8:9], off offset:2048
	global_load_ushort v126, v[6:7], off offset:1024
	v_add_co_u32_e32 v6, vcc, s29, v18
	s_mov_b32 s42, 0xb20a000
	s_nop 0
	v_addc_co_u32_e32 v7, vcc, 0, v19, vcc
	v_add_co_u32_e32 v8, vcc, s42, v18
	s_mov_b32 s6, 0xb20c000
	s_nop 0
	v_addc_co_u32_e32 v9, vcc, 0, v19, vcc
	v_add_co_u32_e32 v10, vcc, s6, v18
	s_mov_b32 s49, 0xb20d000
	s_nop 0
	v_addc_co_u32_e32 v11, vcc, 0, v19, vcc
	v_add_co_u32_e32 v66, vcc, s49, v18
	s_mov_b32 s4, 0xb20f000
	s_nop 0
	v_addc_co_u32_e32 v67, vcc, 0, v19, vcc
	v_add_co_u32_e32 v74, vcc, s4, v18
	s_mov_b32 s4, 0xb211000
	s_nop 0
	v_addc_co_u32_e32 v75, vcc, 0, v19, vcc
	v_add_co_u32_e32 v84, vcc, s4, v18
	s_mov_b32 s4, 0xb223000
	s_nop 0
	v_addc_co_u32_e32 v85, vcc, 0, v19, vcc
	global_load_ushort v159, v[62:63], off offset:512
	global_load_ushort v162, v[64:65], off offset:1536
	global_load_ushort v163, v[76:77], off offset:2560
	global_load_ushort v164, v[102:103], off offset:3584
	global_load_ushort v127, v[62:63], off offset:1024
	global_load_ushort v137, v[64:65], off offset:2048
	global_load_ushort v141, v[64:65], off offset:1024
	global_load_ushort v131, v[62:63], off
	v_add_co_u32_e32 v62, vcc, s4, v18
	s_mov_b32 s4, 0xb221000
	s_nop 0
	v_addc_co_u32_e32 v63, vcc, 0, v19, vcc
	v_add_co_u32_e32 v64, vcc, s4, v18
	s_mov_b32 s4, 0xb21f000
	s_nop 0
	v_addc_co_u32_e32 v65, vcc, 0, v19, vcc
	v_add_co_u32_e32 v70, vcc, s4, v18
	s_mov_b32 s97, 0xb21c000
	s_nop 0
	v_addc_co_u32_e32 v71, vcc, 0, v19, vcc
	v_add_co_u32_e32 v72, vcc, s97, v18
	s_mov_b32 s4, 0xb21a000
	s_nop 0
	v_addc_co_u32_e32 v73, vcc, 0, v19, vcc
	v_add_co_u32_e32 v108, vcc, s4, v18
	s_mov_b32 s48, 0xb218000
	s_nop 0
	v_addc_co_u32_e32 v109, vcc, 0, v19, vcc
	v_add_co_u32_e32 v112, vcc, s48, v18
	s_mov_b32 s47, 0xb216000
	s_nop 0
	v_addc_co_u32_e32 v113, vcc, 0, v19, vcc
	v_add_co_u32_e32 v114, vcc, s47, v18
	s_mov_b32 s43, 0xb213000
	s_nop 0
	v_addc_co_u32_e32 v115, vcc, 0, v19, vcc
	v_add_co_u32_e32 v124, vcc, s43, v18
	global_load_ushort v165, v[78:79], off offset:512
	global_load_ushort v166, v[82:83], off offset:1536
	global_load_ushort v167, v[20:21], off offset:2560
	global_load_ushort v168, v[68:69], off offset:3584
	global_load_ushort v169, v[22:23], off offset:512
	global_load_ushort v170, v[24:25], off offset:1536
	global_load_ushort v171, v[22:23], off offset:-4096
	global_load_ushort v172, v[78:79], off offset:-4096
	v_addc_co_u32_e32 v125, vcc, 0, v19, vcc
	global_load_ushort v128, v[66:67], off offset:-4096
	global_load_ushort v129, v[66:67], off offset:512
	global_load_ushort v173, v[112:113], off offset:1024
	s_nop 0
	global_load_ushort v66, v[66:67], off
	s_nop 0
	global_load_ushort v67, v[4:5], off
	s_nop 0
	global_load_ushort v4, v[124:125], off offset:3072
	global_load_ushort v5, v[2:3], off offset:1536
	global_load_ushort v130, v[2:3], off offset:512
	global_load_ushort v136, v[6:7], off offset:1536
	global_load_ushort v174, v[2:3], off offset:1024
	global_load_ushort v175, v[0:1], off offset:3072
	s_waitcnt vmcnt(37)
	v_lshlrev_b32_e32 v0, 16, v87
	v_max_f32_e32 v0, v0, v0
	v_med3_f32 v0, v0, s9, v244
	v_mul_f32_e32 v0, 0xbfb8aa3b, v0
	v_exp_f32_e32 v87, v0
	global_load_ushort v0, v[74:75], off offset:1536
	global_load_ushort v1, v[84:85], off offset:2560
	global_load_ushort v2, v[84:85], off offset:1536
	global_load_ushort v3, v[62:63], off offset:2048
	global_load_ushort v176, v[64:65], off offset:1024
	global_load_ushort v177, v[72:73], off offset:3072
	global_load_ushort v178, v[108:109], off offset:2048
	global_load_ushort v179, v[84:85], off offset:2048
	global_load_ushort v138, v[6:7], off offset:2560
	global_load_ushort v139, v[8:9], off offset:3584
	global_load_ushort v140, v[8:9], off offset:2560
	s_nop 0
	global_load_ushort v10, v[10:11], off offset:3584
	s_nop 0
	global_load_ushort v11, v[74:75], off offset:512
	global_load_ushort v180, v[74:75], off offset:1024
	s_nop 0
	global_load_ushort v8, v[8:9], off offset:3072
	s_nop 0
	global_load_ushort v181, v[6:7], off offset:2048
	v_lshlrev_b32_e32 v7, 16, v106
	v_max_f32_e32 v7, v7, v7
	v_add_f32_e32 v84, 1.0, v87
	v_med3_f32 v7, v7, s9, v244
	v_rcp_f32_e32 v119, v84
	v_mul_f32_e32 v7, 0xbfb8aa3b, v7
	v_exp_f32_e32 v84, v7
	s_waitcnt vmcnt(52)
	v_lshlrev_b32_e32 v7, 16, v110
	v_fma_f32 v6, v80, v119, v149
	v_mul_f32_e32 v6, v15, v6
	v_add_f32_e32 v9, 1.0, v84
	v_max_f32_e32 v6, 0xda24260, v6
	v_rcp_f32_e32 v132, v9
	v_mul_f32_e32 v7, v6, v7
	v_bfe_u32 v9, v7, 16, 1
	v_lshl_add_u32 v17, v16, 1, v92
	v_add3_u32 v7, v7, v9, s10
	ds_write_b16_d16_hi v17, v7 offset:144
	v_fma_f32 v7, v80, v132, v149
	v_rcp_f32_e32 v123, v6
	v_mul_f32_e32 v6, v6, v7
	v_lshlrev_b32_e32 v7, 16, v107
	v_max_f32_e32 v7, v7, v7
	v_med3_f32 v7, v7, s9, v244
	v_mul_f32_e32 v7, 0xbfb8aa3b, v7
	v_exp_f32_e32 v85, v7
	v_max_f32_e32 v6, 0xda24260, v6
	v_lshlrev_b32_e32 v7, 16, v104
	v_mul_f32_e32 v7, v6, v7
	v_add_f32_e32 v9, 1.0, v85
	v_rcp_f32_e32 v133, v9
	v_bfe_u32 v9, v7, 16, 1
	v_add3_u32 v7, v7, v9, s10
	ds_write_b16_d16_hi v17, v7 offset:288
	v_fma_f32 v7, v80, v133, v149
	v_rcp_f32_e32 v134, v6
	v_mul_f32_e32 v6, v6, v7
	v_lshlrev_b32_e32 v7, 16, v88
	v_max_f32_e32 v7, v7, v7
	v_med3_f32 v7, v7, s9, v244
	v_mul_f32_e32 v7, 0xbfb8aa3b, v7
	v_exp_f32_e32 v74, v7
	v_max_f32_e32 v6, 0xda24260, v6
	s_waitcnt vmcnt(51)
	v_lshlrev_b32_e32 v7, 16, v111
	v_mul_f32_e32 v7, v6, v7
	v_add_f32_e32 v9, 1.0, v74
	v_rcp_f32_e32 v144, v9
	v_bfe_u32 v9, v7, 16, 1
	v_add3_u32 v7, v7, v9, s10
	ds_write_b16_d16_hi v17, v7 offset:432
	v_fma_f32 v7, v80, v144, v149
	v_rcp_f32_e32 v135, v6
	v_mul_f32_e32 v6, v6, v7
	v_max_f32_e32 v6, 0xda24260, v6
	v_rcp_f32_e32 v146, v6
	ds_write_b16_d16_hi v17, v105
	v_rcp_f32_e32 v122, v15
	v_pk_mul_f32 v[84:85], v[84:85], v[132:133]
	v_pk_mul_f32 v[86:87], v[86:87], v[118:119]
	v_pk_mul_f32 v[84:85], v[80:81], v[84:85] op_sel_hi:[0,1]
	v_pk_mul_f32 v[86:87], v[80:81], v[86:87] op_sel_hi:[0,1]
	s_movk_i32 s4, 0x50
	v_pk_mul_f32 v[84:85], v[84:85], v[134:135]
	v_pk_mul_f32 v[86:87], v[86:87], v[122:123]
	v_and_b32_sdwa v132, v85, v239 dst_sel:DWORD dst_unused:UNUSED_PAD src0_sel:WORD_1 src1_sel:DWORD
	s_waitcnt vmcnt(23)
	v_lshl_or_b32 v9, v66, 16, v158
	s_waitcnt vmcnt(22)
	v_lshl_or_b32 v13, v67, 16, v13
	v_mad_u64_u32 v[66:67], s[4:5], v16, s4, v[92:93]
	s_waitcnt vmcnt(20)
	v_lshlrev_b32_e32 v5, 16, v5
	v_max_f32_e32 v5, v5, v5
	v_med3_f32 v5, v5, s9, v244
	v_mul_f32_e32 v5, 0xbfb8aa3b, v5
	v_exp_f32_e32 v75, v5
	v_lshlrev_b32_e32 v5, 16, v95
	v_mul_f32_e32 v5, v6, v5
	s_waitcnt vmcnt(15)
	v_lshlrev_b32_e32 v0, 16, v0
	v_add_f32_e32 v7, 1.0, v75
	v_rcp_f32_e32 v145, v7
	v_bfe_u32 v7, v5, 16, 1
	v_add3_u32 v5, v5, v7, s10
	ds_write_b16_d16_hi v17, v5 offset:576
	v_fma_f32 v5, v80, v145, v149
	v_mul_f32_e32 v5, v6, v5
	v_lshlrev_b32_e32 v6, 16, v116
	v_max_f32_e32 v6, v6, v6
	v_med3_f32 v6, v6, s9, v244
	v_mul_f32_e32 v6, 0xbfb8aa3b, v6
	v_exp_f32_e32 v150, v6
	v_max_f32_e32 v5, 0xda24260, v5
	v_lshlrev_b32_e32 v6, 16, v130
	v_mul_f32_e32 v6, v5, v6
	v_add_f32_e32 v7, 1.0, v150
	v_rcp_f32_e32 v152, v7
	v_bfe_u32 v7, v6, 16, 1
	v_add3_u32 v6, v6, v7, s10
	ds_write_b16_d16_hi v17, v6 offset:720
	v_fma_f32 v6, v80, v152, v149
	v_rcp_f32_e32 v147, v5
	v_mul_f32_e32 v5, v5, v6
	s_waitcnt vmcnt(7)
	v_lshlrev_b32_e32 v6, 16, v138
	v_max_f32_e32 v6, v6, v6
	v_med3_f32 v6, v6, s9, v244
	v_mul_f32_e32 v6, 0xbfb8aa3b, v6
	v_exp_f32_e32 v151, v6
	v_max_f32_e32 v5, 0xda24260, v5
	v_lshlrev_b32_e32 v6, 16, v126
	v_mul_f32_e32 v6, v5, v6
	v_add_f32_e32 v7, 1.0, v151
	v_rcp_f32_e32 v153, v7
	v_bfe_u32 v7, v6, 16, 1
	v_add3_u32 v6, v6, v7, s10
	ds_write_b16_d16_hi v17, v6 offset:864
	v_fma_f32 v6, v80, v153, v149
	v_rcp_f32_e32 v154, v5
	v_mul_f32_e32 v5, v5, v6
	v_lshlrev_b32_e32 v6, 16, v117
	v_max_f32_e32 v6, v6, v6
	v_med3_f32 v6, v6, s9, v244
	v_mul_f32_e32 v6, 0xbfb8aa3b, v6
	v_exp_f32_e32 v104, v6
	v_max_f32_e32 v5, 0xda24260, v5
	v_lshlrev_b32_e32 v6, 16, v136
	v_mul_f32_e32 v6, v5, v6
	v_add_f32_e32 v7, 1.0, v104
	v_rcp_f32_e32 v106, v7
	v_bfe_u32 v7, v6, 16, 1
	v_add3_u32 v6, v6, v7, s10
	ds_write_b16_d16_hi v17, v6 offset:1008
	v_fma_f32 v6, v80, v106, v149
	v_rcp_f32_e32 v155, v5
	v_mul_f32_e32 v5, v5, v6
	s_waitcnt vmcnt(6)
	v_lshlrev_b32_e32 v6, 16, v139
	v_max_f32_e32 v6, v6, v6
	v_med3_f32 v6, v6, s9, v244
	v_mul_f32_e32 v6, 0xbfb8aa3b, v6
	v_exp_f32_e32 v105, v6
	v_max_f32_e32 v5, 0xda24260, v5
	v_lshlrev_b32_e32 v6, 16, v120
	v_mul_f32_e32 v6, v5, v6
	v_add_f32_e32 v7, 1.0, v105
	v_rcp_f32_e32 v107, v7
	v_bfe_u32 v7, v6, 16, 1
	v_add3_u32 v88, v6, v7, s10
	v_rcp_f32_e32 v110, v5
	v_fma_f32 v6, v80, v107, v149
	v_mul_f32_e32 v5, v5, v6
	v_lshlrev_b32_e32 v6, 16, v128
	v_max_f32_e32 v6, v6, v6
	v_med3_f32 v6, v6, s9, v244
	v_mul_f32_e32 v6, 0xbfb8aa3b, v6
	v_exp_f32_e32 v116, v6
	v_max_f32_e32 v5, 0xda24260, v5
	s_waitcnt vmcnt(5)
	v_lshlrev_b32_e32 v6, 16, v140
	v_mul_f32_e32 v6, v5, v6
	v_add_f32_e32 v7, 1.0, v116
	v_rcp_f32_e32 v120, v7
	v_bfe_u32 v7, v6, 16, 1
	v_add3_u32 v95, v6, v7, s10
	v_rcp_f32_e32 v111, v5
	v_fma_f32 v6, v80, v120, v149
	v_mul_f32_e32 v5, v5, v6
	v_lshlrev_b32_e32 v6, 16, v129
	v_max_f32_e32 v6, v6, v6
	v_med3_f32 v6, v6, s9, v244
	v_mul_f32_e32 v6, 0xbfb8aa3b, v6
	v_exp_f32_e32 v117, v6
	v_lshlrev_b32_e32 v6, 16, v121
	v_max_f32_e32 v5, 0xda24260, v5
	v_mul_f32_e32 v6, v5, v6
	v_add_f32_e32 v7, 1.0, v117
	v_rcp_f32_e32 v121, v7
	v_bfe_u32 v7, v6, 16, 1
	v_add3_u32 v182, v6, v7, s10
	v_rcp_f32_e32 v126, v5
	v_fma_f32 v6, v80, v121, v149
	v_mul_f32_e32 v5, v5, v6
	v_lshlrev_b32_e32 v6, 16, v127
	v_max_f32_e32 v6, v6, v6
	v_med3_f32 v6, v6, s9, v244
	v_mul_f32_e32 v6, 0xbfb8aa3b, v6
	v_exp_f32_e32 v128, v6
	v_max_f32_e32 v0, v0, v0
	v_med3_f32 v0, v0, s9, v244
	v_mul_f32_e32 v0, 0xbfb8aa3b, v0
	v_add_f32_e32 v7, 1.0, v128
	v_rcp_f32_e32 v130, v7
	v_max_f32_e32 v5, 0xda24260, v5
	s_waitcnt vmcnt(4)
	v_lshlrev_b32_e32 v6, 16, v10
	v_exp_f32_e32 v129, v0
	v_mul_f32_e32 v6, v5, v6
	v_bfe_u32 v7, v6, 16, 1
	v_add3_u32 v183, v6, v7, s10
	v_fma_f32 v6, v80, v130, v149
	v_rcp_f32_e32 v127, v5
	v_mul_f32_e32 v5, v5, v6
	v_add_f32_e32 v6, 1.0, v129
	v_max_f32_e32 v0, 0xda24260, v5
	v_lshlrev_b32_e32 v5, 16, v131
	v_rcp_f32_e32 v131, v6
	v_mul_f32_e32 v5, v0, v5
	v_bfe_u32 v6, v5, 16, 1
	v_add3_u32 v184, v5, v6, s10
	v_fma_f32 v5, v80, v131, v149
	v_rcp_f32_e32 v136, v0
	v_mul_f32_e32 v0, v0, v5
	v_lshlrev_b32_e32 v5, 16, v137
	v_max_f32_e32 v5, v5, v5
	v_med3_f32 v5, v5, s9, v244
	v_mul_f32_e32 v5, 0xbfb8aa3b, v5
	v_exp_f32_e32 v138, v5
	v_lshlrev_b32_e32 v1, 16, v1
	v_max_f32_e32 v1, v1, v1
	v_med3_f32 v1, v1, s9, v244
	v_add_f32_e32 v6, 1.0, v138
	v_rcp_f32_e32 v140, v6
	v_mul_f32_e32 v1, 0xbfb8aa3b, v1
	v_max_f32_e32 v0, 0xda24260, v0
	s_waitcnt vmcnt(3)
	v_lshlrev_b32_e32 v5, 16, v11
	v_exp_f32_e32 v139, v1
	v_mul_f32_e32 v5, v0, v5
	v_bfe_u32 v6, v5, 16, 1
	v_add3_u32 v185, v5, v6, s10
	v_fma_f32 v5, v80, v140, v149
	v_rcp_f32_e32 v137, v0
	v_mul_f32_e32 v0, v0, v5
	v_add_f32_e32 v5, 1.0, v139
	v_lshlrev_b32_e32 v1, 16, v141
	v_rcp_f32_e32 v141, v5
	v_max_f32_e32 v0, 0xda24260, v0
	v_mul_f32_e32 v1, v0, v1
	v_bfe_u32 v5, v1, 16, 1
	v_add3_u32 v186, v1, v5, s10
	v_fma_f32 v1, v80, v141, v149
	v_pk_mul_f32 v[150:151], v[150:151], v[152:153]
	v_pk_mul_f32 v[74:75], v[74:75], v[144:145]
	v_rcp_f32_e32 v142, v0
	v_mul_f32_e32 v0, v0, v1
	v_pk_mul_f32 v[150:151], v[80:81], v[150:151] op_sel_hi:[0,1]
	v_pk_mul_f32 v[74:75], v[80:81], v[74:75] op_sel_hi:[0,1]
	v_max_f32_e32 v187, 0xda24260, v0
	v_lshlrev_b32_e32 v0, 16, v2
	v_pk_mul_f32 v[150:151], v[150:151], v[154:155]
	v_pk_mul_f32 v[74:75], v[74:75], v[146:147]
	v_mul_f32_e32 v0, v187, v0
	v_and_b32_sdwa v152, v150, v239 dst_sel:DWORD dst_unused:UNUSED_PAD src0_sel:WORD_1 src1_sel:DWORD
	v_and_b32_sdwa v144, v75, v239 dst_sel:DWORD dst_unused:UNUSED_PAD src0_sel:WORD_1 src1_sel:DWORD
	v_and_b32_sdwa v145, v74, v239 dst_sel:DWORD dst_unused:UNUSED_PAD src0_sel:WORD_1 src1_sel:DWORD
	v_and_b32_sdwa v133, v84, v239 dst_sel:DWORD dst_unused:UNUSED_PAD src0_sel:WORD_1 src1_sel:DWORD
	v_and_b32_sdwa v118, v87, v239 dst_sel:DWORD dst_unused:UNUSED_PAD src0_sel:WORD_1 src1_sel:DWORD
	v_and_b32_sdwa v119, v86, v239 dst_sel:DWORD dst_unused:UNUSED_PAD src0_sel:WORD_1 src1_sel:DWORD
	v_bfe_u32 v1, v0, 16, 1
	v_and_b32_sdwa v67, v151, v239 dst_sel:DWORD dst_unused:UNUSED_PAD src0_sel:WORD_1 src1_sel:DWORD
	v_add3_u32 v150, v150, v152, s10
	v_add3_u32 v75, v75, v144, s10
	v_add3_u32 v74, v74, v145, s10
	v_add3_u32 v85, v85, v132, s10
	v_add3_u32 v84, v84, v133, s10
	v_add3_u32 v87, v87, v118, s10
	v_add3_u32 v86, v86, v119, s10
	v_rcp_f32_e32 v143, v187
	v_add3_u32 v188, v0, v1, s10
	v_lshl_or_b32 v3, v3, 16, v170
	v_lshl_or_b32 v2, v176, 16, v169
	v_lshl_or_b32 v1, v171, 16, v168
	v_lshl_or_b32 v0, v177, 16, v167
	v_lshl_or_b32 v7, v178, 16, v166
	v_lshl_or_b32 v6, v173, 16, v165
	v_lshl_or_b32 v5, v172, 16, v164
	v_lshl_or_b32 v4, v4, 16, v163
	v_lshl_or_b32 v11, v179, 16, v162
	s_waitcnt vmcnt(2)
	v_lshl_or_b32 v10, v180, 16, v159
	s_waitcnt vmcnt(1)
	v_lshl_or_b32 v8, v8, 16, v157
	s_waitcnt vmcnt(0)
	v_lshl_or_b32 v15, v181, 16, v156
	v_lshl_or_b32 v14, v174, 16, v14
	v_lshl_or_b32 v12, v175, 16, v12
	s_movk_i32 s16, 0x50
	v_add3_u32 v67, v151, v67, s10
	ds_write_b16_d16_hi v17, v150 offset:5472
	ds_write_b16_d16_hi v17, v67 offset:5616
	ds_write_b16_d16_hi v17, v74 offset:5184
	ds_write_b16_d16_hi v17, v75 offset:5328
	v_and_b32_e32 v75, 0xffff0000, v75
	v_and_b32_e32 v74, 0xffff0000, v74
	ds_write_b16_d16_hi v17, v84 offset:4896
	ds_write_b16_d16_hi v17, v85 offset:5040
	v_and_b32_e32 v85, 0xffff0000, v85
	v_and_b32_e32 v84, 0xffff0000, v84
	ds_write_b16_d16_hi v17, v86 offset:4608
	ds_write_b16_d16_hi v17, v87 offset:4752
	v_and_b32_e32 v87, 0xffff0000, v87
	v_and_b32_e32 v86, 0xffff0000, v86
	global_load_ushort v118, v[76:77], off offset:3072
	s_nop 0
	global_load_ushort v102, v[102:103], off offset:3072
	s_nop 0
	global_load_ushort v103, v[78:79], off offset:1024
	global_load_ushort v119, v[82:83], off offset:1024
	global_load_ushort v123, v[82:83], off offset:2048
	s_nop 0
	global_load_ushort v78, v[78:79], off
	s_nop 0
	global_load_ushort v79, v[76:77], off offset:2048
	global_load_ushort v82, v[124:125], off offset:3584
	s_mov_b32 s5, 0xb215000
	v_add_co_u32_e32 v76, vcc, s5, v18
	v_pk_mul_f32 v[138:139], v[138:139], v[140:141]
	s_nop 0
	v_addc_co_u32_e32 v77, vcc, 0, v19, vcc
	global_load_ushort v83, v[76:77], off
	s_nop 0
	global_load_ushort v76, v[76:77], off offset:3584
	s_nop 0
	global_load_ushort v77, v[124:125], off offset:2560
	s_nop 0
	global_load_ushort v114, v[114:115], off offset:512
	s_nop 0
	global_load_ushort v115, v[112:113], off offset:1536
	global_load_ushort v144, v[108:109], off offset:1536
	ds_write_b16_d16_hi v17, v88 offset:1152
	ds_write_b16_d16_hi v17, v95 offset:1296
	ds_write_b16_d16_hi v17, v182 offset:1440
	ds_write_b16_d16_hi v17, v183 offset:1584
	ds_write_b16_d16_hi v17, v184 offset:1728
	ds_write_b16_d16_hi v17, v185 offset:1872
	ds_write_b16_d16_hi v17, v186 offset:2016
	ds_write_b16_d16_hi v17, v188 offset:2160
	global_load_ushort v88, v[112:113], off offset:512
	global_load_ushort v95, v[108:109], off offset:2560
	v_pk_mul_f32 v[128:129], v[128:129], v[130:131]
	v_pk_mul_f32 v[116:117], v[116:117], v[120:121]
	v_pk_mul_f32 v[104:105], v[104:105], v[106:107]
	v_pk_mul_f32 v[138:139], v[80:81], v[138:139] op_sel_hi:[0,1]
	v_pk_mul_f32 v[128:129], v[80:81], v[128:129] op_sel_hi:[0,1]
	v_pk_mul_f32 v[116:117], v[80:81], v[116:117] op_sel_hi:[0,1]
	v_pk_mul_f32 v[104:105], v[80:81], v[104:105] op_sel_hi:[0,1]
	v_pk_mul_f32 v[138:139], v[138:139], v[142:143]
	v_pk_mul_f32 v[128:129], v[128:129], v[136:137]
	v_pk_mul_f32 v[116:117], v[116:117], v[126:127]
	v_pk_mul_f32 v[104:105], v[104:105], v[110:111]
	v_and_b32_sdwa v140, v138, v239 dst_sel:DWORD dst_unused:UNUSED_PAD src0_sel:WORD_1 src1_sel:DWORD
	v_and_b32_sdwa v130, v129, v239 dst_sel:DWORD dst_unused:UNUSED_PAD src0_sel:WORD_1 src1_sel:DWORD
	v_and_b32_sdwa v131, v128, v239 dst_sel:DWORD dst_unused:UNUSED_PAD src0_sel:WORD_1 src1_sel:DWORD
	v_and_b32_sdwa v120, v117, v239 dst_sel:DWORD dst_unused:UNUSED_PAD src0_sel:WORD_1 src1_sel:DWORD
	v_and_b32_sdwa v121, v116, v239 dst_sel:DWORD dst_unused:UNUSED_PAD src0_sel:WORD_1 src1_sel:DWORD
	v_and_b32_sdwa v106, v105, v239 dst_sel:DWORD dst_unused:UNUSED_PAD src0_sel:WORD_1 src1_sel:DWORD
	v_and_b32_sdwa v107, v104, v239 dst_sel:DWORD dst_unused:UNUSED_PAD src0_sel:WORD_1 src1_sel:DWORD
	v_add3_u32 v142, v138, v140, s10
	v_add3_u32 v129, v129, v130, s10
	v_add3_u32 v128, v128, v131, s10
	v_add3_u32 v117, v117, v120, s10
	v_add3_u32 v116, v116, v121, s10
	v_add3_u32 v105, v105, v106, s10
	v_add3_u32 v104, v104, v107, s10
	s_waitcnt vmcnt(15)
	v_lshlrev_b32_e32 v108, 16, v118
	s_waitcnt vmcnt(14)
	v_lshlrev_b32_e32 v113, 16, v102
	s_waitcnt vmcnt(10)
	v_lshlrev_b32_e32 v118, 16, v78
	v_max_f32_e32 v78, v108, v108
	s_waitcnt vmcnt(9)
	v_lshlrev_b32_e32 v112, 16, v79
	s_waitcnt vmcnt(8)
	v_lshlrev_b32_e32 v79, 16, v82
	v_med3_f32 v78, v78, s9, v244
	v_lshlrev_b32_e32 v82, 16, v103
	v_max_f32_e32 v79, v79, v79
	v_mul_f32_e32 v78, 0xbfb8aa3b, v78
	s_waitcnt vmcnt(5)
	v_lshlrev_b32_e32 v122, 16, v77
	v_lshlrev_b32_e32 v77, 16, v83
	v_lshlrev_b32_e32 v124, 16, v76
	v_max_f32_e32 v76, v82, v82
	s_waitcnt vmcnt(3)
	v_lshlrev_b32_e32 v82, 16, v115
	v_med3_f32 v79, v79, s9, v244
	v_exp_f32_e32 v102, v78
	v_max_f32_e32 v77, v77, v77
	v_max_f32_e32 v82, v82, v82
	v_mul_f32_e32 v79, 0xbfb8aa3b, v79
	v_lshlrev_b32_e32 v83, 16, v114
	v_med3_f32 v76, v76, s9, v244
	v_med3_f32 v77, v77, s9, v244
	v_med3_f32 v82, v82, s9, v244
	v_exp_f32_e32 v103, v79
	v_max_f32_e32 v83, v83, v83
	v_mul_f32_e32 v76, 0xbfb8aa3b, v76
	v_mul_f32_e32 v77, 0xbfb8aa3b, v77
	v_mul_f32_e32 v82, 0xbfb8aa3b, v82
	v_med3_f32 v83, v83, s9, v244
	v_exp_f32_e32 v76, v76
	v_exp_f32_e32 v78, v77
	v_exp_f32_e32 v77, v82
	v_add_f32_e32 v82, 1.0, v102
	v_mul_f32_e32 v79, 0xbfb8aa3b, v83
	v_rcp_f32_e32 v114, v82
	v_exp_f32_e32 v79, v79
	v_add_f32_e32 v83, 1.0, v103
	v_rcp_f32_e32 v115, v83
	v_add_f32_e32 v108, 1.0, v76
	v_add_f32_e32 v83, 1.0, v78
	v_rcp_f32_e32 v82, v108
	v_rcp_f32_e32 v108, v83
	v_fma_f32 v83, v80, v114, v149
	v_add_f32_e32 v109, 1.0, v79
	v_mul_f32_e32 v83, v187, v83
	v_rcp_f32_e32 v109, v109
	v_fma_f32 v125, v80, v115, v149
	v_max_f32_e32 v83, 0xda24260, v83
	v_rcp_f32_e32 v134, v83
	v_mul_f32_e32 v112, v83, v112
	v_mul_f32_e32 v83, v83, v125
	v_fma_f32 v132, v80, v108, v149
	v_bfe_u32 v125, v112, 16, 1
	v_max_f32_e32 v83, 0xda24260, v83
	v_add3_u32 v146, v112, v125, s10
	v_rcp_f32_e32 v135, v83
	v_mul_f32_e32 v112, v83, v122
	v_mul_f32_e32 v83, v83, v132
	v_fma_f32 v133, v80, v109, v149
	v_bfe_u32 v122, v112, 16, 1
	v_max_f32_e32 v83, 0xda24260, v83
	v_add3_u32 v147, v112, v122, s10
	v_rcp_f32_e32 v132, v83
	v_mul_f32_e32 v112, v83, v113
	v_mul_f32_e32 v83, v83, v133
	v_fma_f32 v145, v80, v82, v149
	v_bfe_u32 v113, v112, 16, 1
	v_max_f32_e32 v83, 0xda24260, v83
	v_add3_u32 v151, v112, v113, s10
	v_rcp_f32_e32 v133, v83
	v_mul_f32_e32 v112, v83, v124
	v_mul_f32_e32 v83, v83, v145
	v_max_f32_e32 v124, 0xda24260, v83
	v_add_f32_e32 v83, 1.0, v77
	v_rcp_f32_e32 v83, v83
	v_bfe_u32 v113, v112, 16, 1
	v_add3_u32 v152, v112, v113, s10
	v_mul_f32_e32 v112, v124, v118
	v_bfe_u32 v113, v112, 16, 1
	v_add3_u32 v153, v112, v113, s10
	v_fma_f32 v112, v80, v83, v149
	v_mul_f32_e32 v113, v124, v112
	v_lshlrev_b32_e32 v112, 16, v123
	v_max_f32_e32 v112, v112, v112
	v_med3_f32 v112, v112, s9, v244
	v_mul_f32_e32 v112, 0xbfb8aa3b, v112
	v_exp_f32_e32 v112, v112
	v_max_f32_e32 v113, 0xda24260, v113
	s_waitcnt vmcnt(1)
	v_lshlrev_b32_e32 v88, 16, v88
	s_waitcnt vmcnt(0)
	v_lshlrev_b32_e32 v95, 16, v95
	v_add_f32_e32 v118, 1.0, v112
	v_rcp_f32_e32 v118, v118
	v_mul_f32_e32 v88, v113, v88
	v_max_f32_e32 v95, v95, v95
	v_rcp_f32_e32 v122, v124
	v_bfe_u32 v124, v88, 16, 1
	v_med3_f32 v95, v95, s9, v244
	v_add3_u32 v88, v88, v124, s10
	v_fma_f32 v124, v80, v118, v149
	v_mul_f32_e32 v95, 0xbfb8aa3b, v95
	v_rcp_f32_e32 v123, v113
	v_mul_f32_e32 v124, v113, v124
	v_exp_f32_e32 v113, v95
	v_lshlrev_b32_e32 v125, 16, v119
	v_max_f32_e32 v95, 0xda24260, v124
	v_mul_f32_e32 v125, v95, v125
	v_add_f32_e32 v119, 1.0, v113
	v_rcp_f32_e32 v119, v119
	v_bfe_u32 v145, v125, 16, 1
	v_add3_u32 v154, v125, v145, s10
	v_rcp_f32_e32 v124, v95
	v_fma_f32 v125, v80, v119, v149
	v_mul_f32_e32 v95, v95, v125
	v_max_f32_e32 v95, 0xda24260, v95
	v_lshlrev_b32_e32 v144, 16, v144
	v_mul_f32_e32 v144, v95, v144
	v_bfe_u32 v145, v144, 16, 1
	v_add3_u32 v155, v144, v145, s10
	v_and_b32_e32 v145, 0xffff0000, v67
	v_and_b32_sdwa v67, v139, v239 dst_sel:DWORD dst_unused:UNUSED_PAD src0_sel:WORD_1 src1_sel:DWORD
	v_rcp_f32_e32 v125, v95
	v_and_b32_e32 v144, 0xffff0000, v150
	v_add3_u32 v67, v139, v67, s10
	ds_write_b16_d16_hi v17, v142 offset:6624
	ds_write_b16_d16_hi v17, v67 offset:6768
	ds_write_b16_d16_hi v17, v128 offset:6336
	ds_write_b16_d16_hi v17, v129 offset:6480
	v_and_b32_e32 v129, 0xffff0000, v129
	v_and_b32_e32 v128, 0xffff0000, v128
	ds_write_b16_d16_hi v17, v116 offset:6048
	ds_write_b16_d16_hi v17, v117 offset:6192
	v_and_b32_e32 v117, 0xffff0000, v117
	v_and_b32_e32 v116, 0xffff0000, v116
	ds_write_b16_d16_hi v17, v104 offset:5760
	ds_write_b16_d16_hi v17, v105 offset:5904
	v_and_b32_e32 v105, 0xffff0000, v105
	v_and_b32_e32 v104, 0xffff0000, v104
	global_load_ushort v106, v[20:21], off offset:3072
	s_nop 0
	global_load_ushort v68, v[68:69], off offset:3072
	s_nop 0
	global_load_ushort v69, v[22:23], off offset:1024
	global_load_ushort v139, v[24:25], off offset:1024
	global_load_ushort v131, v[24:25], off offset:2048
	s_nop 0
	global_load_ushort v22, v[22:23], off
	s_nop 0
	global_load_ushort v20, v[20:21], off offset:2048
	s_nop 0
	global_load_ushort v21, v[72:73], off offset:3584
	s_mov_b32 s4, 0xb21e000
	v_add_co_u32_e32 v18, vcc, s4, v18
	s_waitcnt vmcnt(6)
	v_lshlrev_b32_e32 v68, 16, v68
	v_addc_co_u32_e32 v19, vcc, 0, v19, vcc
	global_load_ushort v23, v[18:19], off
	s_nop 0
	global_load_ushort v18, v[18:19], off offset:3584
	s_nop 0
	global_load_ushort v19, v[72:73], off offset:2560
	global_load_ushort v24, v[70:71], off offset:512
	global_load_ushort v25, v[64:65], off offset:1536
	s_nop 0
	global_load_ushort v70, v[62:63], off offset:1536
	ds_write_b16_d16_hi v17, v146 offset:2304
	ds_write_b16_d16_hi v17, v147 offset:2448
	ds_write_b16_d16_hi v17, v151 offset:2592
	ds_write_b16_d16_hi v17, v152 offset:2736
	ds_write_b16_d16_hi v17, v153 offset:2880
	ds_write_b16_d16_hi v17, v88 offset:3024
	ds_write_b16_d16_hi v17, v154 offset:3168
	ds_write_b16_d16_hi v17, v155 offset:3312
	global_load_ushort v64, v[64:65], off offset:512
	s_nop 0
	global_load_ushort v62, v[62:63], off offset:2560
	v_lshlrev_b32_e32 v63, 16, v106
	s_waitcnt vmcnt(9)
	v_lshlrev_b32_e32 v65, 16, v20
	s_waitcnt vmcnt(8)
	v_lshlrev_b32_e32 v20, 16, v21
	v_lshlrev_b32_e32 v21, 16, v69
	v_lshlrev_b32_e32 v69, 16, v22
	v_max_f32_e32 v22, v63, v63
	v_med3_f32 v22, v22, s9, v244
	v_max_f32_e32 v20, v20, v20
	v_mul_f32_e32 v22, 0xbfb8aa3b, v22
	v_med3_f32 v20, v20, s9, v244
	v_mul_f32_e32 v20, 0xbfb8aa3b, v20
	s_waitcnt vmcnt(6)
	v_lshlrev_b32_e32 v71, 16, v18
	s_waitcnt vmcnt(5)
	v_lshlrev_b32_e32 v63, 16, v19
	v_lshlrev_b32_e32 v19, 16, v23
	s_waitcnt vmcnt(4)
	v_lshlrev_b32_e32 v23, 16, v24
	v_exp_f32_e32 v24, v22
	v_max_f32_e32 v18, v21, v21
	s_waitcnt vmcnt(3)
	v_lshlrev_b32_e32 v21, 16, v25
	v_max_f32_e32 v19, v19, v19
	v_max_f32_e32 v23, v23, v23
	v_max_f32_e32 v21, v21, v21
	v_med3_f32 v19, v19, s9, v244
	v_med3_f32 v23, v23, s9, v244
	v_exp_f32_e32 v25, v20
	v_med3_f32 v21, v21, s9, v244
	v_mul_f32_e32 v19, 0xbfb8aa3b, v19
	v_mul_f32_e32 v22, 0xbfb8aa3b, v23
	v_med3_f32 v18, v18, s9, v244
	v_mul_f32_e32 v23, 0xbfb8aa3b, v21
	v_exp_f32_e32 v20, v19
	v_exp_f32_e32 v21, v22
	v_add_f32_e32 v22, 1.0, v24
	v_mul_f32_e32 v18, 0xbfb8aa3b, v18
	v_rcp_f32_e32 v106, v22
	v_exp_f32_e32 v18, v18
	v_exp_f32_e32 v19, v23
	v_add_f32_e32 v23, 1.0, v25
	v_rcp_f32_e32 v107, v23
	v_add_f32_e32 v23, 1.0, v20
	v_rcp_f32_e32 v110, v23
	v_fma_f32 v23, v80, v106, v149
	v_add_f32_e32 v72, 1.0, v18
	v_add_f32_e32 v73, 1.0, v21
	v_mul_f32_e32 v23, v95, v23
	v_rcp_f32_e32 v22, v72
	v_rcp_f32_e32 v111, v73
	v_fma_f32 v72, v80, v107, v149
	v_max_f32_e32 v23, 0xda24260, v23
	v_rcp_f32_e32 v120, v23
	v_mul_f32_e32 v65, v23, v65
	v_mul_f32_e32 v23, v23, v72
	v_fma_f32 v88, v80, v110, v149
	v_max_f32_e32 v23, 0xda24260, v23
	v_bfe_u32 v72, v65, 16, 1
	v_rcp_f32_e32 v121, v23
	v_mul_f32_e32 v63, v23, v63
	v_mul_f32_e32 v23, v23, v88
	v_fma_f32 v95, v80, v111, v149
	v_add3_u32 v143, v65, v72, s10
	v_bfe_u32 v65, v63, 16, 1
	v_max_f32_e32 v23, 0xda24260, v23
	v_add3_u32 v146, v63, v65, s10
	v_rcp_f32_e32 v126, v23
	v_mul_f32_e32 v63, v23, v68
	v_mul_f32_e32 v23, v23, v95
	v_fma_f32 v73, v80, v22, v149
	v_bfe_u32 v65, v63, 16, 1
	v_max_f32_e32 v23, 0xda24260, v23
	v_add3_u32 v95, v63, v65, s10
	v_rcp_f32_e32 v127, v23
	v_mul_f32_e32 v63, v23, v71
	v_mul_f32_e32 v23, v23, v73
	v_bfe_u32 v65, v63, 16, 1
	v_max_f32_e32 v68, 0xda24260, v23
	v_add3_u32 v147, v63, v65, s10
	v_mul_f32_e32 v63, v68, v69
	v_bfe_u32 v65, v63, 16, 1
	v_add3_u32 v150, v63, v65, s10
	v_lshlrev_b32_e32 v65, 16, v131
	v_max_f32_e32 v65, v65, v65
	v_med3_f32 v65, v65, s9, v244
	v_add_f32_e32 v23, 1.0, v19
	v_mul_f32_e32 v65, 0xbfb8aa3b, v65
	v_rcp_f32_e32 v23, v23
	v_exp_f32_e32 v136, v65
	s_waitcnt vmcnt(0)
	v_lshlrev_b32_e32 v62, 16, v62
	v_max_f32_e32 v62, v62, v62
	v_fma_f32 v63, v80, v23, v149
	v_add_f32_e32 v65, 1.0, v136
	v_med3_f32 v62, v62, s9, v244
	v_mul_f32_e32 v63, v68, v63
	v_rcp_f32_e32 v138, v65
	v_mul_f32_e32 v62, 0xbfb8aa3b, v62
	v_max_f32_e32 v63, 0xda24260, v63
	v_lshlrev_b32_e32 v64, 16, v64
	v_exp_f32_e32 v137, v62
	v_mul_f32_e32 v64, v63, v64
	v_bfe_u32 v65, v64, 16, 1
	v_add3_u32 v151, v64, v65, s10
	v_fma_f32 v64, v80, v138, v149
	v_rcp_f32_e32 v131, v63
	v_mul_f32_e32 v63, v63, v64
	v_add_f32_e32 v64, 1.0, v137
	v_max_f32_e32 v62, 0xda24260, v63
	v_lshlrev_b32_e32 v63, 16, v139
	v_rcp_f32_e32 v139, v64
	v_mul_f32_e32 v63, v62, v63
	v_bfe_u32 v64, v63, 16, 1
	v_add3_u32 v152, v63, v64, s10
	v_fma_f32 v63, v80, v139, v149
	v_rcp_f32_e32 v140, v62
	v_mul_f32_e32 v62, v62, v63
	v_max_f32_e32 v88, 0xda24260, v62
	v_lshlrev_b32_e32 v62, 16, v70
	v_mul_f32_e32 v62, v88, v62
	v_bfe_u32 v63, v62, 16, 1
	v_add3_u32 v153, v62, v63, s10
	v_pk_mul_f32 v[62:63], v[88:89], v[86:87] op_sel_hi:[0,1]
	v_pk_mul_f32 v[64:65], v[88:89], v[84:85] op_sel_hi:[0,1]
	v_rcp_f32_e32 v130, v68
	v_cvt_pk_bf16_f32 v62, v62, v63
	v_cvt_pk_bf16_f32 v63, v64, v65
	v_pk_mul_f32 v[64:65], v[88:89], v[74:75] op_sel_hi:[0,1]
	v_pk_mul_f32 v[68:69], v[88:89], v[144:145] op_sel_hi:[0,1]
	v_cvt_pk_bf16_f32 v64, v64, v65
	v_cvt_pk_bf16_f32 v65, v68, v69
	v_pk_mul_f32 v[68:69], v[88:89], v[104:105] op_sel_hi:[0,1]
	v_pk_mul_f32 v[70:71], v[88:89], v[116:117] op_sel_hi:[0,1]
	v_and_b32_e32 v73, 0xffff0000, v67
	v_and_b32_e32 v72, 0xffff0000, v142
	v_cvt_pk_bf16_f32 v68, v68, v69
	v_cvt_pk_bf16_f32 v69, v70, v71
	v_pk_mul_f32 v[70:71], v[88:89], v[128:129] op_sel_hi:[0,1]
	v_pk_mul_f32 v[72:73], v[88:89], v[72:73] op_sel_hi:[0,1]
	v_cvt_pk_bf16_f32 v70, v70, v71
	v_cvt_pk_bf16_f32 v71, v72, v73
	v_pk_mul_f32 v[72:73], v[102:103], v[114:115]
	v_rcp_f32_e32 v141, v88
	v_pk_mul_f32 v[72:73], v[80:81], v[72:73] op_sel_hi:[0,1]
	v_pk_mul_f32 v[72:73], v[72:73], v[134:135]
	s_nop 0
	v_and_b32_sdwa v67, v73, v239 dst_sel:DWORD dst_unused:UNUSED_PAD src0_sel:WORD_1 src1_sel:DWORD
	v_and_b32_sdwa v74, v72, v239 dst_sel:DWORD dst_unused:UNUSED_PAD src0_sel:WORD_1 src1_sel:DWORD
	v_add3_u32 v67, v73, v67, s10
	v_add3_u32 v72, v72, v74, s10
	v_pk_mul_f32 v[74:75], v[78:79], v[108:109]
	ds_write_b16_d16_hi v17, v72 offset:6912
	ds_write_b16_d16_hi v17, v67 offset:7056
	v_and_b32_e32 v73, 0xffff0000, v67
	v_and_b32_e32 v72, 0xffff0000, v72
	v_pk_mul_f32 v[74:75], v[80:81], v[74:75] op_sel_hi:[0,1]
	v_pk_mul_f32 v[72:73], v[88:89], v[72:73] op_sel_hi:[0,1]
	v_pk_mul_f32 v[74:75], v[74:75], v[132:133]
	v_cvt_pk_bf16_f32 v72, v72, v73
	v_and_b32_sdwa v67, v75, v239 dst_sel:DWORD dst_unused:UNUSED_PAD src0_sel:WORD_1 src1_sel:DWORD
	v_and_b32_sdwa v73, v74, v239 dst_sel:DWORD dst_unused:UNUSED_PAD src0_sel:WORD_1 src1_sel:DWORD
	v_add3_u32 v67, v75, v67, s10
	v_add3_u32 v73, v74, v73, s10
	v_and_b32_e32 v75, 0xffff0000, v67
	v_and_b32_e32 v74, 0xffff0000, v73
	v_pk_mul_f32 v[74:75], v[88:89], v[74:75] op_sel_hi:[0,1]
	ds_write_b16_d16_hi v17, v73 offset:7200
	ds_write_b16_d16_hi v17, v67 offset:7344
	v_cvt_pk_bf16_f32 v73, v74, v75
	v_pk_mul_f32 v[74:75], v[76:77], v[82:83]
	s_nop 0
	v_pk_mul_f32 v[74:75], v[80:81], v[74:75] op_sel_hi:[0,1]
	v_pk_mul_f32 v[74:75], v[74:75], v[122:123]
	s_nop 0
	v_and_b32_sdwa v67, v75, v239 dst_sel:DWORD dst_unused:UNUSED_PAD src0_sel:WORD_1 src1_sel:DWORD
	v_and_b32_sdwa v76, v74, v239 dst_sel:DWORD dst_unused:UNUSED_PAD src0_sel:WORD_1 src1_sel:DWORD
	v_add3_u32 v67, v75, v67, s10
	v_add3_u32 v74, v74, v76, s10
	v_pk_mul_f32 v[76:77], v[112:113], v[118:119]
	ds_write_b16_d16_hi v17, v74 offset:7488
	ds_write_b16_d16_hi v17, v67 offset:7632
	v_and_b32_e32 v75, 0xffff0000, v67
	v_and_b32_e32 v74, 0xffff0000, v74
	v_pk_mul_f32 v[76:77], v[80:81], v[76:77] op_sel_hi:[0,1]
	v_pk_mul_f32 v[74:75], v[88:89], v[74:75] op_sel_hi:[0,1]
	v_pk_mul_f32 v[76:77], v[76:77], v[124:125]
	v_cvt_pk_bf16_f32 v74, v74, v75
	v_and_b32_sdwa v75, v76, v239 dst_sel:DWORD dst_unused:UNUSED_PAD src0_sel:WORD_1 src1_sel:DWORD
	v_and_b32_sdwa v67, v77, v239 dst_sel:DWORD dst_unused:UNUSED_PAD src0_sel:WORD_1 src1_sel:DWORD
	v_add3_u32 v75, v76, v75, s10
	v_add3_u32 v67, v77, v67, s10
	ds_write_b16_d16_hi v17, v75 offset:7776
	ds_write_b16_d16_hi v17, v67 offset:7920
	v_pk_mul_f32 v[24:25], v[24:25], v[106:107]
	v_and_b32_e32 v77, 0xffff0000, v67
	v_and_b32_e32 v76, 0xffff0000, v75
	v_pk_mul_f32 v[24:25], v[80:81], v[24:25] op_sel_hi:[0,1]
	v_pk_mul_f32 v[76:77], v[88:89], v[76:77] op_sel_hi:[0,1]
	v_pk_mul_f32 v[24:25], v[24:25], v[120:121]
	v_cvt_pk_bf16_f32 v75, v76, v77
	v_and_b32_sdwa v67, v25, v239 dst_sel:DWORD dst_unused:UNUSED_PAD src0_sel:WORD_1 src1_sel:DWORD
	v_and_b32_sdwa v76, v24, v239 dst_sel:DWORD dst_unused:UNUSED_PAD src0_sel:WORD_1 src1_sel:DWORD
	v_add3_u32 v25, v25, v67, s10
	v_add3_u32 v24, v24, v76, s10
	v_pk_mul_f32 v[20:21], v[20:21], v[110:111]
	ds_write_b16_d16_hi v17, v143 offset:3456
	ds_write_b16_d16_hi v17, v146 offset:3600
	ds_write_b16_d16_hi v17, v95 offset:3744
	ds_write_b16_d16_hi v17, v147 offset:3888
	ds_write_b16_d16_hi v17, v150 offset:4032
	ds_write_b16_d16_hi v17, v151 offset:4176
	ds_write_b16_d16_hi v17, v152 offset:4320
	ds_write_b16_d16_hi v17, v153 offset:4464
	ds_write_b16_d16_hi v17, v24 offset:8064
	ds_write_b16_d16_hi v17, v25 offset:8208
	v_and_b32_e32 v25, 0xffff0000, v25
	v_and_b32_e32 v24, 0xffff0000, v24
	v_pk_mul_f32 v[20:21], v[80:81], v[20:21] op_sel_hi:[0,1]
	v_pk_mul_f32 v[24:25], v[88:89], v[24:25] op_sel_hi:[0,1]
	v_pk_mul_f32 v[20:21], v[20:21], v[126:127]
	v_cvt_pk_bf16_f32 v76, v24, v25
	v_and_b32_sdwa v24, v21, v239 dst_sel:DWORD dst_unused:UNUSED_PAD src0_sel:WORD_1 src1_sel:DWORD
	v_and_b32_sdwa v25, v20, v239 dst_sel:DWORD dst_unused:UNUSED_PAD src0_sel:WORD_1 src1_sel:DWORD
	v_add3_u32 v21, v21, v24, s10
	v_add3_u32 v20, v20, v25, s10
	v_pk_mul_f32 v[18:19], v[18:19], v[22:23]
	ds_write_b16_d16_hi v17, v20 offset:8352
	ds_write_b16_d16_hi v17, v21 offset:8496
	v_and_b32_e32 v21, 0xffff0000, v21
	v_and_b32_e32 v20, 0xffff0000, v20
	v_pk_mul_f32 v[18:19], v[80:81], v[18:19] op_sel_hi:[0,1]
	v_pk_mul_f32 v[20:21], v[88:89], v[20:21] op_sel_hi:[0,1]
	v_pk_mul_f32 v[18:19], v[18:19], v[130:131]
	v_cvt_pk_bf16_f32 v77, v20, v21
	v_and_b32_sdwa v20, v19, v239 dst_sel:DWORD dst_unused:UNUSED_PAD src0_sel:WORD_1 src1_sel:DWORD
	v_and_b32_sdwa v21, v18, v239 dst_sel:DWORD dst_unused:UNUSED_PAD src0_sel:WORD_1 src1_sel:DWORD
	v_add3_u32 v19, v19, v20, s10
	v_add3_u32 v18, v18, v21, s10
	ds_write_b16_d16_hi v17, v18 offset:8640
	ds_write_b16_d16_hi v17, v19 offset:8784
	v_and_b32_e32 v19, 0xffff0000, v19
	v_and_b32_e32 v18, 0xffff0000, v18
	v_pk_mul_f32 v[18:19], v[88:89], v[18:19] op_sel_hi:[0,1]
	v_cvt_pk_bf16_f32 v78, v18, v19
	v_pk_mul_f32 v[18:19], v[136:137], v[138:139]
	s_nop 0
	v_pk_mul_f32 v[18:19], v[80:81], v[18:19] op_sel_hi:[0,1]
	v_pk_mul_f32 v[18:19], v[18:19], v[140:141]
	s_nop 0
	v_and_b32_sdwa v21, v18, v239 dst_sel:DWORD dst_unused:UNUSED_PAD src0_sel:WORD_1 src1_sel:DWORD
	v_and_b32_sdwa v20, v19, v239 dst_sel:DWORD dst_unused:UNUSED_PAD src0_sel:WORD_1 src1_sel:DWORD
	v_add3_u32 v18, v18, v21, s10
	v_add3_u32 v19, v19, v20, s10
	ds_write_b16_d16_hi v17, v18 offset:8928
	ds_write_b16_d16_hi v17, v19 offset:9072
	v_and_b32_e32 v19, 0xffff0000, v19
	v_and_b32_e32 v18, 0xffff0000, v18
	v_pk_mul_f32 v[18:19], v[88:89], v[18:19] op_sel_hi:[0,1]
	v_cvt_pk_bf16_f32 v79, v18, v19
	v_lshl_add_u32 v16, v16, 2, v92
	ds_write_b128 v66, v[62:65] offset:9216
	ds_write_b128 v66, v[68:71] offset:9232
	ds_write_b128 v66, v[72:75] offset:9248
	ds_write_b128 v66, v[76:79] offset:9264
	ds_write_b32 v16, v88 offset:19456
	ds_write_b128 v66, v[12:15] offset:14336
	ds_write_b128 v66, v[8:11] offset:14352
	ds_write_b128 v66, v[4:7] offset:14368
	ds_write_b128 v66, v[0:3] offset:14384
	s_waitcnt lgkmcnt(0)
	s_movk_i32 s17, 0x90
	v_mad_u32_u24 v72, v35, s17, v92
	v_lshlrev_b32_e32 v73, 4, v81
	v_add_u32_e32 v66, v72, v73
	ds_read_b128 v[0:3], v66 offset:4608
	ds_read_b128 v[4:7], v66
	ds_read_b128 v[18:21], v66 offset:32
	ds_read_b128 v[22:25], v66 offset:4640
	ds_read_b128 v[62:65], v66 offset:4672
	s_waitcnt lgkmcnt(3)
	v_mfma_f32_32x32x16_bf16 v[2:17], v[0:3], v[4:7], 0
	v_lshlrev_b32_e32 v70, 2, v81
	v_cmp_le_i32_e32 vcc, v70, v35
	v_or_b32_e32 v74, 2, v70
	v_or_b32_e32 v75, 3, v70
	v_or_b32_e32 v88, v93, v35
	v_add_u32_e32 v76, 8, v70
	v_lshlrev_b64 v[0:1], 11, v[88:89]
	s_waitcnt lgkmcnt(1)
	v_mfma_f32_32x32x16_bf16 v[2:17], v[22:25], v[18:21], v[2:17]
	ds_read_b128 v[18:21], v66 offset:64
	ds_read_b128 v[22:25], v66 offset:4704
	ds_read_b128 v[66:69], v66 offset:96
	v_lshl_add_u64 v[0:1], s[2:3], 0, v[0:1]
	v_ashrrev_i32_e32 v71, 31, v70
	v_lshl_add_u64 v[0:1], v[0:1], 0, v[90:91]
	v_lshl_add_u64 v[84:85], v[70:71], 1, v[0:1]
	v_add_u32_e32 v0, 16, v70
	s_waitcnt lgkmcnt(2)
	v_mfma_f32_32x32x16_bf16 v[2:17], v[62:65], v[18:21], v[2:17]
	v_add_u32_e32 v18, 9, v70
	v_add_u32_e32 v19, 10, v70
	v_add_u32_e32 v20, 11, v70
	v_lshlrev_b32_e32 v138, 16, v42
	v_and_b32_e32 v139, 0xffff0000, v42
	v_lshlrev_b32_e32 v42, 16, v43
	v_and_b32_e32 v43, 0xffff0000, v43
	s_waitcnt lgkmcnt(0)
	v_mfma_f32_32x32x16_bf16 v[2:17], v[22:25], v[66:69], v[2:17]
	v_lshlrev_b32_e32 v140, 16, v36
	v_and_b32_e32 v141, 0xffff0000, v36
	v_lshlrev_b32_e32 v142, 16, v37
	v_and_b32_e32 v143, 0xffff0000, v37
	v_cvt_pk_bf16_f32 v130, v138, v139
	v_cvt_pk_bf16_f32 v131, v42, v43
	v_cvt_pk_bf16_f32 v132, v140, v141
	s_nop 4
	v_cndmask_b32_e32 v21, 0, v2, vcc
	v_cmp_lt_i32_e32 vcc, v70, v35
	v_cvt_pk_bf16_f32 v133, v142, v143
	v_add_u32_e32 v95, v92, v73
	v_cndmask_b32_e32 v22, 0, v3, vcc
	v_cmp_le_i32_e32 vcc, v74, v35
	v_lshlrev_b32_e32 v74, 3, v81
	v_add_u32_e32 v88, v72, v74
	v_cndmask_b32_e32 v4, 0, v4, vcc
	v_cmp_le_i32_e32 vcc, v75, v35
	v_mad_u32_u24 v144, v35, s16, v95
	v_cvt_pk_bf16_f32 v36, v44, v45
	v_cndmask_b32_e32 v5, 0, v5, vcc
	v_cmp_le_i32_e32 vcc, v76, v35
	v_cvt_pk_bf16_f32 v37, v46, v47
	v_lshlrev_b32_e32 v78, 16, v60
	v_cndmask_b32_e32 v6, 0, v6, vcc
	v_cmp_le_i32_e32 vcc, v18, v35
	v_cvt_pk_bf16_f32 v18, v21, v22
	v_and_b32_e32 v79, 0xffff0000, v60
	v_cndmask_b32_e32 v7, 0, v7, vcc
	v_cmp_le_i32_e32 vcc, v19, v35
	v_cvt_pk_bf16_f32 v19, v4, v5
	v_lshlrev_b32_e32 v82, 16, v61
	v_cndmask_b32_e32 v8, 0, v8, vcc
	v_cmp_le_i32_e32 vcc, v20, v35
	v_cvt_pk_bf16_f32 v20, v6, v7
	v_and_b32_e32 v83, 0xffff0000, v61
	v_cndmask_b32_e32 v9, 0, v9, vcc
	v_cmp_le_i32_e32 vcc, v0, v35
	v_add_u32_e32 v0, 17, v70
	v_cvt_pk_bf16_f32 v21, v8, v9
	v_cndmask_b32_e32 v23, 0, v10, vcc
	v_cmp_le_i32_e32 vcc, v0, v35
	v_add_u32_e32 v0, 18, v70
	v_add_u32_e32 v10, 26, v70
	v_cndmask_b32_e32 v24, 0, v11, vcc
	v_cmp_le_i32_e32 vcc, v0, v35
	v_add_u32_e32 v0, 19, v70
	v_cvt_pk_bf16_f32 v22, v23, v24
	v_cndmask_b32_e32 v25, 0, v12, vcc
	v_cmp_le_i32_e32 vcc, v0, v35
	v_add_u32_e32 v0, 24, v70
	v_lshlrev_b32_e32 v60, 16, v58
	v_cndmask_b32_e32 v68, 0, v13, vcc
	v_cmp_le_i32_e32 vcc, v0, v35
	v_add_u32_e32 v0, 25, v70
	v_add_u32_e32 v70, 27, v70
	v_cndmask_b32_e32 v69, 0, v14, vcc
	v_cmp_le_i32_e32 vcc, v0, v35
	v_mul_u32_u24_e32 v0, 0x50, v35
	v_add3_u32 v81, v92, v74, v0
	v_add_u32_e32 v11, 0x3800, v81
	ds_read2_b64 v[0:3], v11 offset1:2
	ds_read2_b64 v[64:67], v11 offset0:4 offset1:6
	v_cndmask_b32_e32 v71, 0, v15, vcc
	v_cmp_le_i32_e32 vcc, v10, v35
	s_waitcnt lgkmcnt(1)
	v_mfma_f32_32x32x16_bf16 v[0:15], v[0:3], v[18:21], 0
	v_cndmask_b32_e32 v16, 0, v16, vcc
	v_cmp_le_i32_e32 vcc, v70, v35
	v_cvt_pk_bf16_f32 v23, v25, v68
	v_cvt_pk_bf16_f32 v24, v69, v71
	v_cndmask_b32_e32 v17, 0, v17, vcc
	v_cvt_pk_bf16_f32 v25, v16, v17
	ds_read2_b64 v[106:109], v88 offset1:2
	ds_read2_b64 v[110:113], v88 offset0:4 offset1:6
	ds_read2_b64 v[114:117], v88 offset0:8 offset1:10
	ds_read2_b64 v[118:121], v88 offset0:12 offset1:14
	s_waitcnt lgkmcnt(4)
	v_mfma_f32_32x32x16_bf16 v[0:15], v[64:67], v[22:25], v[0:15]
	v_cvt_pk_bf16_f32 v35, v40, v41
	v_and_b32_e32 v61, 0xffff0000, v58
	v_lshlrev_b32_e32 v58, 16, v59
	v_and_b32_e32 v59, 0xffff0000, v59
	v_cvt_pk_bf16_f32 v122, v78, v79
	v_cvt_pk_bf16_f32 v123, v82, v83
	v_cvt_pk_bf16_f32 v124, v60, v61
	s_waitcnt lgkmcnt(3)
	v_mfma_f32_32x32x16_bf16 v[0:15], v[130:133], v[106:109], v[0:15]
	v_lshlrev_b32_e32 v106, 16, v34
	v_and_b32_e32 v107, 0xffff0000, v34
	v_cvt_pk_bf16_f32 v34, v106, v107
	v_cvt_pk_bf16_f32 v125, v58, v59
	v_lshlrev_b32_e32 v86, 16, v56
	v_and_b32_e32 v87, 0xffff0000, v56
	v_lshlrev_b32_e32 v56, 16, v57
	s_waitcnt lgkmcnt(2)
	v_mfma_f32_32x32x16_bf16 v[0:15], v[34:37], v[110:113], v[0:15]
	v_and_b32_e32 v57, 0xffff0000, v57
	v_lshlrev_b32_e32 v102, 16, v54
	v_and_b32_e32 v103, 0xffff0000, v54
	v_lshlrev_b32_e32 v104, 16, v55
	v_and_b32_e32 v105, 0xffff0000, v55
	v_cvt_pk_bf16_f32 v126, v86, v87
	v_cvt_pk_bf16_f32 v127, v56, v57
	s_waitcnt lgkmcnt(1)
	v_mfma_f32_32x32x16_bf16 v[0:15], v[122:125], v[114:117], v[0:15]
	v_cvt_pk_bf16_f32 v128, v102, v103
	v_cvt_pk_bf16_f32 v129, v104, v105
	s_mov_b64 s[2:3], 0x16f00600
	v_lshl_add_u64 v[62:63], v[84:85], 0, s[2:3]
	s_mov_b32 s2, 0x16f00000
	v_lshlrev_b32_e32 v16, 16, v26
	v_and_b32_e32 v17, 0xffff0000, v26
	s_waitcnt lgkmcnt(0)
	v_mfma_f32_32x32x16_bf16 v[0:15], v[126:129], v[118:121], v[0:15]
	v_lshlrev_b32_e32 v64, 16, v27
	v_and_b32_e32 v65, 0xffff0000, v27
	v_lshlrev_b32_e32 v66, 16, v28
	v_and_b32_e32 v67, 0xffff0000, v28
	v_lshlrev_b32_e32 v68, 16, v29
	v_and_b32_e32 v69, 0xffff0000, v29
	v_lshlrev_b32_e32 v70, 16, v30
	s_nop 4
	v_cvt_pk_bf16_f32 v0, v0, v1
	v_cvt_pk_bf16_f32 v1, v2, v3
	v_add_co_u32_e32 v2, vcc, s2, v84
	v_and_b32_e32 v71, 0xffff0000, v30
	s_nop 0
	v_addc_co_u32_e32 v3, vcc, 0, v85, vcc
	global_store_dwordx2 v[2:3], v[0:1], off offset:1536
	v_cvt_pk_bf16_f32 v0, v4, v5
	v_cvt_pk_bf16_f32 v1, v6, v7
	global_store_dwordx2 v[62:63], v[0:1], off offset:16
	v_cvt_pk_bf16_f32 v0, v8, v9
	v_cvt_pk_bf16_f32 v1, v10, v11
	v_lshlrev_b32_e32 v72, 16, v31
	v_and_b32_e32 v73, 0xffff0000, v31
	v_lshlrev_b32_e32 v74, 16, v32
	v_and_b32_e32 v75, 0xffff0000, v32
	v_lshlrev_b32_e32 v76, 16, v33
	v_and_b32_e32 v77, 0xffff0000, v33
	v_lshlrev_b32_e32 v54, 16, v52
	v_and_b32_e32 v55, 0xffff0000, v52
	v_lshlrev_b32_e32 v52, 16, v53
	v_and_b32_e32 v53, 0xffff0000, v53
	v_lshlrev_b32_e32 v130, 16, v50
	v_and_b32_e32 v131, 0xffff0000, v50
	v_lshlrev_b32_e32 v50, 16, v51
	v_and_b32_e32 v51, 0xffff0000, v51
	v_lshlrev_b32_e32 v132, 16, v48
	v_and_b32_e32 v133, 0xffff0000, v48
	v_lshlrev_b32_e32 v48, 16, v49
	v_and_b32_e32 v49, 0xffff0000, v49
	v_lshlrev_b32_e32 v114, 16, v38
	v_and_b32_e32 v115, 0xffff0000, v38
	v_lshlrev_b32_e32 v116, 16, v39
	v_and_b32_e32 v117, 0xffff0000, v39
	global_store_dwordx2 v[62:63], v[0:1], off offset:32
	v_cvt_pk_bf16_f32 v0, v12, v13
	v_cvt_pk_bf16_f32 v1, v14, v15
	v_cvt_pk_bf16_f32 v26, v16, v17
	v_cvt_pk_bf16_f32 v27, v64, v65
	v_cvt_pk_bf16_f32 v28, v66, v67
	v_cvt_pk_bf16_f32 v29, v68, v69
	v_cvt_pk_bf16_f32 v30, v70, v71
	v_cvt_pk_bf16_f32 v31, v72, v73
	v_cvt_pk_bf16_f32 v32, v74, v75
	v_cvt_pk_bf16_f32 v33, v76, v77
	v_cvt_pk_bf16_f32 v134, v54, v55
	v_cvt_pk_bf16_f32 v135, v52, v53
	v_cvt_pk_bf16_f32 v136, v130, v131
	v_cvt_pk_bf16_f32 v137, v50, v51
	v_cvt_pk_bf16_f32 v34, v132, v133
	v_cvt_pk_bf16_f32 v35, v48, v49
	v_cvt_pk_bf16_f32 v36, v114, v115
	v_cvt_pk_bf16_f32 v37, v116, v117
	global_store_dwordx2 v[62:63], v[0:1], off offset:48
	v_add_u32_e32 v38, 0x4000, v81
	ds_read2_b64 v[0:3], v38 offset0:64 offset1:66
	s_waitcnt lgkmcnt(0)
	v_mfma_f32_32x32x16_bf16 v[0:15], v[0:3], v[18:21], 0
	ds_read2_b64 v[18:21], v38 offset0:68 offset1:70
	s_waitcnt lgkmcnt(0)
	v_mfma_f32_32x32x16_bf16 v[0:15], v[18:21], v[22:25], v[0:15]
	ds_read2_b64 v[18:21], v88 offset1:2
	s_waitcnt lgkmcnt(0)
	v_mfma_f32_32x32x16_bf16 v[0:15], v[134:137], v[18:21], v[0:15]
	ds_read2_b64 v[18:21], v88 offset0:4 offset1:6
	s_waitcnt lgkmcnt(0)
	v_mfma_f32_32x32x16_bf16 v[0:15], v[34:37], v[18:21], v[0:15]
	ds_read2_b64 v[18:21], v88 offset0:8 offset1:10
	s_waitcnt lgkmcnt(0)
	v_mfma_f32_32x32x16_bf16 v[0:15], v[26:29], v[18:21], v[0:15]
	ds_read2_b64 v[18:21], v88 offset0:12 offset1:14
	s_waitcnt lgkmcnt(0)
	v_mfma_f32_32x32x16_bf16 v[0:15], v[30:33], v[18:21], v[0:15]
	s_nop 11
	v_cvt_pk_bf16_f32 v0, v0, v1
	v_cvt_pk_bf16_f32 v1, v2, v3
	v_cvt_pk_bf16_f32 v2, v4, v5
	v_cvt_pk_bf16_f32 v3, v6, v7
	v_cvt_pk_bf16_f32 v4, v8, v9
	v_cvt_pk_bf16_f32 v5, v10, v11
	v_cvt_pk_bf16_f32 v6, v12, v13
	v_cvt_pk_bf16_f32 v7, v14, v15
	global_store_dwordx2 v[62:63], v[0:1], off offset:64
	global_store_dwordx2 v[62:63], v[2:3], off offset:80
	global_store_dwordx2 v[62:63], v[4:5], off offset:96
	global_store_dwordx2 v[62:63], v[6:7], off offset:112
	ds_read_b128 v[0:3], v95 offset:19456
	ds_read_b128 v[4:7], v95 offset:19488
	ds_read_b128 v[8:11], v95 offset:19520
	ds_read_b128 v[12:15], v95 offset:19552
	ds_read_b128 v[18:21], v144 offset:9216
	s_waitcnt lgkmcnt(4)
	v_pk_mul_f32 v[34:35], v[2:3], v[42:43]
	ds_read_b128 v[22:25], v144 offset:14336
	s_waitcnt lgkmcnt(3)
	v_pk_mul_f32 v[42:43], v[10:11], v[40:41]
	v_pk_mul_f32 v[40:41], v[8:9], v[106:107]
	ds_read_b128 v[26:29], v144 offset:9248
	ds_read_b128 v[106:109], v144 offset:14368
	ds_read_b128 v[110:113], v144 offset:16896
	v_pk_mul_f32 v[32:33], v[0:1], v[138:139]
	v_pk_mul_f32 v[38:39], v[6:7], v[142:143]
	v_pk_mul_f32 v[36:37], v[4:5], v[140:141]
	s_waitcnt lgkmcnt(5)
	v_pk_mul_f32 v[46:47], v[14:15], v[46:47]
	v_pk_mul_f32 v[44:45], v[12:13], v[44:45]
	v_pk_mul_f32 v[0:1], v[0:1], v[54:55]
	v_pk_mul_f32 v[2:3], v[2:3], v[52:53]
	v_pk_mul_f32 v[4:5], v[4:5], v[130:131]
	v_pk_mul_f32 v[6:7], v[6:7], v[50:51]
	v_pk_mul_f32 v[8:9], v[8:9], v[132:133]
	v_pk_mul_f32 v[10:11], v[10:11], v[48:49]
	v_pk_mul_f32 v[12:13], v[12:13], v[114:115]
	v_pk_mul_f32 v[14:15], v[14:15], v[116:117]
	s_waitcnt lgkmcnt(3)
	v_mfma_f32_32x32x16_bf16 v[32:47], v[18:21], v[22:25], v[32:47]
	ds_read_b128 v[114:117], v144 offset:16928
	s_waitcnt lgkmcnt(1)
	v_mfma_f32_32x32x16_bf16 v[0:15], v[18:21], v[110:113], v[0:15]
	v_mfma_f32_32x32x16_bf16 v[32:47], v[26:29], v[106:109], v[32:47]
	s_waitcnt lgkmcnt(0)
	v_mfma_f32_32x32x16_bf16 v[0:15], v[26:29], v[114:117], v[0:15]
	ds_read_b128 v[18:21], v95 offset:19584
	ds_read_b128 v[26:29], v95 offset:19616
	ds_read_b128 v[118:121], v95 offset:19648
	ds_read_b128 v[122:125], v95 offset:19680
	ds_read_b128 v[126:129], v144 offset:11776
	s_waitcnt lgkmcnt(4)
	v_pk_mul_f32 v[50:51], v[20:21], v[82:83]
	v_pk_mul_f32 v[48:49], v[18:19], v[78:79]
	s_waitcnt lgkmcnt(3)
	v_pk_mul_f32 v[54:55], v[28:29], v[58:59]
	v_pk_mul_f32 v[52:53], v[26:27], v[60:61]
	s_waitcnt lgkmcnt(2)
	v_pk_mul_f32 v[58:59], v[120:121], v[56:57]
	v_pk_mul_f32 v[56:57], v[118:119], v[86:87]
	s_waitcnt lgkmcnt(1)
	v_pk_mul_f32 v[62:63], v[124:125], v[104:105]
	v_pk_mul_f32 v[60:61], v[122:123], v[102:103]
	ds_read_b128 v[82:85], v144 offset:11808
	v_pk_mul_f32 v[16:17], v[18:19], v[16:17]
	s_waitcnt lgkmcnt(1)
	v_mfma_f32_32x32x16_bf16 v[48:63], v[126:129], v[22:25], v[48:63]
	v_mul_f32_e64 v18, v20, v64
	v_mul_f32_e64 v19, v21, v65
	v_mul_f32_e64 v20, v26, v66
	v_mul_f32_e64 v21, v27, v67
	v_mul_f32_e64 v22, v28, v68
	v_mul_f32_e64 v23, v29, v69
	v_pk_mul_f32 v[24:25], v[118:119], v[70:71]
	v_pk_mul_f32 v[26:27], v[120:121], v[72:73]
	v_pk_mul_f32 v[28:29], v[122:123], v[74:75]
	v_pk_mul_f32 v[30:31], v[124:125], v[76:77]
	s_waitcnt lgkmcnt(0)
	s_waitcnt lgkmcnt(0)
	v_mfma_f32_32x32x16_bf16 v[48:63], v[82:85], v[106:109], v[48:63]
	v_mfma_f32_32x32x16_bf16 v[16:31], v[126:129], v[110:113], v[16:31]
	v_mfma_f32_32x32x16_bf16 v[16:31], v[82:85], v[114:117], v[16:31]
	v_mov_b32_e32 v82, v94
	s_mov_b64 s[16:17], s[44:45]
	v_or_b32_e32 v95, 32, v93
	v_and_b32_e32 v124, 31, v82
	v_ashrrev_i32_e32 v125, 5, v82
	v_mov_b64_e32 v[64:65], s[16:17]
	s_movk_i32 s2, 0x1200
	v_mad_i64_i32 v[64:65], s[2:3], v95, s2, v[64:65]
	v_ashrrev_i32_e32 v83, 31, v82
	v_lshl_add_u64 v[64:65], v[64:65], 0, v[90:91]
	v_lshl_add_u64 v[64:65], v[82:83], 1, v[64:65]
	v_lshl_add_u64 v[114:115], v[64:65], 0, s[0:1]
	global_load_ushort v88, v[114:115], off offset:2560
	global_load_ushort v81, v[114:115], off offset:3072
	v_add_co_u32_e32 v112, vcc, s7, v64
	s_mov_b32 s0, 0xb20f000
	s_nop 0
	v_addc_co_u32_e32 v113, vcc, 0, v65, vcc
	global_load_ushort v126, v[112:113], off offset:3584
	v_add_co_u32_e32 v110, vcc, s11, v64
	v_lshl_add_u32 v83, v82, 1, v92
	s_nop 0
	v_addc_co_u32_e32 v111, vcc, 0, v65, vcc
	v_add_co_u32_e32 v108, vcc, s12, v64
	s_waitcnt vmcnt(1)
	v_lshlrev_b32_e32 v81, 16, v81
	v_max_f32_e32 v81, v81, v81
	v_med3_f32 v81, v81, s9, v244
	v_mul_f32_e32 v81, 0xbfb8aa3b, v81
	v_exp_f32_e32 v81, v81
	v_addc_co_u32_e32 v109, vcc, 0, v65, vcc
	v_add_co_u32_e32 v106, vcc, s13, v64
	v_add_f32_e32 v116, 1.0, v81
	v_rcp_f32_e32 v116, v116
	v_addc_co_u32_e32 v107, vcc, 0, v65, vcc
	v_add_co_u32_e32 v104, vcc, s14, v64
	v_fma_f32 v117, v80, v116, v149
	v_max_f32_e32 v183, 0xda24260, v117
	v_mul_f32_e32 v81, v81, v116
	v_rcp_f32_e32 v116, v183
	v_mul_f32_e32 v81, v80, v81
	v_addc_co_u32_e32 v105, vcc, 0, v65, vcc
	v_mul_f32_e32 v81, v81, v116
	v_bfe_u32 v116, v81, 16, 1
	v_add3_u32 v133, v81, v116, s10
	global_load_ushort v81, v[114:115], off offset:2048
	global_load_ushort v127, v[110:111], off offset:512
	global_load_ushort v128, v[108:109], off offset:1536
	global_load_ushort v129, v[106:107], off offset:2560
	global_load_ushort v130, v[104:105], off offset:3584
	v_add_co_u32_e32 v102, vcc, s15, v64
	s_waitcnt vmcnt(4)
	v_lshlrev_b32_e32 v81, 16, v81
	v_addc_co_u32_e32 v103, vcc, 0, v65, vcc
	v_add_co_u32_e32 v86, vcc, s18, v64
	global_load_ushort v131, v[102:103], off offset:512
	s_nop 0
	v_addc_co_u32_e32 v87, vcc, 0, v65, vcc
	v_add_co_u32_e32 v74, vcc, s19, v64
	global_load_ushort v132, v[86:87], off offset:1536
	s_nop 0
	v_addc_co_u32_e32 v75, vcc, 0, v65, vcc
	v_add_co_u32_e32 v78, vcc, s21, v64
	global_load_ushort v134, v[74:75], off offset:2560
	s_nop 0
	v_addc_co_u32_e32 v79, vcc, 0, v65, vcc
	v_add_co_u32_e32 v76, vcc, s30, v64
	global_load_ushort v135, v[78:79], off offset:3584
	s_nop 0
	v_addc_co_u32_e32 v77, vcc, 0, v65, vcc
	v_add_co_u32_e32 v84, vcc, s31, v64
	v_mul_f32_e32 v81, v183, v81
	s_nop 0
	v_addc_co_u32_e32 v85, vcc, 0, v65, vcc
	v_add_co_u32_e32 v66, vcc, s34, v64
	global_load_ushort v137, v[84:85], off offset:1536
	global_load_ushort v136, v[76:77], off offset:512
	v_addc_co_u32_e32 v67, vcc, 0, v65, vcc
	v_add_co_u32_e32 v72, vcc, s35, v64
	global_load_ushort v138, v[66:67], off offset:2560
	s_nop 0
	v_addc_co_u32_e32 v73, vcc, 0, v65, vcc
	v_add_co_u32_e32 v68, vcc, s36, v64
	global_load_ushort v139, v[72:73], off offset:3584
	s_nop 0
	v_addc_co_u32_e32 v69, vcc, 0, v65, vcc
	v_add_co_u32_e32 v70, vcc, s37, v64
	global_load_ushort v140, v[68:69], off offset:512
	s_nop 0
	v_addc_co_u32_e32 v71, vcc, 0, v65, vcc
	v_add_co_u32_e32 v116, vcc, s40, v64
	global_load_ushort v141, v[70:71], off offset:1536
	s_nop 0
	v_addc_co_u32_e32 v117, vcc, 0, v65, vcc
	global_load_ushort v187, v[116:117], off offset:3584
	global_load_ushort v182, v[116:117], off offset:2560
	v_bfe_u32 v114, v81, 16, 1
	v_add3_u32 v188, v81, v114, s10
	v_add_co_u32_e32 v114, vcc, s41, v64
	s_nop 1
	v_addc_co_u32_e32 v115, vcc, 0, v65, vcc
	v_add_co_u32_e32 v118, vcc, s46, v64
	s_nop 1
	v_addc_co_u32_e32 v119, vcc, 0, v65, vcc
	global_load_ushort v180, v[118:119], off offset:-4096
	global_load_ushort v176, v[112:113], off offset:3072
	global_load_ushort v175, v[118:119], off offset:512
	global_load_ushort v170, v[114:115], off offset:3584
	global_load_ushort v181, v[110:111], off offset:1024
	global_load_ushort v178, v[110:111], off
	v_add_co_u32_e32 v120, vcc, s28, v64
	s_nop 1
	v_addc_co_u32_e32 v121, vcc, 0, v65, vcc
	v_add_co_u32_e32 v122, vcc, s29, v64
	global_load_ushort v186, v[120:121], off offset:1536
	global_load_ushort v185, v[120:121], off offset:512
	global_load_ushort v184, v[108:109], off offset:2048
	global_load_ushort v179, v[108:109], off offset:1024
	v_addc_co_u32_e32 v123, vcc, 0, v65, vcc
	v_add_co_u32_e32 v190, vcc, s42, v64
	global_load_ushort v177, v[122:123], off offset:2560
	global_load_ushort v173, v[122:123], off offset:1536
	global_load_ushort v174, v[106:107], off offset:3072
	global_load_ushort v172, v[106:107], off offset:2048
	v_addc_co_u32_e32 v191, vcc, 0, v65, vcc
	v_add_co_u32_e32 v106, vcc, s6, v64
	global_load_ushort v171, v[190:191], off offset:3584
	global_load_ushort v169, v[190:191], off offset:2560
	v_addc_co_u32_e32 v107, vcc, 0, v65, vcc
	v_add_co_u32_e32 v154, vcc, s49, v64
	s_waitcnt vmcnt(4)
	v_lshlrev_b32_e32 v173, 16, v173
	v_addc_co_u32_e32 v155, vcc, 0, v65, vcc
	v_add_co_u32_e32 v192, vcc, s0, v64
	s_mov_b32 s0, 0xb211000
	s_nop 0
	v_addc_co_u32_e32 v193, vcc, 0, v65, vcc
	v_add_co_u32_e32 v194, vcc, s0, v64
	s_mov_b32 s0, 0xb21a000
	s_nop 0
	v_addc_co_u32_e32 v195, vcc, 0, v65, vcc
	v_add_co_u32_e32 v108, vcc, s43, v64
	global_load_ushort v166, v[154:155], off offset:-4096
	global_load_ushort v164, v[104:105], off offset:3072
	global_load_ushort v167, v[154:155], off offset:512
	global_load_ushort v158, v[106:107], off offset:3584
	global_load_ushort v168, v[102:103], off offset:1024
	global_load_ushort v163, v[102:103], off
	v_addc_co_u32_e32 v109, vcc, 0, v65, vcc
	v_add_co_u32_e32 v110, vcc, s47, v64
	global_load_ushort v165, v[192:193], off offset:1536
	global_load_ushort v157, v[192:193], off offset:512
	global_load_ushort v162, v[86:87], off offset:2048
	global_load_ushort v156, v[86:87], off offset:1024
	v_addc_co_u32_e32 v111, vcc, 0, v65, vcc
	v_add_co_u32_e32 v112, vcc, s48, v64
	global_load_ushort v159, v[194:195], off offset:2560
	global_load_ushort v81, v[194:195], off offset:1536
	v_addc_co_u32_e32 v113, vcc, 0, v65, vcc
	v_add_co_u32_e32 v114, vcc, s0, v64
	s_mov_b32 s0, 0xb223000
	s_nop 0
	v_addc_co_u32_e32 v115, vcc, 0, v65, vcc
	v_add_co_u32_e32 v86, vcc, s0, v64
	s_mov_b32 s0, 0xb221000
	s_nop 0
	v_addc_co_u32_e32 v87, vcc, 0, v65, vcc
	v_add_co_u32_e32 v102, vcc, s0, v64
	s_mov_b32 s0, 0xb21f000
	s_nop 0
	v_addc_co_u32_e32 v103, vcc, 0, v65, vcc
	v_add_co_u32_e32 v104, vcc, s0, v64
	global_load_ushort v142, v[86:87], off offset:2048
	global_load_ushort v143, v[102:103], off offset:1024
	global_load_ushort v145, v[68:69], off offset:-4096
	v_addc_co_u32_e32 v105, vcc, 0, v65, vcc
	v_add_co_u32_e32 v106, vcc, s97, v64
	s_nop 1
	v_addc_co_u32_e32 v107, vcc, 0, v65, vcc
	global_load_ushort v146, v[106:107], off offset:3072
	global_load_ushort v147, v[114:115], off offset:2048
	global_load_ushort v150, v[112:113], off offset:1024
	global_load_ushort v151, v[76:77], off offset:-4096
	global_load_ushort v152, v[108:109], off offset:3072
	global_load_ushort v153, v[194:195], off offset:2048
	global_load_ushort v144, v[192:193], off offset:1024
	s_nop 0
	global_load_ushort v154, v[154:155], off
	s_nop 0
	global_load_ushort v155, v[190:191], off offset:3072
	s_nop 0
	global_load_ushort v122, v[122:123], off offset:2048
	s_nop 0
	global_load_ushort v120, v[120:121], off offset:1024
	s_nop 0
	global_load_ushort v118, v[118:119], off
	s_nop 0
	global_load_ushort v121, v[116:117], off offset:3072
	v_lshlrev_b32_e32 v116, 16, v187
	v_max_f32_e32 v116, v116, v116
	v_med3_f32 v116, v116, s9, v244
	v_mul_f32_e32 v116, 0xbfb8aa3b, v116
	v_exp_f32_e32 v116, v116
	ds_write_b16_d16_hi v83, v188
	ds_write_b16_d16_hi v83, v133 offset:4608
	v_add_f32_e32 v117, 1.0, v116
	v_rcp_f32_e32 v117, v117
	s_nop 0
	v_fma_f32 v119, v80, v117, v149
	v_mul_f32_e32 v116, v116, v117
	v_mul_f32_e32 v117, v183, v119
	v_max_f32_e32 v117, 0xda24260, v117
	v_rcp_f32_e32 v119, v117
	v_mul_f32_e32 v116, v80, v116
	v_mul_f32_e32 v116, v116, v119
	v_bfe_u32 v119, v116, 16, 1
	v_add3_u32 v119, v116, v119, s10
	v_lshlrev_b32_e32 v116, 16, v182
	v_mul_f32_e32 v116, v117, v116
	v_bfe_u32 v123, v116, 16, 1
	v_add3_u32 v116, v116, v123, s10
	ds_write_b16_d16_hi v83, v116 offset:144
	ds_write_b16_d16_hi v83, v119 offset:4752
	v_lshlrev_b32_e32 v116, 16, v180
	v_max_f32_e32 v116, v116, v116
	v_med3_f32 v116, v116, s9, v244
	v_mul_f32_e32 v116, 0xbfb8aa3b, v116
	v_exp_f32_e32 v116, v116
	s_nop 0
	v_add_f32_e32 v123, 1.0, v116
	v_rcp_f32_e32 v123, v123
	s_nop 0
	v_fma_f32 v180, v80, v123, v149
	v_mul_f32_e32 v117, v117, v180
	v_max_f32_e32 v117, 0xda24260, v117
	v_mul_f32_e32 v116, v116, v123
	v_rcp_f32_e32 v123, v117
	v_mul_f32_e32 v116, v80, v116
	v_mul_f32_e32 v116, v116, v123
	v_bfe_u32 v123, v116, 16, 1
	v_add3_u32 v116, v116, v123, s10
	v_lshlrev_b32_e32 v123, 16, v176
	v_mul_f32_e32 v123, v117, v123
	v_bfe_u32 v176, v123, 16, 1
	v_add3_u32 v123, v123, v176, s10
	ds_write_b16_d16_hi v83, v123 offset:288
	ds_write_b16_d16_hi v83, v116 offset:4896
	v_lshlrev_b32_e32 v123, 16, v175
	v_max_f32_e32 v123, v123, v123
	v_med3_f32 v123, v123, s9, v244
	v_mul_f32_e32 v123, 0xbfb8aa3b, v123
	v_exp_f32_e32 v123, v123
	s_nop 0
	v_add_f32_e32 v175, 1.0, v123
	v_rcp_f32_e32 v175, v175
	s_nop 0
	v_fma_f32 v176, v80, v175, v149
	v_mul_f32_e32 v117, v117, v176
	v_mul_f32_e32 v123, v123, v175
	v_max_f32_e32 v175, 0xda24260, v117
	v_rcp_f32_e32 v117, v175
	v_mul_f32_e32 v123, v80, v123
	v_mul_f32_e32 v117, v123, v117
	v_bfe_u32 v123, v117, 16, 1
	v_add3_u32 v117, v117, v123, s10
	v_lshlrev_b32_e32 v123, 16, v170
	v_mul_f32_e32 v123, v175, v123
	v_bfe_u32 v170, v123, 16, 1
	v_add3_u32 v123, v123, v170, s10
	ds_write_b16_d16_hi v83, v123 offset:432
	ds_write_b16_d16_hi v83, v117 offset:5040
	v_lshlrev_b32_e32 v123, 16, v181
	v_max_f32_e32 v123, v123, v123
	v_med3_f32 v123, v123, s9, v244
	v_mul_f32_e32 v123, 0xbfb8aa3b, v123
	v_exp_f32_e32 v123, v123
	s_nop 0
	v_add_f32_e32 v170, 1.0, v123
	v_rcp_f32_e32 v170, v170
	s_nop 0
	v_fma_f32 v176, v80, v170, v149
	v_mul_f32_e32 v123, v123, v170
	v_mul_f32_e32 v170, v175, v176
	v_max_f32_e32 v170, 0xda24260, v170
	v_rcp_f32_e32 v175, v170
	v_mul_f32_e32 v123, v80, v123
	v_mul_f32_e32 v123, v123, v175
	v_bfe_u32 v175, v123, 16, 1
	v_add3_u32 v123, v123, v175, s10
	v_lshlrev_b32_e32 v175, 16, v178
	v_mul_f32_e32 v175, v170, v175
	v_bfe_u32 v176, v175, 16, 1
	v_add3_u32 v175, v175, v176, s10
	ds_write_b16_d16_hi v83, v175 offset:576
	ds_write_b16_d16_hi v83, v123 offset:5184
	v_lshlrev_b32_e32 v175, 16, v186
	v_max_f32_e32 v175, v175, v175
	v_med3_f32 v175, v175, s9, v244
	v_mul_f32_e32 v175, 0xbfb8aa3b, v175
	v_exp_f32_e32 v175, v175
	s_nop 0
	v_add_f32_e32 v176, 1.0, v175
	v_rcp_f32_e32 v176, v176
	s_nop 0
	v_fma_f32 v178, v80, v176, v149
	v_mul_f32_e32 v170, v170, v178
	v_max_f32_e32 v170, 0xda24260, v170
	v_mul_f32_e32 v175, v175, v176
	v_rcp_f32_e32 v176, v170
	v_mul_f32_e32 v175, v80, v175
	v_mul_f32_e32 v175, v175, v176
	v_bfe_u32 v176, v175, 16, 1
	v_add3_u32 v175, v175, v176, s10
	v_lshlrev_b32_e32 v176, 16, v185
	v_mul_f32_e32 v176, v170, v176
	v_bfe_u32 v178, v176, 16, 1
	v_add3_u32 v176, v176, v178, s10
	ds_write_b16_d16_hi v83, v176 offset:720
	ds_write_b16_d16_hi v83, v175 offset:5328
	v_lshlrev_b32_e32 v176, 16, v184
	v_max_f32_e32 v176, v176, v176
	v_med3_f32 v176, v176, s9, v244
	v_mul_f32_e32 v176, 0xbfb8aa3b, v176
	v_exp_f32_e32 v176, v176
	s_nop 0
	v_add_f32_e32 v178, 1.0, v176
	v_rcp_f32_e32 v178, v178
	s_nop 0
	v_fma_f32 v180, v80, v178, v149
	v_mul_f32_e32 v170, v170, v180
	v_mul_f32_e32 v176, v176, v178
	v_max_f32_e32 v178, 0xda24260, v170
	v_rcp_f32_e32 v170, v178
	v_mul_f32_e32 v176, v80, v176
	v_mul_f32_e32 v170, v176, v170
	v_bfe_u32 v176, v170, 16, 1
	v_add3_u32 v170, v170, v176, s10
	v_lshlrev_b32_e32 v176, 16, v179
	v_mul_f32_e32 v176, v178, v176
	v_bfe_u32 v179, v176, 16, 1
	v_add3_u32 v176, v176, v179, s10
	ds_write_b16_d16_hi v83, v176 offset:864
	ds_write_b16_d16_hi v83, v170 offset:5472
	v_lshlrev_b32_e32 v176, 16, v177
	v_max_f32_e32 v176, v176, v176
	v_med3_f32 v176, v176, s9, v244
	v_mul_f32_e32 v176, 0xbfb8aa3b, v176
	v_exp_f32_e32 v176, v176
	s_nop 0
	v_add_f32_e32 v177, 1.0, v176
	v_rcp_f32_e32 v177, v177
	s_nop 0
	v_fma_f32 v179, v80, v177, v149
	v_mul_f32_e32 v176, v176, v177
	v_mul_f32_e32 v177, v178, v179
	v_max_f32_e32 v177, 0xda24260, v177
	v_rcp_f32_e32 v178, v177
	v_mul_f32_e32 v176, v80, v176
	v_mul_f32_e32 v173, v177, v173
	v_mul_f32_e32 v176, v176, v178
	v_bfe_u32 v178, v176, 16, 1
	v_add3_u32 v176, v176, v178, s10
	v_bfe_u32 v178, v173, 16, 1
	v_add3_u32 v173, v173, v178, s10
	ds_write_b16_d16_hi v83, v173 offset:1008
	ds_write_b16_d16_hi v83, v176 offset:5616
	s_waitcnt vmcnt(31)
	v_lshlrev_b32_e32 v173, 16, v174
	v_max_f32_e32 v173, v173, v173
	v_med3_f32 v173, v173, s9, v244
	v_mul_f32_e32 v173, 0xbfb8aa3b, v173
	v_exp_f32_e32 v173, v173
	s_waitcnt vmcnt(29)
	v_lshlrev_b32_e32 v171, 16, v171
	v_max_f32_e32 v171, v171, v171
	v_med3_f32 v171, v171, s9, v244
	v_add_f32_e32 v174, 1.0, v173
	v_rcp_f32_e32 v174, v174
	v_mul_f32_e32 v171, 0xbfb8aa3b, v171
	v_exp_f32_e32 v178, v171
	v_lshlrev_b32_e32 v172, 16, v172
	v_fma_f32 v171, v80, v174, v149
	v_mul_f32_e32 v171, v177, v171
	v_max_f32_e32 v177, 0xda24260, v171
	v_rcp_f32_e32 v171, v177
	v_mul_f32_e32 v173, v173, v174
	v_mul_f32_e32 v173, v80, v173
	v_mul_f32_e32 v172, v177, v172
	v_mul_f32_e32 v171, v173, v171
	v_bfe_u32 v173, v171, 16, 1
	v_add3_u32 v171, v171, v173, s10
	v_add_f32_e32 v173, 1.0, v178
	v_rcp_f32_e32 v173, v173
	v_bfe_u32 v174, v172, 16, 1
	v_add3_u32 v172, v172, v174, s10
	ds_write_b16_d16_hi v83, v172 offset:1152
	v_fma_f32 v172, v80, v173, v149
	v_mul_f32_e32 v172, v177, v172
	v_max_f32_e32 v174, 0xda24260, v172
	v_rcp_f32_e32 v172, v174
	v_mul_f32_e32 v173, v178, v173
	v_mul_f32_e32 v173, v80, v173
	s_waitcnt vmcnt(28)
	v_lshlrev_b32_e32 v169, 16, v169
	v_mul_f32_e32 v172, v173, v172
	v_bfe_u32 v173, v172, 16, 1
	v_mul_f32_e32 v169, v174, v169
	ds_write_b16_d16_hi v83, v171 offset:5760
	v_add3_u32 v172, v172, v173, s10
	v_bfe_u32 v173, v169, 16, 1
	v_add3_u32 v169, v169, v173, s10
	global_load_ushort v173, v[74:75], off offset:3072
	global_load_ushort v177, v[108:109], off offset:2560
	s_nop 0
	global_load_ushort v78, v[78:79], off offset:3072
	s_nop 0
	global_load_ushort v79, v[76:77], off offset:1024
	global_load_ushort v178, v[84:85], off offset:2048
	s_nop 0
	global_load_ushort v85, v[84:85], off offset:1024
	s_nop 0
	global_load_ushort v76, v[76:77], off
	s_nop 0
	global_load_ushort v77, v[74:75], off offset:2048
	s_waitcnt vmcnt(35)
	v_lshlrev_b32_e32 v74, 16, v166
	v_max_f32_e32 v74, v74, v74
	v_med3_f32 v74, v74, s9, v244
	v_mul_f32_e32 v74, 0xbfb8aa3b, v74
	v_exp_f32_e32 v84, v74
	v_add_co_u32_e32 v74, vcc, s5, v64
	s_waitcnt vmcnt(32)
	v_lshlrev_b32_e32 v158, 16, v158
	v_addc_co_u32_e32 v75, vcc, 0, v65, vcc
	v_add_f32_e32 v166, 1.0, v84
	global_load_ushort v108, v[108:109], off offset:3584
	s_nop 0
	global_load_ushort v109, v[74:75], off
	s_nop 0
	global_load_ushort v110, v[110:111], off offset:512
	s_nop 0
	global_load_ushort v74, v[74:75], off offset:3584
	s_nop 0
	global_load_ushort v75, v[112:113], off offset:1536
	global_load_ushort v111, v[114:115], off offset:2560
	s_nop 0
	global_load_ushort v114, v[114:115], off offset:1536
	s_nop 0
	global_load_ushort v112, v[112:113], off offset:512
	v_rcp_f32_e32 v166, v166
	s_waitcnt vmcnt(37)
	v_lshlrev_b32_e32 v165, 16, v165
	v_max_f32_e32 v165, v165, v165
	v_med3_f32 v165, v165, s9, v244
	v_fma_f32 v113, v80, v166, v149
	v_mul_f32_e32 v113, v174, v113
	v_mul_f32_e32 v84, v84, v166
	v_lshlrev_b32_e32 v166, 16, v167
	v_max_f32_e32 v113, 0xda24260, v113
	v_max_f32_e32 v166, v166, v166
	v_rcp_f32_e32 v115, v113
	v_med3_f32 v166, v166, s9, v244
	v_mul_f32_e32 v166, 0xbfb8aa3b, v166
	v_exp_f32_e32 v166, v166
	v_mul_f32_e32 v84, v80, v84
	v_mul_f32_e32 v84, v84, v115
	v_bfe_u32 v115, v84, 16, 1
	v_add3_u32 v84, v84, v115, s10
	v_lshlrev_b32_e32 v115, 16, v164
	v_add_f32_e32 v164, 1.0, v166
	v_rcp_f32_e32 v164, v164
	v_mul_f32_e32 v115, v113, v115
	v_bfe_u32 v167, v115, 16, 1
	v_add3_u32 v115, v115, v167, s10
	ds_write_b16_d16_hi v83, v115 offset:1440
	v_fma_f32 v115, v80, v164, v149
	v_mul_f32_e32 v113, v113, v115
	v_mul_f32_e32 v164, v166, v164
	v_lshlrev_b32_e32 v166, 16, v168
	v_max_f32_e32 v113, 0xda24260, v113
	v_max_f32_e32 v166, v166, v166
	v_rcp_f32_e32 v115, v113
	v_med3_f32 v166, v166, s9, v244
	v_mul_f32_e32 v166, 0xbfb8aa3b, v166
	v_exp_f32_e32 v166, v166
	v_mul_f32_e32 v164, v80, v164
	v_mul_f32_e32 v115, v164, v115
	v_bfe_u32 v164, v115, 16, 1
	v_add3_u32 v115, v115, v164, s10
	v_add_f32_e32 v164, 1.0, v166
	v_rcp_f32_e32 v164, v164
	v_mul_f32_e32 v158, v113, v158
	v_bfe_u32 v167, v158, 16, 1
	v_add3_u32 v158, v158, v167, s10
	ds_write_b16_d16_hi v83, v158 offset:1584
	v_fma_f32 v158, v80, v164, v149
	v_mul_f32_e32 v113, v113, v158
	v_max_f32_e32 v113, 0xda24260, v113
	v_rcp_f32_e32 v158, v113
	v_mul_f32_e32 v165, 0xbfb8aa3b, v165
	v_mul_f32_e32 v164, v166, v164
	v_exp_f32_e32 v165, v165
	v_mul_f32_e32 v164, v80, v164
	v_mul_f32_e32 v158, v164, v158
	v_bfe_u32 v164, v158, 16, 1
	v_add3_u32 v158, v158, v164, s10
	v_add_f32_e32 v164, 1.0, v165
	v_lshlrev_b32_e32 v163, 16, v163
	v_rcp_f32_e32 v164, v164
	v_mul_f32_e32 v163, v113, v163
	v_bfe_u32 v166, v163, 16, 1
	v_add3_u32 v163, v163, v166, s10
	ds_write_b16_d16_hi v83, v163 offset:1728
	v_fma_f32 v163, v80, v164, v149
	v_mul_f32_e32 v113, v113, v163
	s_waitcnt vmcnt(35)
	v_lshlrev_b32_e32 v162, 16, v162
	v_max_f32_e32 v113, 0xda24260, v113
	v_max_f32_e32 v162, v162, v162
	v_rcp_f32_e32 v163, v113
	v_med3_f32 v162, v162, s9, v244
	v_mul_f32_e32 v162, 0xbfb8aa3b, v162
	v_mul_f32_e32 v164, v165, v164
	v_exp_f32_e32 v162, v162
	v_mul_f32_e32 v164, v80, v164
	v_mul_f32_e32 v163, v164, v163
	v_bfe_u32 v164, v163, 16, 1
	v_add3_u32 v163, v163, v164, s10
	v_add_f32_e32 v164, 1.0, v162
	v_lshlrev_b32_e32 v157, 16, v157
	v_rcp_f32_e32 v164, v164
	v_mul_f32_e32 v157, v113, v157
	v_bfe_u32 v165, v157, 16, 1
	v_add3_u32 v157, v157, v165, s10
	ds_write_b16_d16_hi v83, v157 offset:1872
	v_fma_f32 v157, v80, v164, v149
	v_mul_f32_e32 v113, v113, v157
	s_waitcnt vmcnt(33)
	v_lshlrev_b32_e32 v159, 16, v159
	v_max_f32_e32 v113, 0xda24260, v113
	v_max_f32_e32 v159, v159, v159
	v_rcp_f32_e32 v157, v113
	v_med3_f32 v159, v159, s9, v244
	v_mul_f32_e32 v159, 0xbfb8aa3b, v159
	v_mul_f32_e32 v162, v162, v164
	v_exp_f32_e32 v159, v159
	v_mul_f32_e32 v162, v80, v162
	v_mul_f32_e32 v157, v162, v157
	v_bfe_u32 v162, v157, 16, 1
	v_add3_u32 v157, v157, v162, s10
	v_add_f32_e32 v162, 1.0, v159
	v_lshlrev_b32_e32 v156, 16, v156
	v_rcp_f32_e32 v162, v162
	v_mul_f32_e32 v156, v113, v156
	v_bfe_u32 v164, v156, 16, 1
	v_add3_u32 v156, v156, v164, s10
	ds_write_b16_d16_hi v83, v156 offset:2016
	v_fma_f32 v156, v80, v162, v149
	v_mul_f32_e32 v113, v113, v156
	v_max_f32_e32 v113, 0xda24260, v113
	v_rcp_f32_e32 v156, v113
	v_mul_f32_e32 v159, v159, v162
	v_mul_f32_e32 v159, v80, v159
	s_waitcnt vmcnt(32)
	v_lshlrev_b32_e32 v81, 16, v81
	v_mul_f32_e32 v156, v159, v156
	v_bfe_u32 v159, v156, 16, 1
	v_mul_f32_e32 v81, v113, v81
	v_add3_u32 v159, v156, v159, s10
	v_bfe_u32 v156, v81, 16, 1
	v_add3_u32 v81, v81, v156, s10
	ds_write_b16_d16_hi v83, v169 offset:1296
	ds_write_b16_d16_hi v83, v172 offset:5904
	ds_write_b16_d16_hi v83, v84 offset:6048
	ds_write_b16_d16_hi v83, v115 offset:6192
	ds_write_b16_d16_hi v83, v158 offset:6336
	ds_write_b16_d16_hi v83, v163 offset:6480
	ds_write_b16_d16_hi v83, v157 offset:6624
	ds_write_b16_d16_hi v83, v81 offset:2160
	ds_write_b16_d16_hi v83, v159 offset:6768
	s_waitcnt vmcnt(15)
	v_lshlrev_b32_e32 v81, 16, v173
	v_max_f32_e32 v81, v81, v81
	v_med3_f32 v81, v81, s9, v244
	v_mul_f32_e32 v81, 0xbfb8aa3b, v81
	v_exp_f32_e32 v81, v81
	s_waitcnt vmcnt(7)
	v_lshlrev_b32_e32 v108, 16, v108
	v_max_f32_e32 v108, v108, v108
	v_med3_f32 v108, v108, s9, v244
	v_add_f32_e32 v156, 1.0, v81
	v_rcp_f32_e32 v156, v156
	v_mul_f32_e32 v108, 0xbfb8aa3b, v108
	v_exp_f32_e32 v108, v108
	v_lshlrev_b32_e32 v77, 16, v77
	v_fma_f32 v162, v80, v156, v149
	v_mul_f32_e32 v113, v113, v162
	v_max_f32_e32 v113, 0xda24260, v113
	v_rcp_f32_e32 v162, v113
	v_mul_f32_e32 v81, v81, v156
	v_mul_f32_e32 v81, v80, v81
	v_mul_f32_e32 v77, v113, v77
	v_mul_f32_e32 v81, v81, v162
	v_bfe_u32 v156, v81, 16, 1
	v_add3_u32 v156, v81, v156, s10
	v_add_f32_e32 v81, 1.0, v108
	v_rcp_f32_e32 v81, v81
	v_bfe_u32 v162, v77, 16, 1
	v_add3_u32 v77, v77, v162, s10
	ds_write_b16_d16_hi v83, v77 offset:2304
	v_fma_f32 v77, v80, v81, v149
	ds_write_b16_d16_hi v83, v156 offset:6912
	v_mul_f32_e32 v77, v113, v77
	global_load_ushort v162, v[66:67], off offset:3072
	global_load_ushort v164, v[72:73], off offset:3072
	global_load_ushort v165, v[68:69], off offset:1024
	global_load_ushort v166, v[70:71], off offset:2048
	global_load_ushort v167, v[86:87], off offset:1536
	global_load_ushort v168, v[70:71], off offset:1024
	global_load_ushort v169, v[68:69], off
	global_load_ushort v173, v[66:67], off offset:2048
	s_waitcnt vmcnt(14)
	v_lshlrev_b32_e32 v66, 16, v109
	v_max_f32_e32 v77, 0xda24260, v77
	v_max_f32_e32 v66, v66, v66
	v_rcp_f32_e32 v113, v77
	v_med3_f32 v66, v66, s9, v244
	v_mul_f32_e32 v66, 0xbfb8aa3b, v66
	v_mul_f32_e32 v81, v108, v81
	v_exp_f32_e32 v66, v66
	v_mul_f32_e32 v81, v80, v81
	v_mul_f32_e32 v81, v81, v113
	v_bfe_u32 v108, v81, 16, 1
	v_add_co_u32_e32 v64, vcc, s4, v64
	v_add3_u32 v108, v81, v108, s10
	v_lshlrev_b32_e32 v81, 16, v177
	v_addc_co_u32_e32 v65, vcc, 0, v65, vcc
	v_add_f32_e32 v67, 1.0, v66
	global_load_ushort v174, v[106:107], off offset:3584
	global_load_ushort v177, v[64:65], off
	global_load_ushort v179, v[64:65], off offset:3584
	s_nop 0
	global_load_ushort v106, v[106:107], off offset:2560
	s_nop 0
	global_load_ushort v104, v[104:105], off offset:512
	s_nop 0
	global_load_ushort v180, v[102:103], off offset:1536
	s_nop 0
	global_load_ushort v102, v[102:103], off offset:512
	s_nop 0
	global_load_ushort v86, v[86:87], off offset:2560
	v_rcp_f32_e32 v67, v67
	v_mul_f32_e32 v81, v77, v81
	v_bfe_u32 v113, v81, 16, 1
	v_add3_u32 v81, v81, v113, s10
	v_fma_f32 v64, v80, v67, v149
	v_mul_f32_e32 v64, v77, v64
	v_mul_f32_e32 v66, v66, v67
	s_waitcnt vmcnt(21)
	v_lshlrev_b32_e32 v67, 16, v110
	v_max_f32_e32 v64, 0xda24260, v64
	v_max_f32_e32 v67, v67, v67
	v_rcp_f32_e32 v65, v64
	v_med3_f32 v67, v67, s9, v244
	v_mul_f32_e32 v67, 0xbfb8aa3b, v67
	v_exp_f32_e32 v67, v67
	v_mul_f32_e32 v66, v80, v66
	v_mul_f32_e32 v65, v66, v65
	v_bfe_u32 v66, v65, 16, 1
	v_add3_u32 v181, v65, v66, s10
	v_add_f32_e32 v66, 1.0, v67
	v_lshlrev_b32_e32 v65, 16, v78
	v_rcp_f32_e32 v66, v66
	v_mul_f32_e32 v65, v64, v65
	v_bfe_u32 v68, v65, 16, 1
	v_add3_u32 v65, v65, v68, s10
	ds_write_b16_d16_hi v83, v65 offset:2592
	v_fma_f32 v65, v80, v66, v149
	v_mul_f32_e32 v66, v67, v66
	v_lshlrev_b32_e32 v67, 16, v79
	v_mul_f32_e32 v64, v64, v65
	v_max_f32_e32 v67, v67, v67
	v_max_f32_e32 v64, 0xda24260, v64
	v_med3_f32 v67, v67, s9, v244
	v_rcp_f32_e32 v65, v64
	v_mul_f32_e32 v67, 0xbfb8aa3b, v67
	v_exp_f32_e32 v67, v67
	v_mul_f32_e32 v66, v80, v66
	v_mul_f32_e32 v65, v66, v65
	v_bfe_u32 v66, v65, 16, 1
	v_add_f32_e32 v68, 1.0, v67
	v_add3_u32 v65, v65, v66, s10
	s_waitcnt vmcnt(20)
	v_lshlrev_b32_e32 v66, 16, v74
	v_rcp_f32_e32 v68, v68
	v_mul_f32_e32 v66, v64, v66
	v_bfe_u32 v69, v66, 16, 1
	v_add3_u32 v66, v66, v69, s10
	ds_write_b16_d16_hi v83, v66 offset:2736
	v_fma_f32 v66, v80, v68, v149
	v_mul_f32_e32 v64, v64, v66
	v_mul_f32_e32 v67, v67, v68
	s_waitcnt vmcnt(19)
	v_lshlrev_b32_e32 v68, 16, v75
	v_max_f32_e32 v64, 0xda24260, v64
	v_max_f32_e32 v68, v68, v68
	v_rcp_f32_e32 v66, v64
	v_med3_f32 v68, v68, s9, v244
	v_mul_f32_e32 v68, 0xbfb8aa3b, v68
	v_exp_f32_e32 v68, v68
	v_mul_f32_e32 v67, v80, v67
	v_mul_f32_e32 v66, v67, v66
	v_bfe_u32 v67, v66, 16, 1
	v_add3_u32 v182, v66, v67, s10
	v_add_f32_e32 v67, 1.0, v68
	v_lshlrev_b32_e32 v66, 16, v76
	v_rcp_f32_e32 v67, v67
	v_mul_f32_e32 v66, v64, v66
	v_bfe_u32 v69, v66, 16, 1
	v_add3_u32 v66, v66, v69, s10
	ds_write_b16_d16_hi v83, v66 offset:2880
	v_fma_f32 v66, v80, v67, v149
	v_mul_f32_e32 v67, v68, v67
	v_lshlrev_b32_e32 v68, 16, v178
	v_mul_f32_e32 v64, v64, v66
	v_max_f32_e32 v68, v68, v68
	v_max_f32_e32 v64, 0xda24260, v64
	v_med3_f32 v68, v68, s9, v244
	v_rcp_f32_e32 v66, v64
	v_mul_f32_e32 v68, 0xbfb8aa3b, v68
	v_exp_f32_e32 v68, v68
	v_mul_f32_e32 v67, v80, v67
	v_mul_f32_e32 v66, v67, v66
	v_bfe_u32 v67, v66, 16, 1
	v_add_f32_e32 v69, 1.0, v68
	v_add3_u32 v66, v66, v67, s10
	s_waitcnt vmcnt(16)
	v_lshlrev_b32_e32 v67, 16, v112
	v_rcp_f32_e32 v69, v69
	v_mul_f32_e32 v67, v64, v67
	v_bfe_u32 v70, v67, 16, 1
	v_add3_u32 v67, v67, v70, s10
	ds_write_b16_d16_hi v83, v67 offset:3024
	v_fma_f32 v67, v80, v69, v149
	v_mul_f32_e32 v64, v64, v67
	v_mul_f32_e32 v68, v68, v69
	v_lshlrev_b32_e32 v69, 16, v111
	v_max_f32_e32 v64, 0xda24260, v64
	v_max_f32_e32 v69, v69, v69
	v_rcp_f32_e32 v67, v64
	v_med3_f32 v69, v69, s9, v244
	v_mul_f32_e32 v69, 0xbfb8aa3b, v69
	v_exp_f32_e32 v69, v69
	v_mul_f32_e32 v68, v80, v68
	v_mul_f32_e32 v67, v68, v67
	v_bfe_u32 v68, v67, 16, 1
	v_add3_u32 v178, v67, v68, s10
	v_add_f32_e32 v68, 1.0, v69
	v_lshlrev_b32_e32 v67, 16, v85
	v_rcp_f32_e32 v68, v68
	v_mul_f32_e32 v67, v64, v67
	v_bfe_u32 v70, v67, 16, 1
	v_add3_u32 v67, v67, v70, s10
	ds_write_b16_d16_hi v83, v67 offset:3168
	v_fma_f32 v67, v80, v68, v149
	v_mul_f32_e32 v64, v64, v67
	v_max_f32_e32 v76, 0xda24260, v64
	v_rcp_f32_e32 v64, v76
	v_mul_f32_e32 v67, v69, v68
	v_mul_f32_e32 v67, v80, v67
	ds_write_b16_d16_hi v83, v81 offset:2448
	v_mul_f32_e32 v64, v67, v64
	v_bfe_u32 v67, v64, 16, 1
	v_add3_u32 v64, v64, v67, s10
	v_lshlrev_b32_e32 v67, 16, v114
	v_mul_f32_e32 v67, v76, v67
	v_bfe_u32 v68, v67, 16, 1
	v_add3_u32 v67, v67, v68, s10
	ds_write_b16_d16_hi v83, v108 offset:7056
	ds_write_b16_d16_hi v83, v181 offset:7200
	ds_write_b16_d16_hi v83, v65 offset:7344
	ds_write_b16_d16_hi v83, v182 offset:7488
	ds_write_b16_d16_hi v83, v66 offset:7632
	ds_write_b16_d16_hi v83, v178 offset:7776
	ds_write_b16_d16_hi v83, v67 offset:3312
	ds_write_b16_d16_hi v83, v64 offset:7920
	s_waitcnt vmcnt(15)
	v_lshlrev_b32_e32 v72, 16, v162
	v_max_f32_e32 v72, v72, v72
	v_med3_f32 v72, v72, s9, v244
	v_mul_f32_e32 v72, 0xbfb8aa3b, v72
	v_and_b32_e32 v103, 0xffff0000, v108
	v_exp_f32_e32 v108, v72
	v_lshl_or_b32 v78, v120, 16, v127
	s_waitcnt vmcnt(4)
	v_lshlrev_b32_e32 v106, 16, v106
	s_waitcnt vmcnt(3)
	v_lshlrev_b32_e32 v104, 16, v104
	v_add_f32_e32 v77, 1.0, v108
	v_rcp_f32_e32 v110, v77
	v_max_f32_e32 v104, v104, v104
	v_med3_f32 v104, v104, s9, v244
	v_mul_f32_e32 v104, 0xbfb8aa3b, v104
	v_fma_f32 v112, v80, v110, v149
	v_mul_f32_e32 v76, v76, v112
	v_max_f32_e32 v112, 0xda24260, v76
	v_lshl_or_b32 v76, v121, 16, v88
	v_mul_f32_e32 v88, v108, v110
	v_lshlrev_b32_e32 v110, 16, v174
	v_max_f32_e32 v110, v110, v110
	v_rcp_f32_e32 v114, v112
	v_med3_f32 v110, v110, s9, v244
	v_mul_f32_e32 v110, 0xbfb8aa3b, v110
	v_exp_f32_e32 v110, v110
	v_mul_f32_e32 v88, v80, v88
	v_mul_f32_e32 v88, v88, v114
	v_bfe_u32 v108, v88, 16, 1
	v_add3_u32 v120, v88, v108, s10
	v_add_f32_e32 v108, 1.0, v110
	v_lshlrev_b32_e32 v88, 16, v173
	v_rcp_f32_e32 v108, v108
	v_mul_f32_e32 v88, v112, v88
	v_bfe_u32 v114, v88, 16, 1
	v_add3_u32 v88, v88, v114, s10
	ds_write_b16_d16_hi v83, v88 offset:3456
	v_fma_f32 v88, v80, v108, v149
	v_mul_f32_e32 v88, v112, v88
	v_max_f32_e32 v88, 0xda24260, v88
	v_rcp_f32_e32 v112, v88
	v_mul_f32_e32 v108, v110, v108
	v_mul_f32_e32 v108, v80, v108
	v_mul_f32_e32 v106, v88, v106
	v_mul_f32_e32 v108, v108, v112
	v_bfe_u32 v110, v108, 16, 1
	v_add3_u32 v108, v108, v110, s10
	v_lshlrev_b32_e32 v110, 16, v177
	v_max_f32_e32 v110, v110, v110
	v_med3_f32 v110, v110, s9, v244
	v_mul_f32_e32 v110, 0xbfb8aa3b, v110
	v_exp_f32_e32 v110, v110
	v_bfe_u32 v114, v106, 16, 1
	v_add3_u32 v106, v106, v114, s10
	ds_write_b16_d16_hi v83, v106 offset:3600
	v_add_f32_e32 v112, 1.0, v110
	v_rcp_f32_e32 v112, v112
	v_and_b32_e32 v121, 0xffff0000, v108
	ds_write_b16_d16_hi v83, v108 offset:8208
	v_exp_f32_e32 v104, v104
	v_fma_f32 v106, v80, v112, v149
	v_mul_f32_e32 v88, v88, v106
	v_max_f32_e32 v88, 0xda24260, v88
	v_rcp_f32_e32 v106, v88
	v_mul_f32_e32 v108, v110, v112
	v_mul_f32_e32 v108, v80, v108
	v_lshl_or_b32 v79, v122, 16, v128
	v_mul_f32_e32 v106, v108, v106
	v_bfe_u32 v108, v106, 16, 1
	v_add3_u32 v122, v106, v108, s10
	v_add_f32_e32 v108, 1.0, v104
	v_lshlrev_b32_e32 v106, 16, v164
	v_rcp_f32_e32 v108, v108
	v_mul_f32_e32 v106, v88, v106
	v_bfe_u32 v110, v106, 16, 1
	v_add3_u32 v106, v106, v110, s10
	ds_write_b16_d16_hi v83, v106 offset:3744
	v_fma_f32 v106, v80, v108, v149
	v_mul_f32_e32 v88, v88, v106
	v_max_f32_e32 v88, 0xda24260, v88
	v_rcp_f32_e32 v106, v88
	v_mul_f32_e32 v104, v104, v108
	v_mul_f32_e32 v104, v80, v104
	v_lshlrev_b32_e32 v108, 16, v179
	v_mul_f32_e32 v104, v104, v106
	v_bfe_u32 v106, v104, 16, 1
	v_add3_u32 v104, v104, v106, s10
	v_lshlrev_b32_e32 v106, 16, v165
	v_max_f32_e32 v106, v106, v106
	v_med3_f32 v106, v106, s9, v244
	v_mul_f32_e32 v106, 0xbfb8aa3b, v106
	v_exp_f32_e32 v106, v106
	v_mul_f32_e32 v108, v88, v108
	v_bfe_u32 v112, v108, 16, 1
	v_add3_u32 v108, v108, v112, s10
	v_add_f32_e32 v110, 1.0, v106
	v_rcp_f32_e32 v110, v110
	ds_write_b16_d16_hi v83, v108 offset:3888
	v_lshl_or_b32 v74, v144, 16, v131
	v_and_b32_e32 v131, 0xffff0000, v104
	v_fma_f32 v108, v80, v110, v149
	v_mul_f32_e32 v88, v88, v108
	v_max_f32_e32 v88, 0xda24260, v88
	v_rcp_f32_e32 v108, v88
	ds_write_b16_d16_hi v83, v104 offset:8496
	v_mul_f32_e32 v104, v106, v110
	v_mul_f32_e32 v104, v80, v104
	v_mul_f32_e32 v104, v104, v108
	s_waitcnt vmcnt(2)
	v_lshlrev_b32_e32 v108, 16, v180
	v_max_f32_e32 v108, v108, v108
	v_med3_f32 v108, v108, s9, v244
	v_mul_f32_e32 v108, 0xbfb8aa3b, v108
	v_exp_f32_e32 v108, v108
	v_bfe_u32 v106, v104, 16, 1
	v_lshl_or_b32 v75, v153, 16, v132
	v_add3_u32 v132, v104, v106, s10
	v_add_f32_e32 v106, 1.0, v108
	v_lshlrev_b32_e32 v104, 16, v169
	v_rcp_f32_e32 v106, v106
	v_mul_f32_e32 v104, v88, v104
	v_bfe_u32 v110, v104, 16, 1
	v_add3_u32 v104, v104, v110, s10
	ds_write_b16_d16_hi v83, v104 offset:4032
	v_fma_f32 v104, v80, v106, v149
	v_mul_f32_e32 v88, v88, v104
	v_max_f32_e32 v88, 0xda24260, v88
	v_rcp_f32_e32 v104, v88
	v_mul_f32_e32 v106, v108, v106
	v_mul_f32_e32 v106, v80, v106
	s_waitcnt vmcnt(1)
	v_lshlrev_b32_e32 v102, 16, v102
	v_mul_f32_e32 v104, v106, v104
	v_bfe_u32 v106, v104, 16, 1
	v_add3_u32 v104, v104, v106, s10
	v_lshlrev_b32_e32 v106, 16, v166
	v_max_f32_e32 v106, v106, v106
	v_med3_f32 v106, v106, s9, v244
	v_mul_f32_e32 v106, 0xbfb8aa3b, v106
	v_exp_f32_e32 v106, v106
	v_mul_f32_e32 v102, v88, v102
	v_bfe_u32 v110, v102, 16, 1
	v_add3_u32 v102, v102, v110, s10
	v_add_f32_e32 v108, 1.0, v106
	v_rcp_f32_e32 v108, v108
	ds_write_b16_d16_hi v83, v102 offset:4176
	s_waitcnt vmcnt(0)
	v_lshlrev_b32_e32 v86, 16, v86
	v_max_f32_e32 v86, v86, v86
	v_fma_f32 v102, v80, v108, v149
	v_mul_f32_e32 v88, v88, v102
	v_max_f32_e32 v88, 0xda24260, v88
	v_rcp_f32_e32 v102, v88
	v_med3_f32 v86, v86, s9, v244
	v_mul_f32_e32 v86, 0xbfb8aa3b, v86
	v_lshl_or_b32 v69, v151, 16, v135
	v_and_b32_e32 v135, 0xffff0000, v104
	ds_write_b16_d16_hi v83, v104 offset:8784
	v_mul_f32_e32 v104, v106, v108
	v_exp_f32_e32 v86, v86
	v_mul_f32_e32 v104, v80, v104
	v_mul_f32_e32 v102, v104, v102
	v_bfe_u32 v104, v102, 16, 1
	v_lshl_or_b32 v70, v150, 16, v136
	v_add3_u32 v136, v102, v104, s10
	v_add_f32_e32 v104, 1.0, v86
	v_rcp_f32_e32 v104, v104
	v_lshlrev_b32_e32 v102, 16, v168
	v_mul_f32_e32 v102, v88, v102
	v_bfe_u32 v106, v102, 16, 1
	v_fmac_f32_e32 v149, v80, v104
	v_mul_f32_e32 v88, v88, v149
	v_add3_u32 v102, v102, v106, s10
	v_max_f32_e32 v88, 0xda24260, v88
	ds_write_b16_d16_hi v83, v102 offset:4320
	v_rcp_f32_e32 v102, v88
	v_mul_f32_e32 v86, v86, v104
	v_mul_f32_e32 v80, v80, v86
	v_and_b32_e32 v81, 0xffff0000, v64
	v_mul_f32_e32 v80, v80, v102
	v_bfe_u32 v86, v80, 16, 1
	v_add3_u32 v80, v80, v86, s10
	v_lshlrev_b32_e32 v86, 16, v167
	v_mul_f32_e32 v86, v88, v86
	v_bfe_u32 v102, v86, 16, 1
	v_add3_u32 v86, v86, v102, s10
	v_and_b32_e32 v85, 0xffff0000, v66
	v_and_b32_e32 v87, 0xffff0000, v65
	v_and_b32_e32 v105, 0xffff0000, v159
	v_and_b32_e32 v107, 0xffff0000, v163
	v_and_b32_e32 v109, 0xffff0000, v115
	v_and_b32_e32 v111, 0xffff0000, v172
	v_and_b32_e32 v113, 0xffff0000, v176
	v_and_b32_e32 v115, 0xffff0000, v175
	v_and_b32_e32 v117, 0xffff0000, v117
	v_and_b32_e32 v119, 0xffff0000, v119
	v_lshl_or_b32 v67, v142, 16, v141
	v_lshl_or_b32 v66, v143, 16, v140
	v_lshl_or_b32 v65, v145, 16, v139
	v_lshl_or_b32 v64, v146, 16, v138
	v_lshl_or_b32 v71, v147, 16, v137
	v_lshl_or_b32 v68, v152, 16, v134
	v_lshl_or_b32 v73, v154, 16, v130
	v_lshl_or_b32 v72, v155, 16, v129
	v_lshl_or_b32 v77, v118, 16, v126
	ds_write_b16_d16_hi v83, v120 offset:8064
	ds_write_b16_d16_hi v83, v122 offset:8352
	ds_write_b16_d16_hi v83, v132 offset:8640
	ds_write_b16_d16_hi v83, v136 offset:8928
	v_and_b32_e32 v137, 0xffff0000, v80
	ds_write_b16_d16_hi v83, v86 offset:4464
	ds_write_b16_d16_hi v83, v80 offset:9072
	v_and_b32_e32 v112, 0xffff0000, v170
	v_and_b32_e32 v104, 0xffff0000, v157
	v_and_b32_e32 v80, 0xffff0000, v178
	v_pk_mul_f32 v[112:113], v[88:89], v[112:113] op_sel_hi:[0,1]
	v_and_b32_e32 v108, 0xffff0000, v84
	v_pk_mul_f32 v[104:105], v[88:89], v[104:105] op_sel_hi:[0,1]
	v_and_b32_e32 v84, 0xffff0000, v182
	v_pk_mul_f32 v[80:81], v[88:89], v[80:81] op_sel_hi:[0,1]
	v_and_b32_e32 v120, 0xffff0000, v120
	v_cvt_pk_bf16_f32 v129, v112, v113
	v_cvt_pk_bf16_f32 v113, v104, v105
	v_pk_mul_f32 v[84:85], v[88:89], v[84:85] op_sel_hi:[0,1]
	v_cvt_pk_bf16_f32 v105, v80, v81
	v_pk_mul_f32 v[80:81], v[88:89], v[120:121] op_sel_hi:[0,1]
	v_and_b32_e32 v130, 0xffff0000, v122
	v_and_b32_e32 v102, 0xffff0000, v156
	v_and_b32_e32 v86, 0xffff0000, v181
	v_cvt_pk_bf16_f32 v104, v84, v85
	v_cvt_pk_bf16_f32 v84, v80, v81
	v_pk_mul_f32 v[80:81], v[88:89], v[130:131] op_sel_hi:[0,1]
	v_and_b32_e32 v134, 0xffff0000, v132
	v_and_b32_e32 v118, 0xffff0000, v133
	v_and_b32_e32 v116, 0xffff0000, v116
	v_and_b32_e32 v114, 0xffff0000, v123
	v_and_b32_e32 v110, 0xffff0000, v171
	v_and_b32_e32 v106, 0xffff0000, v158
	v_pk_mul_f32 v[102:103], v[88:89], v[102:103] op_sel_hi:[0,1]
	v_pk_mul_f32 v[86:87], v[88:89], v[86:87] op_sel_hi:[0,1]
	v_cvt_pk_bf16_f32 v85, v80, v81
	v_pk_mul_f32 v[80:81], v[88:89], v[134:135] op_sel_hi:[0,1]
	v_and_b32_e32 v136, 0xffff0000, v136
	s_movk_i32 s0, 0x50
	v_pk_mul_f32 v[118:119], v[88:89], v[118:119] op_sel_hi:[0,1]
	v_pk_mul_f32 v[116:117], v[88:89], v[116:117] op_sel_hi:[0,1]
	v_pk_mul_f32 v[114:115], v[88:89], v[114:115] op_sel_hi:[0,1]
	v_pk_mul_f32 v[110:111], v[88:89], v[110:111] op_sel_hi:[0,1]
	v_pk_mul_f32 v[108:109], v[88:89], v[108:109] op_sel_hi:[0,1]
	v_pk_mul_f32 v[106:107], v[88:89], v[106:107] op_sel_hi:[0,1]
	v_cvt_pk_bf16_f32 v102, v102, v103
	v_cvt_pk_bf16_f32 v103, v86, v87
	v_cvt_pk_bf16_f32 v86, v80, v81
	v_pk_mul_f32 v[80:81], v[88:89], v[136:137] op_sel_hi:[0,1]
	v_mad_u64_u32 v[138:139], s[2:3], v82, s0, v[92:93]
	v_cvt_pk_bf16_f32 v126, v118, v119
	v_cvt_pk_bf16_f32 v127, v116, v117
	v_cvt_pk_bf16_f32 v128, v114, v115
	v_cvt_pk_bf16_f32 v110, v110, v111
	v_cvt_pk_bf16_f32 v111, v108, v109
	v_cvt_pk_bf16_f32 v112, v106, v107
	v_cvt_pk_bf16_f32 v87, v80, v81
	v_lshl_add_u32 v80, v82, 2, v92
	ds_write_b128 v138, v[126:129] offset:9216
	ds_write_b128 v138, v[110:113] offset:9232
	ds_write_b128 v138, v[102:105] offset:9248
	ds_write_b128 v138, v[84:87] offset:9264
	ds_write_b32 v80, v88 offset:19456
	ds_write_b128 v138, v[76:79] offset:14336
	ds_write_b128 v138, v[72:75] offset:14352
	ds_write_b128 v138, v[68:71] offset:14368
	ds_write_b128 v138, v[64:67] offset:14384
	s_waitcnt lgkmcnt(0)
	v_or_b32_e32 v88, v95, v124
	v_lshlrev_b64 v[64:65], 11, v[88:89]
	v_lshl_add_u64 v[64:65], s[16:17], 0, v[64:65]
	v_lshlrev_b32_e32 v80, 2, v125
	s_movk_i32 s48, 0x90
	v_lshl_add_u64 v[64:65], v[64:65], 0, v[90:91]
	v_ashrrev_i32_e32 v81, 31, v80
	v_mad_u32_u24 v88, v124, s48, v92
	v_lshl_add_u64 v[104:105], v[80:81], 1, v[64:65]
	v_lshl_add_u32 v81, v125, 4, v88
	ds_read_b128 v[64:67], v81 offset:4608
	ds_read_b128 v[68:71], v81
	ds_read_b128 v[82:85], v81 offset:32
	ds_read_b128 v[106:109], v81 offset:4640
	s_waitcnt lgkmcnt(2)
	v_mfma_f32_32x32x16_bf16 v[64:79], v[64:67], v[68:71], 0
	v_cmp_le_i32_e32 vcc, v80, v124
	v_cvt_pk_bf16_f32 v32, v32, v33
	v_cvt_pk_bf16_f32 v33, v34, v35
	v_cvt_pk_bf16_f32 v34, v36, v37
	v_cvt_pk_bf16_f32 v35, v38, v39
	v_cvt_pk_bf16_f32 v36, v48, v49
	v_cvt_pk_bf16_f32 v37, v50, v51
	s_waitcnt lgkmcnt(0)
	v_mfma_f32_32x32x16_bf16 v[64:79], v[106:109], v[82:85], v[64:79]
	ds_read_b128 v[82:85], v81 offset:4672
	ds_read_b128 v[106:109], v81 offset:64
	v_cvt_pk_bf16_f32 v38, v52, v53
	v_cvt_pk_bf16_f32 v39, v54, v55
	s_mov_b32 s6, 0x16f00000
	s_mov_b64 s[4:5], 0x16f00600
	v_lshl_add_u64 v[102:103], v[104:105], 0, s[4:5]
	s_waitcnt lgkmcnt(0)
	v_mfma_f32_32x32x16_bf16 v[64:79], v[82:85], v[106:109], v[64:79]
	ds_read_b128 v[82:85], v81 offset:4704
	ds_read_b128 v[106:109], v81 offset:96
	v_or_b32_e32 v81, 2, v80
	s_waitcnt lgkmcnt(0)
	v_mfma_f32_32x32x16_bf16 v[64:79], v[82:85], v[106:109], v[64:79]
	s_nop 11
	v_cndmask_b32_e32 v64, 0, v64, vcc
	v_cmp_lt_i32_e32 vcc, v80, v124
	s_nop 1
	v_cndmask_b32_e32 v65, 0, v65, vcc
	v_cmp_le_i32_e32 vcc, v81, v124
	v_or_b32_e32 v81, 3, v80
	v_cvt_pk_bf16_f32 v84, v64, v65
	v_cndmask_b32_e32 v66, 0, v66, vcc
	v_cmp_le_i32_e32 vcc, v81, v124
	v_add_u32_e32 v81, 8, v80
	v_lshlrev_b32_e32 v64, 3, v125
	v_cndmask_b32_e32 v67, 0, v67, vcc
	v_cmp_le_i32_e32 vcc, v81, v124
	v_add_u32_e32 v81, 9, v80
	v_mul_u32_u24_e32 v65, 0x50, v124
	v_cndmask_b32_e32 v68, 0, v68, vcc
	v_cmp_le_i32_e32 vcc, v81, v124
	v_add_u32_e32 v81, 10, v80
	v_add3_u32 v114, v92, v64, v65
	v_cndmask_b32_e32 v69, 0, v69, vcc
	v_cmp_le_i32_e32 vcc, v81, v124
	v_add_u32_e32 v81, 11, v80
	v_cvt_pk_bf16_f32 v86, v68, v69
	v_cndmask_b32_e32 v70, 0, v70, vcc
	v_cmp_le_i32_e32 vcc, v81, v124
	v_add_u32_e32 v81, 16, v80
	v_add_u32_e32 v68, 0x3800, v114
	v_cndmask_b32_e32 v71, 0, v71, vcc
	v_cmp_le_i32_e32 vcc, v81, v124
	v_add_u32_e32 v81, 17, v80
	v_cvt_pk_bf16_f32 v85, v66, v67
	v_cndmask_b32_e32 v72, 0, v72, vcc
	v_cmp_le_i32_e32 vcc, v81, v124
	v_add_u32_e32 v81, 18, v80
	v_add_u32_e32 v88, v88, v64
	v_cndmask_b32_e32 v73, 0, v73, vcc
	v_cmp_le_i32_e32 vcc, v81, v124
	v_add_u32_e32 v81, 19, v80
	ds_read2_b64 v[64:67], v68 offset1:2
	ds_read2_b64 v[106:109], v68 offset0:4 offset1:6
	v_cndmask_b32_e32 v74, 0, v74, vcc
	v_cmp_le_i32_e32 vcc, v81, v124
	v_add_u32_e32 v81, 24, v80
	v_cvt_pk_bf16_f32 v87, v70, v71
	v_cndmask_b32_e32 v75, 0, v75, vcc
	v_cmp_le_i32_e32 vcc, v81, v124
	v_add_u32_e32 v81, 25, v80
	s_nop 0
	v_cndmask_b32_e32 v76, 0, v76, vcc
	v_cmp_le_i32_e32 vcc, v81, v124
	v_add_u32_e32 v81, 26, v80
	v_add_u32_e32 v80, 27, v80
	v_cndmask_b32_e32 v77, 0, v77, vcc
	v_cmp_le_i32_e32 vcc, v81, v124
	v_cvt_pk_bf16_f32 v81, v74, v75
	v_cvt_pk_bf16_f32 v82, v76, v77
	v_cndmask_b32_e32 v78, 0, v78, vcc
	v_cmp_le_i32_e32 vcc, v80, v124
	v_cvt_pk_bf16_f32 v80, v72, v73
	s_nop 0
	v_cndmask_b32_e32 v79, 0, v79, vcc
	v_cvt_pk_bf16_f32 v83, v78, v79
	s_waitcnt lgkmcnt(1)
	v_mfma_f32_32x32x16_bf16 v[64:79], v[64:67], v[84:87], 0
	s_waitcnt lgkmcnt(0)
	v_mfma_f32_32x32x16_bf16 v[64:79], v[106:109], v[80:83], v[64:79]
	ds_read2_b64 v[106:109], v88 offset1:2
	ds_read2_b64 v[110:113], v88 offset0:4 offset1:6
	s_waitcnt lgkmcnt(1)
	v_mfma_f32_32x32x16_bf16 v[64:79], v[32:35], v[106:109], v[64:79]
	v_cvt_pk_bf16_f32 v32, v40, v41
	v_cvt_pk_bf16_f32 v33, v42, v43
	v_cvt_pk_bf16_f32 v34, v44, v45
	v_cvt_pk_bf16_f32 v35, v46, v47
	s_waitcnt lgkmcnt(0)
	s_nop 0
	v_mfma_f32_32x32x16_bf16 v[64:79], v[32:35], v[110:113], v[64:79]
	ds_read2_b64 v[32:35], v88 offset0:8 offset1:10
	s_waitcnt lgkmcnt(0)
	v_mfma_f32_32x32x16_bf16 v[64:79], v[36:39], v[32:35], v[64:79]
	ds_read2_b64 v[32:35], v88 offset0:12 offset1:14
	v_cvt_pk_bf16_f32 v36, v56, v57
	v_cvt_pk_bf16_f32 v37, v58, v59
	v_cvt_pk_bf16_f32 v38, v60, v61
	v_cvt_pk_bf16_f32 v39, v62, v63
	s_waitcnt lgkmcnt(0)
	s_nop 0
	v_mfma_f32_32x32x16_bf16 v[64:79], v[36:39], v[32:35], v[64:79]
	v_add_co_u32_e32 v34, vcc, s6, v104
	s_nop 1
	v_addc_co_u32_e32 v35, vcc, 0, v105, vcc
	s_nop 7
	v_cvt_pk_bf16_f32 v32, v64, v65
	v_cvt_pk_bf16_f32 v33, v66, v67
	global_store_dwordx2 v[34:35], v[32:33], off offset:1536
	v_cvt_pk_bf16_f32 v32, v68, v69
	v_cvt_pk_bf16_f32 v33, v70, v71
	global_store_dwordx2 v[102:103], v[32:33], off offset:16
	v_cvt_pk_bf16_f32 v32, v72, v73
	v_cvt_pk_bf16_f32 v33, v74, v75
	global_store_dwordx2 v[102:103], v[32:33], off offset:32
	v_cvt_pk_bf16_f32 v32, v76, v77
	v_cvt_pk_bf16_f32 v33, v78, v79
	global_store_dwordx2 v[102:103], v[32:33], off offset:48
	v_add_u32_e32 v48, 0x4000, v114
	ds_read2_b64 v[32:35], v48 offset0:64 offset1:66
	ds_read2_b64 v[48:51], v48 offset0:68 offset1:70
	ds_read2_b64 v[52:55], v88 offset1:2
	v_cvt_pk_bf16_f32 v0, v0, v1
	v_cvt_pk_bf16_f32 v1, v2, v3
	v_cvt_pk_bf16_f32 v2, v4, v5
	v_cvt_pk_bf16_f32 v3, v6, v7
	ds_read2_b64 v[4:7], v88 offset0:4 offset1:6
	v_cvt_pk_bf16_f32 v8, v8, v9
	v_cvt_pk_bf16_f32 v9, v10, v11
	s_waitcnt lgkmcnt(3)
	v_mfma_f32_32x32x16_bf16 v[32:47], v[32:35], v[84:87], 0
	v_cvt_pk_bf16_f32 v10, v12, v13
	v_cvt_pk_bf16_f32 v11, v14, v15
	v_cvt_pk_bf16_f32 v12, v16, v17
	v_cvt_pk_bf16_f32 v13, v18, v19
	v_cvt_pk_bf16_f32 v14, v20, v21
	v_cvt_pk_bf16_f32 v15, v22, v23
	s_waitcnt lgkmcnt(2)
	v_mfma_f32_32x32x16_bf16 v[32:47], v[48:51], v[80:83], v[32:47]
	s_waitcnt lgkmcnt(1)
	v_mfma_f32_32x32x16_bf16 v[32:47], v[0:3], v[52:55], v[32:47]
	ds_read2_b64 v[0:3], v88 offset0:8 offset1:10
	s_waitcnt lgkmcnt(1)
	v_mfma_f32_32x32x16_bf16 v[32:47], v[8:11], v[4:7], v[32:47]
	ds_read2_b64 v[4:7], v88 offset0:12 offset1:14
	v_cvt_pk_bf16_f32 v8, v24, v25
	v_cvt_pk_bf16_f32 v9, v26, v27
	v_cvt_pk_bf16_f32 v10, v28, v29
	v_cvt_pk_bf16_f32 v11, v30, v31
	s_waitcnt lgkmcnt(1)
	v_mfma_f32_32x32x16_bf16 v[32:47], v[12:15], v[0:3], v[32:47]
	s_waitcnt lgkmcnt(0)
	v_mfma_f32_32x32x16_bf16 v[32:47], v[8:11], v[4:7], v[32:47]
	s_nop 11
	v_cvt_pk_bf16_f32 v0, v32, v33
	v_cvt_pk_bf16_f32 v1, v34, v35
	v_cvt_pk_bf16_f32 v2, v36, v37
	v_cvt_pk_bf16_f32 v3, v38, v39
	v_cvt_pk_bf16_f32 v4, v40, v41
	v_cvt_pk_bf16_f32 v5, v42, v43
	v_cvt_pk_bf16_f32 v6, v44, v45
	v_cvt_pk_bf16_f32 v7, v46, v47
	global_store_dwordx2 v[102:103], v[0:1], off offset:64
	global_store_dwordx2 v[102:103], v[2:3], off offset:80
	global_store_dwordx2 v[102:103], v[4:5], off offset:96
	global_store_dwordx2 v[102:103], v[6:7], off offset:112
	s_waitcnt lgkmcnt(0)
	v_lshl_add_u64 v[0:1], s[44:45], 0, v[160:161]
	v_add_co_u32_e32 v2, vcc, s20, v0
	s_movk_i32 s11, 0x3000
	s_nop 0
	v_addc_co_u32_e32 v3, vcc, 0, v1, vcc
	v_add_co_u32_e32 v4, vcc, s11, v0
	s_movk_i32 s7, 0x4000
	s_nop 0
	v_addc_co_u32_e32 v5, vcc, 0, v1, vcc
	v_add_co_u32_e32 v0, vcc, s7, v0
	v_readlane_b32 s0, v255, 22
	s_nop 0
	v_addc_co_u32_e32 v1, vcc, 0, v1, vcc
	global_load_dword v24, v[2:3], off offset:3072
	global_load_dword v25, v[4:5], off offset:1024
	global_load_dword v26, v[4:5], off offset:3072
	global_load_dword v27, v[0:1], off offset:1024
	v_or_b32_e32 v0, 1, v148
	v_mad_i64_i32 v[0:1], s[2:3], v0, 36, v[96:97]
	v_lshlrev_b64 v[0:1], 13, v[0:1]
	v_readlane_b32 s1, v255, 23
	v_readlane_b32 s2, v255, 1
	v_readlane_b32 s3, v255, 2
	v_lshl_add_u64 v[0:1], s[0:1], 0, v[0:1]
	v_lshl_add_u64 v[0:1], v[0:1], 0, v[98:99]
	v_lshl_add_u64 v[0:1], v[0:1], 0, v[100:101]
	global_load_dwordx2 v[2:3], v[0:1], off
	global_load_dwordx2 v[4:5], v[0:1], off offset:16
	global_load_dwordx2 v[6:7], v[0:1], off offset:32
	global_load_dwordx2 v[8:9], v[0:1], off offset:48
	s_movk_i32 s0, 0x1000
	v_add_co_u32_e32 v10, vcc, s0, v0
	s_mov_b32 s1, 0xf149f2ca
	s_nop 0
	v_addc_co_u32_e32 v11, vcc, 0, v1, vcc
	global_load_dwordx2 v[12:13], v[10:11], off
	global_load_dwordx2 v[14:15], v[10:11], off offset:16
	global_load_dwordx2 v[16:17], v[10:11], off offset:32
	global_load_dwordx2 v[18:19], v[10:11], off offset:48
	global_load_dwordx2 v[20:21], v[0:1], off offset:64
	global_load_dwordx2 v[22:23], v[0:1], off offset:80
	global_load_dwordx2 v[58:59], v[0:1], off offset:96
	s_nop 0
	global_load_dwordx2 v[0:1], v[0:1], off offset:112
	s_nop 0
	global_load_dwordx2 v[64:65], v[10:11], off offset:64
	global_load_dwordx2 v[72:73], v[10:11], off offset:80
	global_load_dwordx2 v[76:77], v[10:11], off offset:96
	s_nop 0
	global_load_dwordx2 v[10:11], v[10:11], off offset:112
	s_mov_b64 s[40:41], s[44:45]
	s_mov_b64 s[12:13], s[44:45]
	s_waitcnt vmcnt(18)
	v_max3_f32 v28, v24, s1, v25
	s_waitcnt vmcnt(16)
	v_max3_f32 v28, v28, v26, v27
	v_sub_f32_e32 v25, v25, v28
	v_mul_f32_e32 v25, 0x3fb8aa3b, v25
	v_sub_f32_e32 v24, v24, v28
	v_sub_f32_e32 v26, v26, v28
	v_exp_f32_e32 v25, v25
	v_mul_f32_e32 v24, 0x3fb8aa3b, v24
	v_mul_f32_e32 v26, 0x3fb8aa3b, v26
	v_sub_f32_e32 v27, v27, v28
	v_exp_f32_e32 v50, v24
	v_exp_f32_e32 v51, v26
	v_mul_f32_e32 v27, 0x3fb8aa3b, v27
	v_exp_f32_e32 v52, v27
	s_waitcnt vmcnt(15)
	v_lshlrev_b32_e32 v32, 16, v2
	v_and_b32_e32 v33, 0xffff0000, v2
	v_add_f32_e32 v2, 0, v25
	v_cndmask_b32_e64 v2, v2, 0, s[2:3]
	v_readlane_b32 s2, v255, 3
	v_lshlrev_b32_e32 v34, 16, v3
	v_and_b32_e32 v35, 0xffff0000, v3
	s_waitcnt vmcnt(14)
	v_lshlrev_b32_e32 v36, 16, v4
	v_and_b32_e32 v37, 0xffff0000, v4
	v_add_f32_e32 v3, 0, v50
	v_add_f32_e32 v4, v51, v2
	v_readlane_b32 s3, v255, 4
	v_add_f32_e32 v3, v25, v3
	v_add_f32_e32 v3, v51, v3
	v_cndmask_b32_e64 v2, v4, v2, s[2:3]
	v_readlane_b32 s2, v255, 5
	v_add_f32_e32 v4, v52, v2
	v_readlane_b32 s3, v255, 6
	v_add_f32_e32 v3, v52, v3
	v_lshlrev_b32_e32 v38, 16, v5
	v_cndmask_b32_e64 v2, v4, v2, s[2:3]
	v_div_scale_f32 v4, s[2:3], v3, v3, v2
	v_and_b32_e32 v39, 0xffff0000, v5
	v_rcp_f32_e32 v5, v4
	s_waitcnt vmcnt(13)
	v_lshlrev_b32_e32 v42, 16, v7
	v_and_b32_e32 v43, 0xffff0000, v7
	v_lshlrev_b32_e32 v40, 16, v6
	v_fma_f32 v7, -v4, v5, 1.0
	v_and_b32_e32 v41, 0xffff0000, v6
	v_div_scale_f32 v6, vcc, v2, v3, v2
	v_fmac_f32_e32 v5, v7, v5
	v_mul_f32_e32 v7, v6, v5
	s_waitcnt vmcnt(12)
	v_lshlrev_b32_e32 v44, 16, v8
	v_and_b32_e32 v45, 0xffff0000, v8
	v_fma_f32 v8, -v4, v7, v6
	v_fmac_f32_e32 v7, v8, v5
	v_fma_f32 v4, -v4, v7, v6
	s_waitcnt vmcnt(9)
	v_lshlrev_b32_e32 v24, 16, v16
	v_and_b32_e32 v25, 0xffff0000, v16
	v_div_fmas_f32 v4, v4, v5, v7
	v_mov_b32_e32 v16, v94
	v_div_fixup_f32 v116, v4, v3, v2
	s_add_u32 s2, s40, 0xb200000
	v_lshlrev_b32_e32 v46, 16, v9
	v_and_b32_e32 v47, 0xffff0000, v9
	v_lshlrev_b32_e32 v26, 16, v12
	v_and_b32_e32 v27, 0xffff0000, v12
	v_lshlrev_b32_e32 v28, 16, v13
	v_and_b32_e32 v29, 0xffff0000, v13
	v_lshlrev_b32_e32 v30, 16, v14
	v_and_b32_e32 v31, 0xffff0000, v14
	v_lshlrev_b32_e32 v48, 16, v15
	v_and_b32_e32 v49, 0xffff0000, v15
	v_lshlrev_b32_e32 v84, 16, v17
	v_and_b32_e32 v85, 0xffff0000, v17
	s_waitcnt vmcnt(8)
	v_lshlrev_b32_e32 v86, 16, v18
	v_and_b32_e32 v87, 0xffff0000, v18
	v_lshlrev_b32_e32 v96, 16, v19
	v_and_b32_e32 v97, 0xffff0000, v19
	s_waitcnt vmcnt(7)
	v_lshlrev_b32_e32 v54, 16, v20
	v_and_b32_e32 v55, 0xffff0000, v20
	v_lshlrev_b32_e32 v50, 16, v21
	v_and_b32_e32 v51, 0xffff0000, v21
	s_waitcnt vmcnt(6)
	v_lshlrev_b32_e32 v52, 16, v22
	v_and_b32_e32 v53, 0xffff0000, v22
	v_lshlrev_b32_e32 v82, 16, v23
	v_and_b32_e32 v83, 0xffff0000, v23
	s_waitcnt vmcnt(5)
	v_lshlrev_b32_e32 v56, 16, v58
	v_and_b32_e32 v57, 0xffff0000, v58
	v_lshlrev_b32_e32 v58, 16, v59
	v_and_b32_e32 v59, 0xffff0000, v59
	s_waitcnt vmcnt(4)
	v_lshlrev_b32_e32 v60, 16, v0
	v_and_b32_e32 v61, 0xffff0000, v0
	v_lshlrev_b32_e32 v62, 16, v1
	v_and_b32_e32 v63, 0xffff0000, v1
	s_waitcnt vmcnt(3)
	v_lshlrev_b32_e32 v66, 16, v64
	v_and_b32_e32 v67, 0xffff0000, v64
	v_lshlrev_b32_e32 v68, 16, v65
	v_and_b32_e32 v69, 0xffff0000, v65
	s_waitcnt vmcnt(2)
	v_lshlrev_b32_e32 v70, 16, v72
	v_and_b32_e32 v71, 0xffff0000, v72
	v_lshlrev_b32_e32 v72, 16, v73
	v_and_b32_e32 v73, 0xffff0000, v73
	s_waitcnt vmcnt(1)
	v_lshlrev_b32_e32 v74, 16, v76
	v_and_b32_e32 v75, 0xffff0000, v76
	v_lshlrev_b32_e32 v76, 16, v77
	v_and_b32_e32 v77, 0xffff0000, v77
	s_waitcnt vmcnt(0)
	v_lshlrev_b32_e32 v78, 16, v10
	v_and_b32_e32 v79, 0xffff0000, v10
	v_lshlrev_b32_e32 v80, 16, v11
	v_and_b32_e32 v81, 0xffff0000, v11
	v_sub_f32_e32 v117, 1.0, v116
	v_and_b32_e32 v118, 31, v16
	v_ashrrev_i32_e32 v119, 5, v16
	s_addc_u32 s3, s41, 0
	v_mov_b64_e32 v[64:65], s[2:3]
	s_movk_i32 s1, 0x1200
	v_mad_i64_i32 v[0:1], s[2:3], v95, s1, v[64:65]
	v_ashrrev_i32_e32 v17, 31, v16
	v_lshl_add_u64 v[0:1], v[0:1], 0, v[90:91]
	v_lshl_add_u64 v[0:1], v[16:17], 1, v[0:1]
	s_mov_b32 s37, 0x23000
	v_add_co_u32_e32 v12, vcc, s37, v0
	s_movk_i32 s2, 0x5000
	s_nop 0
	v_addc_co_u32_e32 v13, vcc, 0, v1, vcc
	global_load_ushort v88, v[12:13], off offset:3072
	global_load_ushort v109, v[12:13], off offset:1536
	v_add_co_u32_e32 v2, vcc, s20, v0
	s_mov_b32 s28, 0x9000
	s_nop 0
	v_addc_co_u32_e32 v3, vcc, 0, v1, vcc
	v_add_co_u32_e32 v4, vcc, s2, v0
	s_movk_i32 s2, 0x7000
	s_nop 0
	v_addc_co_u32_e32 v5, vcc, 0, v1, vcc
	v_add_co_u32_e32 v6, vcc, s2, v0
	s_mov_b32 s29, 0xb000
	s_nop 0
	v_addc_co_u32_e32 v7, vcc, 0, v1, vcc
	v_add_co_u32_e32 v18, vcc, s28, v0
	s_mov_b32 s18, 0xe000
	s_nop 0
	v_addc_co_u32_e32 v19, vcc, 0, v1, vcc
	v_add_co_u32_e32 v20, vcc, s29, v0
	s_mov_b32 s2, 0x10000
	s_nop 0
	v_addc_co_u32_e32 v21, vcc, 0, v1, vcc
	v_add_co_u32_e32 v22, vcc, s18, v0
	s_mov_b32 s30, 0x17000
	s_nop 0
	v_addc_co_u32_e32 v23, vcc, 0, v1, vcc
	v_add_co_u32_e32 v98, vcc, s2, v0
	s_mov_b32 s2, 0x14000
	s_nop 0
	v_addc_co_u32_e32 v99, vcc, 0, v1, vcc
	v_add_co_u32_e32 v8, vcc, s51, v0
	s_mov_b32 s31, 0x19000
	s_nop 0
	v_addc_co_u32_e32 v9, vcc, 0, v1, vcc
	v_add_co_u32_e32 v10, vcc, s2, v0
	s_mov_b32 s34, 0x1b000
	s_nop 0
	v_addc_co_u32_e32 v11, vcc, 0, v1, vcc
	v_add_co_u32_e32 v14, vcc, s30, v0
	s_mov_b32 s35, 0x1d000
	s_nop 0
	v_addc_co_u32_e32 v15, vcc, 0, v1, vcc
	v_add_co_u32_e32 v100, vcc, s31, v0
	s_mov_b32 s19, 0x20000
	s_nop 0
	v_addc_co_u32_e32 v101, vcc, 0, v1, vcc
	v_add_co_u32_e32 v102, vcc, s34, v0
	s_mov_b32 s36, 0x22000
	s_nop 0
	v_addc_co_u32_e32 v103, vcc, 0, v1, vcc
	v_add_co_u32_e32 v104, vcc, s35, v0
	s_mov_b32 s21, 0x21000
	s_nop 0
	v_addc_co_u32_e32 v105, vcc, 0, v1, vcc
	v_add_co_u32_e32 v106, vcc, s19, v0
	s_mov_b32 s42, 0x1f000
	s_nop 0
	v_addc_co_u32_e32 v107, vcc, 0, v1, vcc
	v_add_co_u32_e32 v120, vcc, s36, v0
	s_mov_b32 s17, 0x1e000
	s_nop 0
	v_addc_co_u32_e32 v121, vcc, 0, v1, vcc
	v_add_co_u32_e32 v110, vcc, s21, v0
	s_mov_b32 s16, 0x1c000
	s_nop 0
	v_addc_co_u32_e32 v111, vcc, 0, v1, vcc
	global_load_ushort v113, v[110:111], off offset:512
	global_load_ushort v108, v[110:111], off offset:1024
	global_load_ushort v122, v[110:111], off offset:2048
	s_nop 0
	global_load_ushort v110, v[12:13], off offset:2048
	global_load_ushort v112, v[120:121], off offset:1536
	global_load_ushort v145, v[120:121], off offset:2560
	global_load_ushort v123, v[104:105], off offset:3584
	global_load_ushort v124, v[106:107], off offset:512
	global_load_ushort v154, v[120:121], off offset:1024
	global_load_ushort v155, v[106:107], off offset:1536
	global_load_ushort v156, v[106:107], off
	global_load_ushort v159, v[104:105], off offset:3072
	global_load_ushort v162, v[104:105], off
	global_load_ushort v166, v[102:103], off offset:3584
	s_waitcnt vmcnt(15)
	v_lshlrev_b32_e32 v12, 16, v88
	v_max_f32_e32 v12, v12, v12
	v_med3_f32 v12, v12, s9, v244
	v_mul_f32_e32 v12, 0xbfb8aa3b, v12
	v_exp_f32_e32 v88, v12
	v_add_co_u32_e32 v12, vcc, s42, v0
	s_mov_b32 s2, 0x1a000
	v_add_f32_e32 v111, 1.0, v88
	v_addc_co_u32_e32 v13, vcc, 0, v1, vcc
	v_rcp_f32_e32 v111, v111
	v_add_co_u32_e32 v136, vcc, s17, v0
	s_waitcnt vmcnt(14)
	v_lshlrev_b32_e32 v109, 16, v109
	v_addc_co_u32_e32 v137, vcc, 0, v1, vcc
	v_add_co_u32_e32 v134, vcc, s16, v0
	v_fma_f32 v114, v117, v111, v116
	s_nop 0
	v_addc_co_u32_e32 v135, vcc, 0, v1, vcc
	v_max_f32_e32 v152, 0xda24260, v114
	v_add_co_u32_e32 v120, vcc, s2, v0
	v_mul_f32_e32 v88, v88, v111
	v_rcp_f32_e32 v111, v152
	v_addc_co_u32_e32 v121, vcc, 0, v1, vcc
	s_mov_b32 s2, 0x18000
	v_add_co_u32_e32 v138, vcc, s2, v0
	s_mov_b32 s2, 0x16000
	s_nop 0
	v_addc_co_u32_e32 v139, vcc, 0, v1, vcc
	v_mul_f32_e32 v88, v117, v88
	v_mul_f32_e32 v109, v152, v109
	global_load_ushort v125, v[14:15], off offset:512
	global_load_ushort v127, v[100:101], off offset:1536
	global_load_ushort v128, v[102:103], off offset:2560
	global_load_ushort v167, v[102:103], off offset:2048
	global_load_ushort v169, v[100:101], off offset:2560
	global_load_ushort v172, v[100:101], off offset:1024
	global_load_ushort v168, v[14:15], off offset:1536
	global_load_ushort v164, v[14:15], off
	v_add_co_u32_e32 v14, vcc, s2, v0
	v_bfe_u32 v114, v109, 16, 1
	v_mul_f32_e32 v88, v88, v111
	v_addc_co_u32_e32 v15, vcc, 0, v1, vcc
	s_mov_b32 s43, 0x15000
	v_add3_u32 v153, v109, v114, s10
	v_bfe_u32 v109, v88, 16, 1
	v_add_co_u32_e32 v140, vcc, s43, v0
	v_add3_u32 v114, v88, v109, s10
	s_nop 0
	v_addc_co_u32_e32 v141, vcc, 0, v1, vcc
	global_load_ushort v126, v[22:23], off offset:512
	global_load_ushort v129, v[98:99], off offset:1536
	global_load_ushort v130, v[8:9], off offset:2560
	global_load_ushort v131, v[10:11], off offset:3584
	global_load_ushort v158, v[10:11], off offset:3072
	global_load_ushort v115, v[10:11], off
	global_load_ushort v111, v[8:9], off offset:3584
	global_load_ushort v109, v[8:9], off offset:2048
	global_load_ushort v173, v[12:13], off offset:1024
	global_load_ushort v174, v[136:137], off offset:3584
	global_load_ushort v175, v[134:135], off offset:2560
	global_load_ushort v176, v[120:121], off offset:1536
	global_load_ushort v133, v[120:121], off offset:2048
	s_nop 0
	global_load_ushort v134, v[134:135], off offset:3072
	s_nop 0
	global_load_ushort v177, v[136:137], off offset:512
	global_load_ushort v135, v[12:13], off
	global_load_ushort v178, v[120:121], off offset:3072
	global_load_ushort v171, v[138:139], off offset:2048
	global_load_ushort v170, v[138:139], off offset:512
	global_load_ushort v165, v[14:15], off offset:1024
	global_load_ushort v163, v[140:141], off offset:3584
	global_load_ushort v160, v[140:141], off offset:512
	global_load_ushort v137, v[14:15], off
	s_nop 0
	global_load_ushort v139, v[138:139], off offset:1024
	s_mov_b32 s44, 0x13000
	v_add_co_u32_e32 v146, vcc, s44, v0
	s_mov_b32 s45, 0x11000
	s_nop 0
	v_addc_co_u32_e32 v147, vcc, 0, v1, vcc
	v_add_co_u32_e32 v106, vcc, s45, v0
	s_mov_b32 s46, 0xf000
	s_nop 0
	v_addc_co_u32_e32 v107, vcc, 0, v1, vcc
	v_add_co_u32_e32 v102, vcc, s46, v0
	s_mov_b32 s47, 0xd000
	s_nop 0
	v_addc_co_u32_e32 v103, vcc, 0, v1, vcc
	v_add_co_u32_e32 v104, vcc, s47, v0
	s_mov_b32 s15, 0xa000
	s_nop 0
	v_addc_co_u32_e32 v105, vcc, 0, v1, vcc
	v_add_co_u32_e32 v100, vcc, s15, v0
	s_mov_b32 s14, 0x8000
	s_waitcnt vmcnt(40)
	v_lshlrev_b32_e32 v8, 16, v145
	v_max_f32_e32 v8, v8, v8
	v_med3_f32 v8, v8, s9, v244
	v_mul_f32_e32 v8, 0xbfb8aa3b, v8
	v_exp_f32_e32 v88, v8
	v_addc_co_u32_e32 v101, vcc, 0, v1, vcc
	v_lshlrev_b32_e32 v122, 16, v122
	v_add_f32_e32 v120, 1.0, v88
	v_rcp_f32_e32 v120, v120
	v_add_co_u32_e32 v10, vcc, s14, v0
	v_max_f32_e32 v122, v122, v122
	v_fma_f32 v121, v117, v120, v116
	v_mul_f32_e32 v121, v152, v121
	v_addc_co_u32_e32 v11, vcc, 0, v1, vcc
	v_max_f32_e32 v121, 0xda24260, v121
	v_med3_f32 v122, v122, s9, v244
	v_add_co_u32_e32 v12, vcc, s27, v0
	v_rcp_f32_e32 v152, v121
	v_mul_f32_e32 v122, 0xbfb8aa3b, v122
	v_addc_co_u32_e32 v13, vcc, 0, v1, vcc
	v_exp_f32_e32 v122, v122
	v_add_co_u32_e32 v14, vcc, s7, v0
	v_mul_f32_e32 v88, v88, v120
	s_nop 0
	v_addc_co_u32_e32 v15, vcc, 0, v1, vcc
	v_mul_f32_e32 v88, v117, v88
	v_add_co_u32_e32 v8, vcc, s0, v0
	v_mul_f32_e32 v88, v88, v152
	global_load_ushort v132, v[0:1], off offset:2560
	global_load_ushort v136, v[2:3], off offset:3584
	global_load_ushort v138, v[4:5], off offset:512
	global_load_ushort v140, v[6:7], off offset:1536
	global_load_ushort v141, v[18:19], off offset:2560
	global_load_ushort v143, v[20:21], off offset:3584
	global_load_ushort v144, v[22:23], off offset:-4096
	global_load_ushort v142, v[4:5], off offset:-4096
	v_addc_co_u32_e32 v9, vcc, 0, v1, vcc
	global_load_ushort v157, v[146:147], off offset:2560
	global_load_ushort v150, v[146:147], off offset:3072
	global_load_ushort v151, v[106:107], off offset:2048
	global_load_ushort v149, v[102:103], off offset:1024
	global_load_ushort v148, v[100:101], off offset:3072
	s_nop 0
	global_load_ushort v146, v[10:11], off offset:2048
	global_load_ushort v147, v[12:13], off offset:1024
	global_load_ushort v145, v[8:9], off offset:3072
	v_bfe_u32 v120, v88, 16, 1
	v_add_f32_e32 v152, 1.0, v122
	v_add3_u32 v88, v88, v120, s10
	s_waitcnt vmcnt(53)
	v_lshlrev_b32_e32 v120, 16, v154
	v_rcp_f32_e32 v152, v152
	v_lshl_add_u32 v17, v16, 1, v92
	v_mul_f32_e32 v120, v121, v120
	ds_write_b16_d16_hi v17, v153 offset:4464
	v_bfe_u32 v153, v120, 16, 1
	v_add3_u32 v120, v120, v153, s10
	ds_write_b16_d16_hi v17, v120 offset:4320
	v_fma_f32 v120, v117, v152, v116
	v_mul_f32_e32 v120, v121, v120
	v_mul_f32_e32 v122, v122, v152
	s_waitcnt vmcnt(52)
	v_lshlrev_b32_e32 v152, 16, v155
	v_max_f32_e32 v120, 0xda24260, v120
	v_max_f32_e32 v152, v152, v152
	v_rcp_f32_e32 v121, v120
	v_med3_f32 v152, v152, s9, v244
	v_mul_f32_e32 v152, 0xbfb8aa3b, v152
	v_exp_f32_e32 v152, v152
	v_mul_f32_e32 v122, v117, v122
	v_mul_f32_e32 v121, v122, v121
	v_bfe_u32 v122, v121, 16, 1
	v_add3_u32 v153, v121, v122, s10
	v_add_f32_e32 v121, 1.0, v152
	v_lshlrev_b32_e32 v113, 16, v113
	v_rcp_f32_e32 v121, v121
	v_mul_f32_e32 v113, v120, v113
	v_bfe_u32 v122, v113, 16, 1
	v_add3_u32 v113, v113, v122, s10
	ds_write_b16_d16_hi v17, v113 offset:4176
	v_fma_f32 v113, v117, v121, v116
	s_waitcnt vmcnt(31)
	v_lshlrev_b32_e32 v122, 16, v173
	v_mul_f32_e32 v113, v120, v113
	v_max_f32_e32 v122, v122, v122
	v_max_f32_e32 v113, 0xda24260, v113
	v_med3_f32 v122, v122, s9, v244
	v_rcp_f32_e32 v120, v113
	v_mul_f32_e32 v122, 0xbfb8aa3b, v122
	v_exp_f32_e32 v122, v122
	v_mul_f32_e32 v121, v152, v121
	v_mul_f32_e32 v121, v117, v121
	v_mul_f32_e32 v120, v121, v120
	v_bfe_u32 v121, v120, 16, 1
	v_add_f32_e32 v152, 1.0, v122
	v_add3_u32 v120, v120, v121, s10
	v_lshlrev_b32_e32 v121, 16, v156
	v_rcp_f32_e32 v152, v152
	v_mul_f32_e32 v121, v113, v121
	v_bfe_u32 v154, v121, 16, 1
	v_add3_u32 v121, v121, v154, s10
	ds_write_b16_d16_hi v17, v121 offset:4032
	v_fma_f32 v121, v117, v152, v116
	v_mul_f32_e32 v113, v113, v121
	v_mul_f32_e32 v122, v122, v152
	s_waitcnt vmcnt(25)
	v_lshlrev_b32_e32 v152, 16, v177
	v_max_f32_e32 v113, 0xda24260, v113
	v_max_f32_e32 v152, v152, v152
	v_rcp_f32_e32 v121, v113
	v_med3_f32 v152, v152, s9, v244
	v_mul_f32_e32 v152, 0xbfb8aa3b, v152
	v_exp_f32_e32 v152, v152
	v_mul_f32_e32 v122, v117, v122
	v_mul_f32_e32 v121, v122, v121
	v_bfe_u32 v122, v121, 16, 1
	v_add3_u32 v154, v121, v122, s10
	v_add_f32_e32 v122, 1.0, v152
	v_lshlrev_b32_e32 v121, 16, v174
	v_rcp_f32_e32 v122, v122
	v_mul_f32_e32 v121, v113, v121
	v_bfe_u32 v155, v121, 16, 1
	v_add3_u32 v121, v121, v155, s10
	ds_write_b16_d16_hi v17, v121 offset:3888
	v_fma_f32 v121, v117, v122, v116
	v_mul_f32_e32 v122, v152, v122
	v_lshlrev_b32_e32 v152, 16, v162
	v_mul_f32_e32 v113, v113, v121
	v_max_f32_e32 v152, v152, v152
	v_max_f32_e32 v113, 0xda24260, v113
	v_med3_f32 v152, v152, s9, v244
	v_rcp_f32_e32 v121, v113
	v_mul_f32_e32 v152, 0xbfb8aa3b, v152
	v_exp_f32_e32 v152, v152
	v_mul_f32_e32 v122, v117, v122
	v_mul_f32_e32 v121, v122, v121
	v_bfe_u32 v122, v121, 16, 1
	v_add_f32_e32 v155, 1.0, v152
	v_add3_u32 v121, v121, v122, s10
	v_lshlrev_b32_e32 v122, 16, v159
	v_rcp_f32_e32 v155, v155
	v_mul_f32_e32 v122, v113, v122
	v_bfe_u32 v156, v122, 16, 1
	v_add3_u32 v122, v122, v156, s10
	ds_write_b16_d16_hi v17, v122 offset:3744
	v_fma_f32 v122, v117, v155, v116
	v_mul_f32_e32 v113, v113, v122
	v_mul_f32_e32 v152, v152, v155
	v_lshlrev_b32_e32 v155, 16, v166
	v_max_f32_e32 v113, 0xda24260, v113
	v_max_f32_e32 v155, v155, v155
	v_rcp_f32_e32 v122, v113
	v_med3_f32 v155, v155, s9, v244
	v_mul_f32_e32 v155, 0xbfb8aa3b, v155
	v_exp_f32_e32 v156, v155
	v_mul_f32_e32 v152, v117, v152
	v_mul_f32_e32 v122, v152, v122
	v_bfe_u32 v152, v122, 16, 1
	v_add3_u32 v155, v122, v152, s10
	v_add_f32_e32 v152, 1.0, v156
	v_lshlrev_b32_e32 v122, 16, v175
	v_rcp_f32_e32 v152, v152
	v_mul_f32_e32 v122, v113, v122
	v_bfe_u32 v159, v122, 16, 1
	v_add3_u32 v122, v122, v159, s10
	ds_write_b16_d16_hi v17, v122 offset:3600
	v_fma_f32 v122, v117, v152, v116
	v_mul_f32_e32 v113, v113, v122
	v_max_f32_e32 v113, 0xda24260, v113
	v_rcp_f32_e32 v122, v113
	v_mul_f32_e32 v152, v156, v152
	v_mul_f32_e32 v152, v117, v152
	ds_write_b16_d16_hi v17, v114 offset:9072
	v_mul_f32_e32 v122, v152, v122
	v_bfe_u32 v152, v122, 16, 1
	v_add3_u32 v122, v122, v152, s10
	v_lshlrev_b32_e32 v152, 16, v167
	v_mul_f32_e32 v152, v113, v152
	v_bfe_u32 v156, v152, 16, 1
	v_add3_u32 v152, v152, v156, s10
	ds_write_b16_d16_hi v17, v88 offset:8928
	ds_write_b16_d16_hi v17, v153 offset:8784
	ds_write_b16_d16_hi v17, v120 offset:8640
	ds_write_b16_d16_hi v17, v154 offset:8496
	ds_write_b16_d16_hi v17, v121 offset:8352
	ds_write_b16_d16_hi v17, v155 offset:8208
	ds_write_b16_d16_hi v17, v152 offset:3456
	ds_write_b16_d16_hi v17, v122 offset:8064
	s_waitcnt vmcnt(23)
	v_lshlrev_b32_e32 v152, 16, v178
	v_max_f32_e32 v152, v152, v152
	v_med3_f32 v152, v152, s9, v244
	v_mul_f32_e32 v152, 0xbfb8aa3b, v152
	v_exp_f32_e32 v152, v152
	v_lshlrev_b32_e32 v109, 16, v109
	v_add_f32_e32 v156, 1.0, v152
	v_rcp_f32_e32 v156, v156
	s_nop 0
	v_fma_f32 v159, v117, v156, v116
	v_mul_f32_e32 v113, v113, v159
	v_max_f32_e32 v113, 0xda24260, v113
	v_mul_f32_e32 v152, v152, v156
	v_rcp_f32_e32 v156, v113
	v_mul_f32_e32 v152, v117, v152
	v_mul_f32_e32 v152, v152, v156
	v_bfe_u32 v156, v152, 16, 1
	v_add3_u32 v156, v152, v156, s10
	v_lshlrev_b32_e32 v152, 16, v176
	v_mul_f32_e32 v152, v113, v152
	v_bfe_u32 v159, v152, 16, 1
	v_add3_u32 v152, v152, v159, s10
	ds_write_b16_d16_hi v17, v152 offset:3312
	ds_write_b16_d16_hi v17, v156 offset:7920
	v_lshlrev_b32_e32 v152, 16, v169
	v_max_f32_e32 v152, v152, v152
	v_med3_f32 v152, v152, s9, v244
	v_mul_f32_e32 v152, 0xbfb8aa3b, v152
	v_exp_f32_e32 v152, v152
	s_nop 0
	v_add_f32_e32 v159, 1.0, v152
	v_rcp_f32_e32 v159, v159
	s_nop 0
	v_fma_f32 v162, v117, v159, v116
	v_mul_f32_e32 v113, v113, v162
	v_max_f32_e32 v173, 0xda24260, v113
	v_rcp_f32_e32 v113, v173
	v_mul_f32_e32 v152, v152, v159
	v_mul_f32_e32 v152, v117, v152
	v_mul_f32_e32 v113, v152, v113
	v_bfe_u32 v152, v113, 16, 1
	v_add3_u32 v152, v113, v152, s10
	v_lshlrev_b32_e32 v113, 16, v172
	v_mul_f32_e32 v113, v173, v113
	v_bfe_u32 v159, v113, 16, 1
	v_add3_u32 v172, v113, v159, s10
	global_load_ushort v169, v[106:107], off offset:3072
	global_load_ushort v167, v[106:107], off offset:1536
	global_load_ushort v166, v[98:99], off offset:2560
	global_load_ushort v162, v[98:99], off offset:1024
	global_load_ushort v159, v[102:103], off offset:2048
	global_load_ushort v113, v[102:103], off offset:512
	s_nop 0
	global_load_ushort v107, v[22:23], off offset:1536
	global_load_ushort v106, v[22:23], off
	s_nop 0
	global_load_ushort v104, v[104:105], off offset:1024
	v_add_co_u32_e32 v22, vcc, s50, v0
	s_nop 1
	v_addc_co_u32_e32 v23, vcc, 0, v1, vcc
	global_load_ushort v103, v[22:23], off offset:3584
	global_load_ushort v102, v[22:23], off offset:512
	global_load_ushort v99, v[20:21], off offset:3072
	global_load_ushort v98, v[20:21], off
	s_nop 0
	global_load_ushort v21, v[100:101], off offset:2560
	global_load_ushort v20, v[18:19], off offset:3584
	s_nop 0
	global_load_ushort v19, v[18:19], off offset:2048
	s_waitcnt vmcnt(38)
	v_lshlrev_b32_e32 v18, 16, v171
	v_max_f32_e32 v18, v18, v18
	v_med3_f32 v18, v18, s9, v244
	v_mul_f32_e32 v18, 0xbfb8aa3b, v18
	v_exp_f32_e32 v18, v18
	ds_write_b16_d16_hi v17, v172 offset:3168
	ds_write_b16_d16_hi v17, v152 offset:7776
	v_add_f32_e32 v22, 1.0, v18
	v_rcp_f32_e32 v22, v22
	s_nop 0
	v_fma_f32 v23, v117, v22, v116
	v_mul_f32_e32 v18, v18, v22
	v_mul_f32_e32 v22, v173, v23
	v_max_f32_e32 v22, 0xda24260, v22
	v_rcp_f32_e32 v23, v22
	v_mul_f32_e32 v18, v117, v18
	v_mul_f32_e32 v18, v18, v23
	v_bfe_u32 v23, v18, 16, 1
	v_add3_u32 v23, v18, v23, s10
	s_waitcnt vmcnt(37)
	v_lshlrev_b32_e32 v18, 16, v170
	v_mul_f32_e32 v18, v22, v18
	v_bfe_u32 v100, v18, 16, 1
	v_add3_u32 v18, v18, v100, s10
	ds_write_b16_d16_hi v17, v18 offset:3024
	ds_write_b16_d16_hi v17, v23 offset:7632
	v_lshlrev_b32_e32 v18, 16, v168
	v_max_f32_e32 v18, v18, v18
	v_med3_f32 v18, v18, s9, v244
	v_mul_f32_e32 v18, 0xbfb8aa3b, v18
	v_exp_f32_e32 v18, v18
	s_nop 0
	v_add_f32_e32 v100, 1.0, v18
	v_rcp_f32_e32 v100, v100
	s_nop 0
	v_fma_f32 v101, v117, v100, v116
	v_mul_f32_e32 v22, v22, v101
	v_max_f32_e32 v22, 0xda24260, v22
	v_mul_f32_e32 v18, v18, v100
	v_rcp_f32_e32 v100, v22
	v_mul_f32_e32 v18, v117, v18
	v_mul_f32_e32 v18, v18, v100
	v_bfe_u32 v100, v18, 16, 1
	v_add3_u32 v18, v18, v100, s10
	v_lshlrev_b32_e32 v100, 16, v164
	v_mul_f32_e32 v100, v22, v100
	v_bfe_u32 v101, v100, 16, 1
	v_add3_u32 v100, v100, v101, s10
	ds_write_b16_d16_hi v17, v100 offset:2880
	ds_write_b16_d16_hi v17, v18 offset:7488
	s_waitcnt vmcnt(36)
	v_lshlrev_b32_e32 v100, 16, v165
	v_max_f32_e32 v100, v100, v100
	v_med3_f32 v100, v100, s9, v244
	v_mul_f32_e32 v100, 0xbfb8aa3b, v100
	v_exp_f32_e32 v100, v100
	s_nop 0
	v_add_f32_e32 v101, 1.0, v100
	v_rcp_f32_e32 v101, v101
	s_nop 0
	v_fma_f32 v105, v117, v101, v116
	v_mul_f32_e32 v22, v22, v105
	v_max_f32_e32 v22, 0xda24260, v22
	v_mul_f32_e32 v100, v100, v101
	v_rcp_f32_e32 v101, v22
	v_mul_f32_e32 v100, v117, v100
	v_mul_f32_e32 v100, v100, v101
	v_bfe_u32 v101, v100, 16, 1
	v_add3_u32 v101, v100, v101, s10
	s_waitcnt vmcnt(35)
	v_lshlrev_b32_e32 v100, 16, v163
	v_mul_f32_e32 v100, v22, v100
	v_bfe_u32 v105, v100, 16, 1
	v_add3_u32 v100, v100, v105, s10
	ds_write_b16_d16_hi v17, v100 offset:2736
	ds_write_b16_d16_hi v17, v101 offset:7344
	s_waitcnt vmcnt(34)
	v_lshlrev_b32_e32 v100, 16, v160
	v_max_f32_e32 v100, v100, v100
	v_med3_f32 v100, v100, s9, v244
	v_mul_f32_e32 v100, 0xbfb8aa3b, v100
	v_exp_f32_e32 v100, v100
	s_nop 0
	v_add_f32_e32 v105, 1.0, v100
	v_rcp_f32_e32 v105, v105
	s_nop 0
	v_fma_f32 v160, v117, v105, v116
	v_mul_f32_e32 v22, v22, v160
	v_mul_f32_e32 v100, v100, v105
	v_max_f32_e32 v105, 0xda24260, v22
	v_rcp_f32_e32 v22, v105
	v_mul_f32_e32 v100, v117, v100
	v_mul_f32_e32 v22, v100, v22
	v_bfe_u32 v100, v22, 16, 1
	v_add3_u32 v22, v22, v100, s10
	v_lshlrev_b32_e32 v100, 16, v158
	v_mul_f32_e32 v100, v105, v100
	v_bfe_u32 v158, v100, 16, 1
	v_add3_u32 v100, v100, v158, s10
	ds_write_b16_d16_hi v17, v100 offset:2592
	ds_write_b16_d16_hi v17, v22 offset:7200
	v_lshlrev_b32_e32 v100, 16, v115
	v_max_f32_e32 v100, v100, v100
	v_med3_f32 v100, v100, s9, v244
	v_mul_f32_e32 v100, 0xbfb8aa3b, v100
	v_exp_f32_e32 v100, v100
	s_nop 0
	v_add_f32_e32 v115, 1.0, v100
	v_rcp_f32_e32 v115, v115
	s_nop 0
	v_fma_f32 v158, v117, v115, v116
	v_mul_f32_e32 v105, v105, v158
	v_mul_f32_e32 v100, v100, v115
	v_max_f32_e32 v115, 0xda24260, v105
	v_rcp_f32_e32 v105, v115
	v_mul_f32_e32 v100, v117, v100
	v_mul_f32_e32 v100, v100, v105
	v_bfe_u32 v105, v100, 16, 1
	v_add3_u32 v105, v100, v105, s10
	s_waitcnt vmcnt(23)
	v_lshlrev_b32_e32 v100, 16, v157
	v_mul_f32_e32 v100, v115, v100
	v_bfe_u32 v157, v100, 16, 1
	v_add3_u32 v100, v100, v157, s10
	ds_write_b16_d16_hi v17, v100 offset:2448
	ds_write_b16_d16_hi v17, v105 offset:7056
	v_lshlrev_b32_e32 v100, 16, v111
	v_max_f32_e32 v100, v100, v100
	v_med3_f32 v100, v100, s9, v244
	v_mul_f32_e32 v100, 0xbfb8aa3b, v100
	v_exp_f32_e32 v100, v100
	s_nop 0
	v_add_f32_e32 v111, 1.0, v100
	v_rcp_f32_e32 v111, v111
	s_nop 0
	v_fma_f32 v157, v117, v111, v116
	v_mul_f32_e32 v100, v100, v111
	v_mul_f32_e32 v111, v115, v157
	v_max_f32_e32 v111, 0xda24260, v111
	v_rcp_f32_e32 v115, v111
	v_mul_f32_e32 v100, v117, v100
	v_mul_f32_e32 v109, v111, v109
	v_mul_f32_e32 v100, v100, v115
	v_bfe_u32 v115, v100, 16, 1
	v_add3_u32 v100, v100, v115, s10
	v_bfe_u32 v115, v109, 16, 1
	v_add3_u32 v109, v109, v115, s10
	ds_write_b16_d16_hi v17, v109 offset:2304
	ds_write_b16_d16_hi v17, v100 offset:6912
	s_waitcnt vmcnt(15)
	v_lshlrev_b32_e32 v109, 16, v169
	v_max_f32_e32 v109, v109, v109
	v_med3_f32 v109, v109, s9, v244
	v_mul_f32_e32 v109, 0xbfb8aa3b, v109
	v_exp_f32_e32 v109, v109
	s_nop 0
	v_add_f32_e32 v115, 1.0, v109
	v_rcp_f32_e32 v115, v115
	s_nop 0
	v_fma_f32 v157, v117, v115, v116
	v_mul_f32_e32 v111, v111, v157
	v_max_f32_e32 v111, 0xda24260, v111
	v_mul_f32_e32 v109, v109, v115
	v_rcp_f32_e32 v115, v111
	v_mul_f32_e32 v109, v117, v109
	v_mul_f32_e32 v109, v109, v115
	v_bfe_u32 v115, v109, 16, 1
	v_add3_u32 v109, v109, v115, s10
	s_waitcnt vmcnt(14)
	v_lshlrev_b32_e32 v115, 16, v167
	v_mul_f32_e32 v115, v111, v115
	v_bfe_u32 v157, v115, 16, 1
	v_add3_u32 v115, v115, v157, s10
	ds_write_b16_d16_hi v17, v115 offset:2160
	ds_write_b16_d16_hi v17, v109 offset:6768
	s_waitcnt vmcnt(13)
	v_lshlrev_b32_e32 v115, 16, v166
	v_max_f32_e32 v115, v115, v115
	v_med3_f32 v115, v115, s9, v244
	v_mul_f32_e32 v115, 0xbfb8aa3b, v115
	v_exp_f32_e32 v115, v115
	global_load_ushort v175, v[10:11], off offset:3072
	global_load_ushort v173, v[10:11], off offset:1536
	global_load_ushort v174, v[6:7], off offset:2560
	global_load_ushort v171, v[6:7], off offset:1024
	global_load_ushort v172, v[12:13], off offset:2048
	global_load_ushort v169, v[12:13], off offset:512
	global_load_ushort v170, v[4:5], off offset:1536
	global_load_ushort v166, v[4:5], off
	global_load_ushort v168, v[14:15], off offset:1024
	v_add_co_u32_e32 v4, vcc, s11, v0
	v_add_f32_e32 v157, 1.0, v115
	v_rcp_f32_e32 v157, v157
	v_addc_co_u32_e32 v5, vcc, 0, v1, vcc
	v_fma_f32 v158, v117, v157, v116
	v_mul_f32_e32 v111, v111, v158
	v_max_f32_e32 v111, 0xda24260, v111
	v_mul_f32_e32 v115, v115, v157
	v_rcp_f32_e32 v157, v111
	v_mul_f32_e32 v115, v117, v115
	v_mul_f32_e32 v115, v115, v157
	v_bfe_u32 v157, v115, 16, 1
	v_add3_u32 v157, v115, v157, s10
	s_waitcnt vmcnt(21)
	v_lshlrev_b32_e32 v115, 16, v162
	v_mul_f32_e32 v115, v111, v115
	v_bfe_u32 v158, v115, 16, 1
	v_add3_u32 v115, v115, v158, s10
	global_load_ushort v165, v[4:5], off offset:3584
	global_load_ushort v167, v[4:5], off offset:512
	global_load_ushort v163, v[2:3], off offset:3072
	global_load_ushort v164, v[2:3], off
	global_load_ushort v160, v[8:9], off offset:2560
	global_load_ushort v162, v[0:1], off offset:3584
	global_load_ushort v158, v[0:1], off offset:2048
	s_waitcnt vmcnt(27)
	v_lshlrev_b32_e32 v0, 16, v159
	v_max_f32_e32 v0, v0, v0
	v_med3_f32 v0, v0, s9, v244
	v_mul_f32_e32 v0, 0xbfb8aa3b, v0
	v_exp_f32_e32 v0, v0
	ds_write_b16_d16_hi v17, v115 offset:2016
	ds_write_b16_d16_hi v17, v157 offset:6624
	v_add_f32_e32 v1, 1.0, v0
	v_rcp_f32_e32 v1, v1
	s_nop 0
	v_fma_f32 v2, v117, v1, v116
	v_mul_f32_e32 v0, v0, v1
	v_mul_f32_e32 v1, v111, v2
	v_max_f32_e32 v1, 0xda24260, v1
	v_rcp_f32_e32 v2, v1
	v_mul_f32_e32 v0, v117, v0
	v_mul_f32_e32 v0, v0, v2
	v_bfe_u32 v2, v0, 16, 1
	v_add3_u32 v0, v0, v2, s10
	s_waitcnt vmcnt(26)
	v_lshlrev_b32_e32 v2, 16, v113
	v_mul_f32_e32 v2, v1, v2
	v_bfe_u32 v3, v2, 16, 1
	v_add3_u32 v2, v2, v3, s10
	ds_write_b16_d16_hi v17, v2 offset:1872
	ds_write_b16_d16_hi v17, v0 offset:6480
	s_waitcnt vmcnt(25)
	v_lshlrev_b32_e32 v2, 16, v107
	v_max_f32_e32 v2, v2, v2
	v_med3_f32 v2, v2, s9, v244
	v_mul_f32_e32 v2, 0xbfb8aa3b, v2
	v_exp_f32_e32 v2, v2
	s_nop 0
	v_add_f32_e32 v3, 1.0, v2
	v_rcp_f32_e32 v3, v3
	s_nop 0
	v_fma_f32 v4, v117, v3, v116
	v_mul_f32_e32 v1, v1, v4
	v_max_f32_e32 v1, 0xda24260, v1
	v_mul_f32_e32 v2, v2, v3
	v_rcp_f32_e32 v3, v1
	v_mul_f32_e32 v2, v117, v2
	v_mul_f32_e32 v2, v2, v3
	v_bfe_u32 v3, v2, 16, 1
	v_add3_u32 v159, v2, v3, s10
	s_waitcnt vmcnt(24)
	v_lshlrev_b32_e32 v2, 16, v106
	v_mul_f32_e32 v2, v1, v2
	v_bfe_u32 v3, v2, 16, 1
	v_add3_u32 v2, v2, v3, s10
	ds_write_b16_d16_hi v17, v2 offset:1728
	ds_write_b16_d16_hi v17, v159 offset:6336
	s_waitcnt vmcnt(23)
	v_lshlrev_b32_e32 v2, 16, v104
	v_max_f32_e32 v2, v2, v2
	v_med3_f32 v2, v2, s9, v244
	v_mul_f32_e32 v2, 0xbfb8aa3b, v2
	v_exp_f32_e32 v2, v2
	s_nop 0
	v_add_f32_e32 v3, 1.0, v2
	v_rcp_f32_e32 v3, v3
	s_nop 0
	v_fma_f32 v4, v117, v3, v116
	v_mul_f32_e32 v1, v1, v4
	v_max_f32_e32 v1, 0xda24260, v1
	v_mul_f32_e32 v2, v2, v3
	v_rcp_f32_e32 v3, v1
	v_mul_f32_e32 v2, v117, v2
	v_mul_f32_e32 v2, v2, v3
	v_bfe_u32 v3, v2, 16, 1
	v_add3_u32 v2, v2, v3, s10
	s_waitcnt vmcnt(22)
	v_lshlrev_b32_e32 v3, 16, v103
	v_mul_f32_e32 v3, v1, v3
	v_bfe_u32 v4, v3, 16, 1
	v_add3_u32 v3, v3, v4, s10
	ds_write_b16_d16_hi v17, v3 offset:1584
	ds_write_b16_d16_hi v17, v2 offset:6192
	s_waitcnt vmcnt(21)
	v_lshlrev_b32_e32 v3, 16, v102
	v_max_f32_e32 v3, v3, v3
	v_med3_f32 v3, v3, s9, v244
	v_mul_f32_e32 v3, 0xbfb8aa3b, v3
	v_exp_f32_e32 v3, v3
	s_nop 0
	v_add_f32_e32 v4, 1.0, v3
	v_rcp_f32_e32 v4, v4
	s_nop 0
	v_fma_f32 v5, v117, v4, v116
	v_mul_f32_e32 v1, v1, v5
	v_max_f32_e32 v1, 0xda24260, v1
	v_mul_f32_e32 v3, v3, v4
	v_rcp_f32_e32 v4, v1
	v_mul_f32_e32 v3, v117, v3
	v_mul_f32_e32 v3, v3, v4
	v_bfe_u32 v4, v3, 16, 1
	v_add3_u32 v102, v3, v4, s10
	s_waitcnt vmcnt(20)
	v_lshlrev_b32_e32 v3, 16, v99
	v_mul_f32_e32 v3, v1, v3
	v_bfe_u32 v4, v3, 16, 1
	v_add3_u32 v3, v3, v4, s10
	ds_write_b16_d16_hi v17, v3 offset:1440
	ds_write_b16_d16_hi v17, v102 offset:6048
	s_waitcnt vmcnt(19)
	v_lshlrev_b32_e32 v3, 16, v98
	v_max_f32_e32 v3, v3, v3
	v_med3_f32 v3, v3, s9, v244
	v_mul_f32_e32 v3, 0xbfb8aa3b, v3
	v_exp_f32_e32 v3, v3
	s_nop 0
	v_add_f32_e32 v4, 1.0, v3
	v_rcp_f32_e32 v4, v4
	s_nop 0
	v_fma_f32 v5, v117, v4, v116
	v_mul_f32_e32 v1, v1, v5
	v_max_f32_e32 v1, 0xda24260, v1
	v_mul_f32_e32 v3, v3, v4
	v_rcp_f32_e32 v4, v1
	v_mul_f32_e32 v3, v117, v3
	v_mul_f32_e32 v3, v3, v4
	v_bfe_u32 v4, v3, 16, 1
	v_add3_u32 v3, v3, v4, s10
	s_waitcnt vmcnt(18)
	v_lshlrev_b32_e32 v4, 16, v21
	v_mul_f32_e32 v4, v1, v4
	v_bfe_u32 v5, v4, 16, 1
	v_add3_u32 v4, v4, v5, s10
	ds_write_b16_d16_hi v17, v4 offset:1296
	ds_write_b16_d16_hi v17, v3 offset:5904
	s_waitcnt vmcnt(17)
	v_lshlrev_b32_e32 v4, 16, v20
	v_max_f32_e32 v4, v4, v4
	v_med3_f32 v4, v4, s9, v244
	v_mul_f32_e32 v4, 0xbfb8aa3b, v4
	v_exp_f32_e32 v4, v4
	s_nop 0
	v_add_f32_e32 v5, 1.0, v4
	v_rcp_f32_e32 v5, v5
	s_nop 0
	v_fma_f32 v6, v117, v5, v116
	v_mul_f32_e32 v1, v1, v6
	v_max_f32_e32 v12, 0xda24260, v1
	v_rcp_f32_e32 v1, v12
	v_mul_f32_e32 v4, v4, v5
	v_mul_f32_e32 v4, v117, v4
	v_mul_f32_e32 v1, v4, v1
	v_bfe_u32 v4, v1, 16, 1
	v_add3_u32 v20, v1, v4, s10
	s_waitcnt vmcnt(16)
	v_lshlrev_b32_e32 v1, 16, v19
	v_mul_f32_e32 v1, v12, v1
	v_bfe_u32 v4, v1, 16, 1
	v_add3_u32 v1, v1, v4, s10
	ds_write_b16_d16_hi v17, v1 offset:1152
	ds_write_b16_d16_hi v17, v20 offset:5760
	s_waitcnt vmcnt(15)
	v_lshlrev_b32_e32 v8, 16, v175
	v_max_f32_e32 v8, v8, v8
	v_med3_f32 v8, v8, s9, v244
	v_mul_f32_e32 v8, 0xbfb8aa3b, v8
	v_exp_f32_e32 v98, v8
	v_and_b32_e32 v113, 0xffff0000, v2
	v_lshl_or_b32 v2, v108, 16, v124
	v_and_b32_e32 v115, 0xffff0000, v3
	v_add_f32_e32 v13, 1.0, v98
	v_rcp_f32_e32 v104, v13
	v_lshl_or_b32 v3, v110, 16, v112
	v_lshl_or_b32 v11, v151, 16, v129
	v_and_b32_e32 v19, 0xffff0000, v114
	v_fma_f32 v106, v117, v104, v116
	v_mul_f32_e32 v12, v12, v106
	v_max_f32_e32 v106, 0xda24260, v12
	v_rcp_f32_e32 v108, v106
	v_mul_f32_e32 v98, v98, v104
	v_mul_f32_e32 v98, v117, v98
	v_lshl_or_b32 v7, v133, 16, v127
	v_mul_f32_e32 v98, v98, v108
	v_bfe_u32 v104, v98, 16, 1
	v_add3_u32 v98, v98, v104, s10
	s_waitcnt vmcnt(13)
	v_lshlrev_b32_e32 v104, 16, v174
	v_max_f32_e32 v104, v104, v104
	v_med3_f32 v104, v104, s9, v244
	v_mul_f32_e32 v104, 0xbfb8aa3b, v104
	v_exp_f32_e32 v104, v104
	v_lshlrev_b32_e32 v108, 16, v173
	v_mul_f32_e32 v108, v106, v108
	v_bfe_u32 v112, v108, 16, 1
	v_add_f32_e32 v110, 1.0, v104
	v_rcp_f32_e32 v110, v110
	v_add3_u32 v108, v108, v112, s10
	ds_write_b16_d16_hi v17, v108 offset:1008
	v_and_b32_e32 v129, 0xffff0000, v98
	v_fma_f32 v108, v117, v110, v116
	v_mul_f32_e32 v106, v106, v108
	v_max_f32_e32 v106, 0xda24260, v106
	v_rcp_f32_e32 v108, v106
	ds_write_b16_d16_hi v17, v98 offset:5616
	v_mul_f32_e32 v98, v104, v110
	v_mul_f32_e32 v98, v117, v98
	v_mul_f32_e32 v98, v98, v108
	s_waitcnt vmcnt(11)
	v_lshlrev_b32_e32 v108, 16, v172
	v_max_f32_e32 v108, v108, v108
	v_med3_f32 v108, v108, s9, v244
	v_mul_f32_e32 v108, 0xbfb8aa3b, v108
	v_exp_f32_e32 v108, v108
	v_bfe_u32 v104, v98, 16, 1
	v_add3_u32 v98, v98, v104, s10
	v_lshlrev_b32_e32 v104, 16, v171
	v_add_f32_e32 v110, 1.0, v108
	v_rcp_f32_e32 v110, v110
	v_mul_f32_e32 v104, v106, v104
	v_bfe_u32 v112, v104, 16, 1
	v_add3_u32 v104, v104, v112, s10
	ds_write_b16_d16_hi v17, v104 offset:864
	v_fma_f32 v104, v117, v110, v116
	v_mul_f32_e32 v104, v106, v104
	v_max_f32_e32 v104, 0xda24260, v104
	v_rcp_f32_e32 v106, v104
	v_mul_f32_e32 v108, v108, v110
	v_mul_f32_e32 v108, v117, v108
	s_waitcnt vmcnt(10)
	v_lshlrev_b32_e32 v110, 16, v169
	v_mul_f32_e32 v106, v108, v106
	v_bfe_u32 v108, v106, 16, 1
	v_add3_u32 v106, v106, v108, s10
	s_waitcnt vmcnt(9)
	v_lshlrev_b32_e32 v108, 16, v170
	v_max_f32_e32 v108, v108, v108
	v_med3_f32 v108, v108, s9, v244
	v_mul_f32_e32 v108, 0xbfb8aa3b, v108
	v_exp_f32_e32 v108, v108
	v_mul_f32_e32 v110, v104, v110
	v_bfe_u32 v114, v110, 16, 1
	v_add3_u32 v110, v110, v114, s10
	v_add_f32_e32 v112, 1.0, v108
	v_rcp_f32_e32 v112, v112
	ds_write_b16_d16_hi v17, v110 offset:720
	v_and_b32_e32 v127, 0xffff0000, v106
	ds_write_b16_d16_hi v17, v106 offset:5328
	v_fma_f32 v110, v117, v112, v116
	v_mul_f32_e32 v104, v104, v110
	v_max_f32_e32 v104, 0xda24260, v104
	v_rcp_f32_e32 v110, v104
	v_mul_f32_e32 v106, v108, v112
	v_mul_f32_e32 v106, v117, v106
	v_lshl_or_b32 v1, v135, 16, v123
	v_mul_f32_e32 v106, v106, v110
	s_waitcnt vmcnt(7)
	v_lshlrev_b32_e32 v110, 16, v168
	v_max_f32_e32 v110, v110, v110
	v_med3_f32 v110, v110, s9, v244
	v_mul_f32_e32 v110, 0xbfb8aa3b, v110
	v_exp_f32_e32 v110, v110
	v_bfe_u32 v108, v106, 16, 1
	v_add3_u32 v106, v106, v108, s10
	v_lshlrev_b32_e32 v108, 16, v166
	v_add_f32_e32 v112, 1.0, v110
	v_rcp_f32_e32 v112, v112
	v_mul_f32_e32 v108, v104, v108
	v_bfe_u32 v114, v108, 16, 1
	v_add3_u32 v108, v108, v114, s10
	ds_write_b16_d16_hi v17, v108 offset:576
	v_fma_f32 v108, v117, v112, v116
	v_mul_f32_e32 v104, v104, v108
	v_max_f32_e32 v104, 0xda24260, v104
	v_rcp_f32_e32 v108, v104
	v_mul_f32_e32 v110, v110, v112
	v_mul_f32_e32 v110, v117, v110
	s_waitcnt vmcnt(6)
	v_lshlrev_b32_e32 v112, 16, v165
	v_mul_f32_e32 v108, v110, v108
	v_bfe_u32 v110, v108, 16, 1
	v_add3_u32 v108, v108, v110, s10
	s_waitcnt vmcnt(5)
	v_lshlrev_b32_e32 v110, 16, v167
	v_max_f32_e32 v110, v110, v110
	v_med3_f32 v110, v110, s9, v244
	v_mul_f32_e32 v110, 0xbfb8aa3b, v110
	v_exp_f32_e32 v110, v110
	v_mul_f32_e32 v112, v104, v112
	v_bfe_u32 v123, v112, 16, 1
	v_add3_u32 v112, v112, v123, s10
	v_add_f32_e32 v114, 1.0, v110
	v_rcp_f32_e32 v114, v114
	ds_write_b16_d16_hi v17, v112 offset:432
	v_lshl_or_b32 v5, v137, 16, v131
	v_and_b32_e32 v131, 0xffff0000, v108
	v_fma_f32 v112, v117, v114, v116
	v_mul_f32_e32 v104, v104, v112
	v_max_f32_e32 v104, 0xda24260, v104
	v_rcp_f32_e32 v112, v104
	ds_write_b16_d16_hi v17, v108 offset:5040
	v_mul_f32_e32 v108, v110, v114
	v_mul_f32_e32 v108, v117, v108
	v_mul_f32_e32 v108, v108, v112
	s_waitcnt vmcnt(3)
	v_lshlrev_b32_e32 v112, 16, v164
	v_max_f32_e32 v112, v112, v112
	v_med3_f32 v112, v112, s9, v244
	v_mul_f32_e32 v112, 0xbfb8aa3b, v112
	v_exp_f32_e32 v112, v112
	v_bfe_u32 v110, v108, 16, 1
	v_add3_u32 v108, v108, v110, s10
	v_lshlrev_b32_e32 v110, 16, v163
	v_add_f32_e32 v114, 1.0, v112
	v_rcp_f32_e32 v114, v114
	v_mul_f32_e32 v110, v104, v110
	v_bfe_u32 v123, v110, 16, 1
	v_add3_u32 v110, v110, v123, s10
	ds_write_b16_d16_hi v17, v110 offset:288
	v_fma_f32 v110, v117, v114, v116
	v_mul_f32_e32 v104, v104, v110
	v_max_f32_e32 v104, 0xda24260, v104
	v_rcp_f32_e32 v110, v104
	v_mul_f32_e32 v112, v112, v114
	v_mul_f32_e32 v112, v117, v112
	s_waitcnt vmcnt(2)
	v_lshlrev_b32_e32 v114, 16, v160
	v_mul_f32_e32 v110, v112, v110
	v_bfe_u32 v112, v110, 16, 1
	v_add3_u32 v110, v110, v112, s10
	s_waitcnt vmcnt(1)
	v_lshlrev_b32_e32 v112, 16, v162
	v_max_f32_e32 v112, v112, v112
	v_med3_f32 v112, v112, s9, v244
	v_mul_f32_e32 v112, 0xbfb8aa3b, v112
	v_exp_f32_e32 v112, v112
	v_mul_f32_e32 v114, v104, v114
	v_bfe_u32 v124, v114, 16, 1
	v_add3_u32 v114, v114, v124, s10
	v_add_f32_e32 v123, 1.0, v112
	v_rcp_f32_e32 v123, v123
	ds_write_b16_d16_hi v17, v114 offset:144
	v_lshl_or_b32 v12, v145, 16, v132
	v_lshl_or_b32 v6, v139, 16, v125
	v_fma_f32 v114, v117, v123, v116
	v_mul_f32_e32 v104, v104, v114
	v_max_f32_e32 v132, 0xda24260, v104
	v_rcp_f32_e32 v104, v132
	v_and_b32_e32 v125, 0xffff0000, v110
	ds_write_b16_d16_hi v17, v110 offset:4752
	v_mul_f32_e32 v110, v112, v123
	v_mul_f32_e32 v110, v117, v110
	v_mul_f32_e32 v104, v110, v104
	v_bfe_u32 v110, v104, 16, 1
	v_add3_u32 v104, v104, v110, s10
	s_waitcnt vmcnt(0)
	v_lshlrev_b32_e32 v110, 16, v158
	v_mul_f32_e32 v110, v132, v110
	v_bfe_u32 v112, v110, 16, 1
	v_add3_u32 v110, v110, v112, s10
	v_and_b32_e32 v111, 0xffff0000, v0
	v_and_b32_e32 v109, 0xffff0000, v109
	v_and_b32_e32 v107, 0xffff0000, v105
	v_and_b32_e32 v105, 0xffff0000, v101
	v_and_b32_e32 v103, 0xffff0000, v23
	v_and_b32_e32 v101, 0xffff0000, v156
	v_and_b32_e32 v99, 0xffff0000, v155
	v_and_b32_e32 v23, 0xffff0000, v154
	v_and_b32_e32 v21, 0xffff0000, v153
	v_lshl_or_b32 v0, v134, 16, v128
	v_lshl_or_b32 v4, v150, 16, v130
	v_lshl_or_b32 v10, v149, 16, v126
	v_lshl_or_b32 v9, v144, 16, v143
	v_lshl_or_b32 v8, v148, 16, v141
	v_lshl_or_b32 v15, v146, 16, v140
	v_lshl_or_b32 v14, v147, 16, v138
	v_lshl_or_b32 v13, v142, 16, v136
	ds_write_b16_d16_hi v17, v98 offset:5472
	ds_write_b16_d16_hi v17, v106 offset:5184
	ds_write_b16_d16_hi v17, v108 offset:4896
	ds_write_b16_d16_hi v17, v110
	ds_write_b16_d16_hi v17, v104 offset:4608
	v_and_b32_e32 v124, 0xffff0000, v104
	v_and_b32_e32 v130, 0xffff0000, v108
	v_and_b32_e32 v126, 0xffff0000, v106
	v_and_b32_e32 v128, 0xffff0000, v98
	s_movk_i32 s0, 0x50
	v_pk_mul_f32 v[124:125], v[132:133], v[124:125] op_sel_hi:[0,1]
	v_pk_mul_f32 v[130:131], v[132:133], v[130:131] op_sel_hi:[0,1]
	v_pk_mul_f32 v[126:127], v[132:133], v[126:127] op_sel_hi:[0,1]
	v_pk_mul_f32 v[128:129], v[132:133], v[128:129] op_sel_hi:[0,1]
	v_and_b32_e32 v114, 0xffff0000, v20
	v_and_b32_e32 v112, 0xffff0000, v102
	v_and_b32_e32 v110, 0xffff0000, v159
	v_and_b32_e32 v108, 0xffff0000, v157
	v_and_b32_e32 v106, 0xffff0000, v100
	v_and_b32_e32 v104, 0xffff0000, v22
	v_and_b32_e32 v102, 0xffff0000, v18
	v_and_b32_e32 v100, 0xffff0000, v152
	v_and_b32_e32 v98, 0xffff0000, v122
	v_and_b32_e32 v22, 0xffff0000, v121
	v_and_b32_e32 v20, 0xffff0000, v120
	v_and_b32_e32 v18, 0xffff0000, v88
	v_mad_u64_u32 v[134:135], s[2:3], v16, s0, v[92:93]
	v_cvt_pk_bf16_f32 v124, v124, v125
	v_cvt_pk_bf16_f32 v125, v130, v131
	v_cvt_pk_bf16_f32 v126, v126, v127
	v_cvt_pk_bf16_f32 v127, v128, v129
	v_pk_mul_f32 v[114:115], v[132:133], v[114:115] op_sel_hi:[0,1]
	v_pk_mul_f32 v[112:113], v[132:133], v[112:113] op_sel_hi:[0,1]
	v_pk_mul_f32 v[110:111], v[132:133], v[110:111] op_sel_hi:[0,1]
	v_pk_mul_f32 v[108:109], v[132:133], v[108:109] op_sel_hi:[0,1]
	v_pk_mul_f32 v[106:107], v[132:133], v[106:107] op_sel_hi:[0,1]
	v_pk_mul_f32 v[104:105], v[132:133], v[104:105] op_sel_hi:[0,1]
	v_pk_mul_f32 v[102:103], v[132:133], v[102:103] op_sel_hi:[0,1]
	v_pk_mul_f32 v[100:101], v[132:133], v[100:101] op_sel_hi:[0,1]
	v_pk_mul_f32 v[98:99], v[132:133], v[98:99] op_sel_hi:[0,1]
	v_pk_mul_f32 v[22:23], v[132:133], v[22:23] op_sel_hi:[0,1]
	v_pk_mul_f32 v[20:21], v[132:133], v[20:21] op_sel_hi:[0,1]
	v_pk_mul_f32 v[18:19], v[132:133], v[18:19] op_sel_hi:[0,1]
	ds_write_b128 v134, v[124:127] offset:9216
	v_cvt_pk_bf16_f32 v124, v114, v115
	v_cvt_pk_bf16_f32 v125, v112, v113
	v_cvt_pk_bf16_f32 v126, v110, v111
	v_cvt_pk_bf16_f32 v127, v108, v109
	v_cvt_pk_bf16_f32 v106, v106, v107
	v_cvt_pk_bf16_f32 v107, v104, v105
	v_cvt_pk_bf16_f32 v108, v102, v103
	v_cvt_pk_bf16_f32 v109, v100, v101
	v_cvt_pk_bf16_f32 v98, v98, v99
	v_cvt_pk_bf16_f32 v99, v22, v23
	v_cvt_pk_bf16_f32 v100, v20, v21
	v_cvt_pk_bf16_f32 v101, v18, v19
	v_lshl_add_u32 v16, v16, 2, v92
	ds_write_b128 v134, v[124:127] offset:9232
	ds_write_b128 v134, v[106:109] offset:9248
	ds_write_b128 v134, v[98:101] offset:9264
	ds_write_b32 v16, v132 offset:19456
	ds_write_b128 v134, v[12:15] offset:14336
	ds_write_b128 v134, v[8:11] offset:14352
	ds_write_b128 v134, v[4:7] offset:14368
	ds_write_b128 v134, v[0:3] offset:14384
	s_waitcnt lgkmcnt(0)
	v_or_b32_e32 v88, v95, v118
	v_lshlrev_b64 v[0:1], 11, v[88:89]
	v_lshlrev_b32_e32 v100, 2, v119
	v_lshl_add_u64 v[0:1], s[40:41], 0, v[0:1]
	v_ashrrev_i32_e32 v101, 31, v100
	v_mad_u32_u24 v106, v118, s48, v92
	v_lshlrev_b32_e32 v95, 4, v119
	v_lshl_add_u64 v[0:1], v[0:1], 0, v[90:91]
	v_lshlrev_b64 v[102:103], 1, v[100:101]
	v_add_u32_e32 v107, v106, v95
	v_lshl_add_u64 v[104:105], v[0:1], 0, v[102:103]
	ds_read_b128 v[0:3], v107 offset:4608
	ds_read_b128 v[4:7], v107
	ds_read_b128 v[16:19], v107 offset:32
	ds_read_b128 v[20:23], v107 offset:4640
	s_waitcnt lgkmcnt(2)
	v_mfma_f32_32x32x16_bf16 v[0:15], v[0:3], v[4:7], 0
	v_cmp_ge_i32_e32 vcc, v100, v118
	v_cvt_pk_bf16_f32 v120, v32, v33
	v_cvt_pk_bf16_f32 v121, v34, v35
	v_cvt_pk_bf16_f32 v122, v36, v37
	v_cvt_pk_bf16_f32 v123, v38, v39
	v_lshl_add_u64 v[98:99], v[104:105], 0, s[4:5]
	global_load_dwordx2 v[196:197], v[98:99], off
	global_load_dwordx2 v[198:199], v[98:99], off offset:16
	global_load_dwordx2 v[200:201], v[98:99], off offset:32
	global_load_dwordx2 v[202:203], v[98:99], off offset:48
	global_load_dwordx2 v[230:231], v[98:99], off offset:64
	global_load_dwordx2 v[232:233], v[98:99], off offset:80
	global_load_dwordx2 v[234:235], v[98:99], off offset:96
	global_load_dwordx2 v[240:241], v[98:99], off offset:112
	s_waitcnt lgkmcnt(0)
	v_mfma_f32_32x32x16_bf16 v[0:15], v[20:23], v[16:19], v[0:15]
	ds_read_b128 v[16:19], v107 offset:4672
	ds_read_b128 v[20:23], v107 offset:64
	s_waitcnt lgkmcnt(0)
	v_mfma_f32_32x32x16_bf16 v[0:15], v[16:19], v[20:23], v[0:15]
	ds_read_b128 v[16:19], v107 offset:4704
	ds_read_b128 v[20:23], v107 offset:96
	s_waitcnt lgkmcnt(0)
	v_mfma_f32_32x32x16_bf16 v[0:15], v[16:19], v[20:23], v[0:15]
	v_or_b32_e32 v16, 1, v100
	s_nop 10
	v_cndmask_b32_e32 v0, 0, v0, vcc
	v_cmp_ge_i32_e32 vcc, v16, v118
	v_or_b32_e32 v16, 2, v100
	s_nop 0
	v_cndmask_b32_e32 v1, 0, v1, vcc
	v_cmp_ge_i32_e32 vcc, v16, v118
	v_or_b32_e32 v16, 3, v100
	s_nop 0
	v_cndmask_b32_e32 v2, 0, v2, vcc
	v_cmp_ge_i32_e32 vcc, v16, v118
	v_add_u32_e32 v16, 8, v100
	s_nop 0
	v_cndmask_b32_e32 v3, 0, v3, vcc
	v_cmp_ge_i32_e32 vcc, v16, v118
	v_add_u32_e32 v16, 9, v100
	v_cvt_pk_bf16_f32 v17, v2, v3
	v_cndmask_b32_e32 v4, 0, v4, vcc
	v_cmp_ge_i32_e32 vcc, v16, v118
	v_add_u32_e32 v16, 10, v100
	s_nop 0
	v_cndmask_b32_e32 v5, 0, v5, vcc
	v_cmp_ge_i32_e32 vcc, v16, v118
	v_add_u32_e32 v16, 11, v100
	v_cvt_pk_bf16_f32 v18, v4, v5
	v_cndmask_b32_e32 v6, 0, v6, vcc
	v_cmp_ge_i32_e32 vcc, v16, v118
	v_add_u32_e32 v16, 16, v100
	s_nop 0
	v_cndmask_b32_e32 v7, 0, v7, vcc
	v_cmp_ge_i32_e32 vcc, v16, v118
	v_add_u32_e32 v16, 17, v100
	v_cvt_pk_bf16_f32 v19, v6, v7
	v_cndmask_b32_e32 v8, 0, v8, vcc
	v_cmp_ge_i32_e32 vcc, v16, v118
	v_add_u32_e32 v16, 18, v100
	s_nop 0
	v_cndmask_b32_e32 v9, 0, v9, vcc
	v_cmp_ge_i32_e32 vcc, v16, v118
	v_add_u32_e32 v16, 19, v100
	v_cvt_pk_bf16_f32 v20, v8, v9
	v_cndmask_b32_e32 v10, 0, v10, vcc
	v_cmp_ge_i32_e32 vcc, v16, v118
	v_add_u32_e32 v16, 24, v100
	s_nop 0
	v_cndmask_b32_e32 v11, 0, v11, vcc
	v_cmp_ge_i32_e32 vcc, v16, v118
	v_add_u32_e32 v16, 25, v100
	v_cvt_pk_bf16_f32 v21, v10, v11
	v_cndmask_b32_e32 v12, 0, v12, vcc
	v_cmp_ge_i32_e32 vcc, v16, v118
	v_add_u32_e32 v16, 26, v100
	s_nop 0
	v_cndmask_b32_e32 v13, 0, v13, vcc
	v_cmp_ge_i32_e32 vcc, v16, v118
	v_add_u32_e32 v16, 27, v100
	v_cvt_pk_bf16_f32 v22, v12, v13
	v_cndmask_b32_e32 v14, 0, v14, vcc
	v_cmp_ge_i32_e32 vcc, v16, v118
	v_cvt_pk_bf16_f32 v16, v0, v1
	v_lshlrev_b32_e32 v0, 3, v119
	v_mul_u32_u24_e32 v1, 0x50, v118
	v_add3_u32 v107, v92, v0, v1
	v_add_u32_e32 v4, 0x3800, v107
	v_add_u32_e32 v106, v106, v0
	ds_read2_b64 v[0:3], v4 offset1:2
	ds_read2_b64 v[108:111], v4 offset0:4 offset1:6
	v_cndmask_b32_e32 v15, 0, v15, vcc
	v_cvt_pk_bf16_f32 v23, v14, v15
	s_waitcnt lgkmcnt(1)
	v_mfma_f32_32x32x16_bf16 v[0:15], v[0:3], v[16:19], 0
	v_add_co_u32_e32 v104, vcc, s6, v104
	s_nop 1
	v_addc_co_u32_e32 v105, vcc, 0, v105, vcc
	s_waitcnt lgkmcnt(0)
	v_mfma_f32_32x32x16_bf16 v[0:15], v[108:111], v[20:23], v[0:15]
	ds_read2_b64 v[108:111], v106 offset1:2
	ds_read2_b64 v[112:115], v106 offset0:4 offset1:6
	s_waitcnt lgkmcnt(1)
	v_mfma_f32_32x32x16_bf16 v[0:15], v[120:123], v[108:111], v[0:15]
	v_cvt_pk_bf16_f32 v108, v40, v41
	v_cvt_pk_bf16_f32 v109, v42, v43
	v_cvt_pk_bf16_f32 v110, v44, v45
	v_cvt_pk_bf16_f32 v111, v46, v47
	s_waitcnt lgkmcnt(0)
	s_nop 0
	v_mfma_f32_32x32x16_bf16 v[0:15], v[108:111], v[112:115], v[0:15]
	ds_read2_b64 v[108:111], v106 offset0:8 offset1:10
	v_cvt_pk_bf16_f32 v112, v54, v55
	v_cvt_pk_bf16_f32 v113, v50, v51
	v_cvt_pk_bf16_f32 v114, v52, v53
	v_cvt_pk_bf16_f32 v115, v82, v83
	s_waitcnt lgkmcnt(0)
	s_nop 0
	v_mfma_f32_32x32x16_bf16 v[0:15], v[112:115], v[108:111], v[0:15]
	ds_read2_b64 v[108:111], v106 offset0:12 offset1:14
	v_cvt_pk_bf16_f32 v112, v56, v57
	v_cvt_pk_bf16_f32 v113, v58, v59
	v_cvt_pk_bf16_f32 v114, v60, v61
	v_cvt_pk_bf16_f32 v115, v62, v63
	s_waitcnt lgkmcnt(0)
	s_nop 0
	v_mfma_f32_32x32x16_bf16 v[0:15], v[112:115], v[108:111], v[0:15]
	s_waitcnt vmcnt(7)
	v_lshlrev_b32_e32 v110, 16, v196
	v_and_b32_e32 v111, 0xffff0000, v196
	s_nop 7
	v_pk_add_f32 v[0:1], v[0:1], v[110:111]
	v_lshlrev_b32_e32 v108, 16, v197
	v_and_b32_e32 v109, 0xffff0000, v197
	v_pk_add_f32 v[2:3], v[2:3], v[108:109]
	v_mul_f32_e32 v108, v1, v1
	v_pk_fma_f32 v[108:109], v[0:1], v[0:1], v[108:109] op_sel_hi:[1,1,0]
	v_cvt_pk_bf16_f32 v0, v0, v1
	v_cvt_pk_bf16_f32 v1, v2, v3
	global_store_dwordx2 v[104:105], v[0:1], off offset:1536
	v_mul_f32_e32 v110, v3, v3
	v_pk_fma_f32 v[110:111], v[2:3], v[2:3], v[110:111] op_sel_hi:[1,1,0]
	s_waitcnt vmcnt(7)
	v_lshlrev_b32_e32 v2, 16, v198
	v_and_b32_e32 v3, 0xffff0000, v198
	v_lshlrev_b32_e32 v0, 16, v199
	v_and_b32_e32 v1, 0xffff0000, v199
	v_pk_add_f32 v[2:3], v[4:5], v[2:3]
	v_pk_add_f32 v[0:1], v[6:7], v[0:1]
	v_mul_f32_e32 v4, v3, v3
	v_mul_f32_e32 v6, v1, v1
	v_pk_fma_f32 v[4:5], v[2:3], v[2:3], v[4:5] op_sel_hi:[1,1,0]
	v_pk_fma_f32 v[6:7], v[0:1], v[0:1], v[6:7] op_sel_hi:[1,1,0]
	v_cvt_pk_bf16_f32 v2, v2, v3
	v_cvt_pk_bf16_f32 v3, v0, v1
	v_pk_add_f32 v[4:5], v[4:5], v[6:7]
	global_store_dwordx2 v[98:99], v[2:3], off offset:16
	v_pk_add_f32 v[108:109], v[108:109], v[110:111]
	s_waitcnt vmcnt(7)
	v_lshlrev_b32_e32 v2, 16, v200
	v_and_b32_e32 v3, 0xffff0000, v200
	v_pk_add_f32 v[2:3], v[8:9], v[2:3]
	v_lshlrev_b32_e32 v0, 16, v201
	v_and_b32_e32 v1, 0xffff0000, v201
	v_pk_add_f32 v[6:7], v[10:11], v[0:1]
	v_mul_f32_e32 v0, v3, v3
	v_pk_fma_f32 v[0:1], v[2:3], v[2:3], v[0:1] op_sel_hi:[1,1,0]
	v_cvt_pk_bf16_f32 v2, v2, v3
	v_cvt_pk_bf16_f32 v3, v6, v7
	global_store_dwordx2 v[98:99], v[2:3], off offset:32
	v_mul_f32_e32 v8, v7, v7
	v_pk_fma_f32 v[8:9], v[6:7], v[6:7], v[8:9] op_sel_hi:[1,1,0]
	v_pk_add_f32 v[4:5], v[108:109], v[4:5]
	v_pk_add_f32 v[0:1], v[0:1], v[8:9]
	s_nop 0
	v_pk_add_f32 v[0:1], v[4:5], v[0:1]
	s_waitcnt vmcnt(7)
	v_lshlrev_b32_e32 v4, 16, v202
	v_and_b32_e32 v5, 0xffff0000, v202
	v_lshlrev_b32_e32 v2, 16, v203
	v_and_b32_e32 v3, 0xffff0000, v203
	v_pk_add_f32 v[4:5], v[12:13], v[4:5]
	v_pk_add_f32 v[2:3], v[14:15], v[2:3]
	v_mul_f32_e32 v6, v5, v5
	v_mul_f32_e32 v8, v3, v3
	v_pk_fma_f32 v[6:7], v[4:5], v[4:5], v[6:7] op_sel_hi:[1,1,0]
	v_pk_fma_f32 v[8:9], v[2:3], v[2:3], v[8:9] op_sel_hi:[1,1,0]
	s_nop 0
	v_pk_add_f32 v[6:7], v[6:7], v[8:9]
	s_nop 0
	v_pk_add_f32 v[112:113], v[0:1], v[6:7]
	v_cvt_pk_bf16_f32 v0, v4, v5
	v_cvt_pk_bf16_f32 v1, v2, v3
	global_store_dwordx2 v[98:99], v[0:1], off offset:48
	v_add_u32_e32 v4, 0x4000, v107
	ds_read2_b64 v[0:3], v4 offset0:64 offset1:66
	ds_read2_b64 v[108:111], v4 offset0:68 offset1:70
	s_waitcnt lgkmcnt(1)
	v_mfma_f32_32x32x16_bf16 v[0:15], v[0:3], v[16:19], 0
	s_waitcnt lgkmcnt(0)
	v_mfma_f32_32x32x16_bf16 v[0:15], v[108:111], v[20:23], v[0:15]
	v_cvt_pk_bf16_f32 v108, v26, v27
	v_cvt_pk_bf16_f32 v109, v28, v29
	v_cvt_pk_bf16_f32 v110, v30, v31
	v_cvt_pk_bf16_f32 v111, v48, v49
	ds_read2_b64 v[16:19], v106 offset1:2
	ds_read2_b64 v[20:23], v106 offset0:4 offset1:6
	s_waitcnt lgkmcnt(1)
	v_mfma_f32_32x32x16_bf16 v[0:15], v[108:111], v[16:19], v[0:15]
	v_cvt_pk_bf16_f32 v16, v24, v25
	v_cvt_pk_bf16_f32 v17, v84, v85
	v_cvt_pk_bf16_f32 v18, v86, v87
	v_cvt_pk_bf16_f32 v19, v96, v97
	s_waitcnt lgkmcnt(0)
	s_nop 0
	v_mfma_f32_32x32x16_bf16 v[0:15], v[16:19], v[20:23], v[0:15]
	ds_read2_b64 v[16:19], v106 offset0:8 offset1:10
	v_cvt_pk_bf16_f32 v20, v66, v67
	v_cvt_pk_bf16_f32 v21, v68, v69
	v_cvt_pk_bf16_f32 v22, v70, v71
	v_cvt_pk_bf16_f32 v23, v72, v73
	s_waitcnt lgkmcnt(0)
	s_nop 0
	v_mfma_f32_32x32x16_bf16 v[0:15], v[20:23], v[16:19], v[0:15]
	ds_read2_b64 v[16:19], v106 offset0:12 offset1:14
	v_cvt_pk_bf16_f32 v20, v74, v75
	v_cvt_pk_bf16_f32 v21, v76, v77
	v_cvt_pk_bf16_f32 v22, v78, v79
	v_cvt_pk_bf16_f32 v23, v80, v81
	s_waitcnt lgkmcnt(0)
	s_nop 0
	v_mfma_f32_32x32x16_bf16 v[0:15], v[20:23], v[16:19], v[0:15]
	s_waitcnt vmcnt(7)
	v_lshlrev_b32_e32 v18, 16, v230
	v_and_b32_e32 v19, 0xffff0000, v230
	s_nop 7
	v_pk_add_f32 v[0:1], v[0:1], v[18:19]
	v_lshlrev_b32_e32 v16, 16, v231
	v_and_b32_e32 v17, 0xffff0000, v231
	v_pk_add_f32 v[2:3], v[2:3], v[16:17]
	v_mul_f32_e32 v16, v1, v1
	v_pk_fma_f32 v[16:17], v[0:1], v[0:1], v[16:17] op_sel_hi:[1,1,0]
	v_cvt_pk_bf16_f32 v0, v0, v1
	v_cvt_pk_bf16_f32 v1, v2, v3
	global_store_dwordx2 v[98:99], v[0:1], off offset:64
	v_mul_f32_e32 v18, v3, v3
	v_pk_fma_f32 v[18:19], v[2:3], v[2:3], v[18:19] op_sel_hi:[1,1,0]
	s_waitcnt vmcnt(7)
	v_lshlrev_b32_e32 v2, 16, v232
	v_and_b32_e32 v3, 0xffff0000, v232
	v_lshlrev_b32_e32 v0, 16, v233
	v_and_b32_e32 v1, 0xffff0000, v233
	v_pk_add_f32 v[2:3], v[4:5], v[2:3]
	v_pk_add_f32 v[0:1], v[6:7], v[0:1]
	v_mul_f32_e32 v4, v3, v3
	v_mul_f32_e32 v6, v1, v1
	v_pk_fma_f32 v[4:5], v[2:3], v[2:3], v[4:5] op_sel_hi:[1,1,0]
	v_pk_fma_f32 v[6:7], v[0:1], v[0:1], v[6:7] op_sel_hi:[1,1,0]
	v_cvt_pk_bf16_f32 v2, v2, v3
	v_cvt_pk_bf16_f32 v3, v0, v1
	v_pk_add_f32 v[4:5], v[4:5], v[6:7]
	global_store_dwordx2 v[98:99], v[2:3], off offset:80
	v_pk_add_f32 v[16:17], v[16:17], v[18:19]
	s_waitcnt vmcnt(7)
	v_lshlrev_b32_e32 v2, 16, v234
	v_and_b32_e32 v3, 0xffff0000, v234
	v_lshlrev_b32_e32 v0, 16, v235
	v_and_b32_e32 v1, 0xffff0000, v235
	v_pk_add_f32 v[2:3], v[8:9], v[2:3]
	v_pk_add_f32 v[6:7], v[10:11], v[0:1]
	v_mov_b32_e32 v0, v2
	v_mov_b32_e32 v8, v3
	v_cvt_pk_bf16_f32 v2, v2, v3
	v_cvt_pk_bf16_f32 v3, v6, v7
	global_store_dwordx2 v[98:99], v[2:3], off offset:96
	v_mov_b32_e32 v9, v7
	v_mov_b32_e32 v1, v6
	v_pk_mul_f32 v[8:9], v[8:9], v[8:9]
	v_pk_add_f32 v[16:17], v[112:113], v[16:17]
	v_pk_fma_f32 v[0:1], v[0:1], v[0:1], v[8:9]
	v_pk_add_f32 v[4:5], v[16:17], v[4:5]
	v_pk_add_f32 v[0:1], v[0:1], v[0:1] op_sel:[0,1] op_sel_hi:[1,0]
	s_nop 0
	v_pk_add_f32 v[0:1], v[4:5], v[0:1]
	s_waitcnt vmcnt(7)
	v_lshlrev_b32_e32 v4, 16, v240
	v_and_b32_e32 v5, 0xffff0000, v240
	v_lshlrev_b32_e32 v2, 16, v241
	v_and_b32_e32 v3, 0xffff0000, v241
	v_pk_add_f32 v[4:5], v[12:13], v[4:5]
	v_pk_add_f32 v[2:3], v[14:15], v[2:3]
	v_mov_b32_e32 v8, v5
	v_mov_b32_e32 v9, v3
	v_mov_b32_e32 v6, v4
	v_mov_b32_e32 v7, v2
	v_pk_mul_f32 v[8:9], v[8:9], v[8:9]
	s_nop 0
	v_pk_fma_f32 v[6:7], v[6:7], v[6:7], v[8:9]
	s_nop 0
	v_pk_add_f32 v[6:7], v[6:7], v[6:7] op_sel:[0,1] op_sel_hi:[1,0]
	s_nop 0
	v_pk_add_f32 v[114:115], v[0:1], v[6:7]
	v_cvt_pk_bf16_f32 v0, v4, v5
	v_cvt_pk_bf16_f32 v1, v2, v3
	global_store_dwordx2 v[98:99], v[0:1], off offset:112
	v_add_u32_e32 v95, v92, v95
	v_mad_u32_u24 v115, v118, s0, v95
	ds_read_b128 v[0:3], v95 offset:19456
	ds_read_b128 v[4:7], v95 offset:19488
	ds_read_b128 v[8:11], v95 offset:19520
	ds_read_b128 v[12:15], v95 offset:19552
	ds_read_b128 v[16:19], v115 offset:9216
	ds_read_b128 v[20:23], v115 offset:14336
	ds_read_b128 v[106:109], v115 offset:9248
	ds_read_b128 v[110:113], v115 offset:14368
	ds_read_b128 v[118:121], v115 offset:16896
	s_waitcnt lgkmcnt(8)
	v_pk_mul_f32 v[34:35], v[2:3], v[34:35]
	v_pk_mul_f32 v[32:33], v[0:1], v[32:33]
	s_waitcnt lgkmcnt(7)
	v_pk_mul_f32 v[38:39], v[6:7], v[38:39]
	v_pk_mul_f32 v[36:37], v[4:5], v[36:37]
	s_waitcnt lgkmcnt(6)
	v_pk_mul_f32 v[42:43], v[10:11], v[42:43]
	v_pk_mul_f32 v[40:41], v[8:9], v[40:41]
	s_waitcnt lgkmcnt(5)
	v_pk_mul_f32 v[46:47], v[14:15], v[46:47]
	v_pk_mul_f32 v[44:45], v[12:13], v[44:45]
	v_pk_mul_f32 v[0:1], v[0:1], v[26:27]
	v_pk_mul_f32 v[2:3], v[2:3], v[28:29]
	v_pk_mul_f32 v[4:5], v[4:5], v[30:31]
	v_pk_mul_f32 v[6:7], v[6:7], v[48:49]
	v_pk_mul_f32 v[8:9], v[8:9], v[24:25]
	v_pk_mul_f32 v[10:11], v[10:11], v[84:85]
	v_pk_mul_f32 v[12:13], v[12:13], v[86:87]
	v_pk_mul_f32 v[14:15], v[14:15], v[96:97]
	s_waitcnt lgkmcnt(3)
	v_mfma_f32_32x32x16_bf16 v[32:47], v[16:19], v[20:23], v[32:47]
	ds_read_b128 v[84:87], v115 offset:16928
	s_movk_i32 s4, 0x50
	s_waitcnt lgkmcnt(1)
	v_mfma_f32_32x32x16_bf16 v[0:15], v[16:19], v[118:121], v[0:15]
	v_mfma_f32_32x32x16_bf16 v[32:47], v[106:109], v[110:113], v[32:47]
	s_waitcnt lgkmcnt(0)
	v_mfma_f32_32x32x16_bf16 v[0:15], v[106:109], v[84:87], v[0:15]
	ds_read_b128 v[16:19], v95 offset:19584
	ds_read_b128 v[24:27], v95 offset:19616
	ds_read_b128 v[28:31], v95 offset:19648
	ds_read_b128 v[106:109], v95 offset:19680
	ds_read_b128 v[122:125], v115 offset:11776
	s_waitcnt lgkmcnt(4)
	v_pk_mul_f32 v[50:51], v[18:19], v[50:51]
	v_pk_mul_f32 v[48:49], v[16:17], v[54:55]
	s_waitcnt lgkmcnt(3)
	v_pk_mul_f32 v[54:55], v[26:27], v[82:83]
	v_pk_mul_f32 v[52:53], v[24:25], v[52:53]
	s_waitcnt lgkmcnt(2)
	v_pk_mul_f32 v[58:59], v[30:31], v[58:59]
	v_pk_mul_f32 v[56:57], v[28:29], v[56:57]
	s_waitcnt lgkmcnt(1)
	v_pk_mul_f32 v[62:63], v[108:109], v[62:63]
	v_pk_mul_f32 v[60:61], v[106:107], v[60:61]
	ds_read_b128 v[126:129], v115 offset:11808
	v_pk_mul_f32 v[16:17], v[16:17], v[66:67]
	s_waitcnt lgkmcnt(1)
	v_mfma_f32_32x32x16_bf16 v[48:63], v[122:125], v[20:23], v[48:63]
	v_mul_f32_e64 v18, v18, v68
	v_mul_f32_e64 v19, v19, v69
	v_mul_f32_e64 v20, v24, v70
	v_mul_f32_e64 v21, v25, v71
	v_mul_f32_e64 v22, v26, v72
	v_mul_f32_e64 v23, v27, v73
	v_pk_mul_f32 v[24:25], v[28:29], v[74:75]
	v_pk_mul_f32 v[26:27], v[30:31], v[76:77]
	v_pk_mul_f32 v[28:29], v[106:107], v[78:79]
	v_pk_mul_f32 v[30:31], v[108:109], v[80:81]
	s_waitcnt lgkmcnt(0)
	s_waitcnt lgkmcnt(0)
	v_mfma_f32_32x32x16_bf16 v[48:63], v[126:129], v[110:113], v[48:63]
	v_mfma_f32_32x32x16_bf16 v[16:31], v[122:125], v[118:121], v[16:31]
	v_mfma_f32_32x32x16_bf16 v[16:31], v[126:129], v[84:87], v[16:31]
	v_mad_i64_i32 v[64:65], s[2:3], v88, s1, v[64:65]
	v_lshl_add_u64 v[64:65], v[64:65], 0, v[90:91]
	v_lshl_add_u64 v[64:65], v[64:65], 0, v[102:103]
	s_mov_b64 s[48:49], 0x1000
	s_movk_i32 s5, 0x1000
	v_lshl_add_u64 v[72:73], v[64:65], 0, s[48:49]
	v_add_co_u32_e32 v64, vcc, s5, v64
	global_load_dwordx2 v[74:75], v[104:105], off offset:1536
	s_nop 0
	v_addc_co_u32_e32 v65, vcc, 0, v65, vcc
	global_load_dwordx2 v[76:77], v[64:65], off
	v_readlane_b32 s0, v255, 18
	v_readlane_b32 s1, v255, 19
	s_add_u32 s2, s40, s0
	v_mov_b32_e32 v66, v114
	s_addc_u32 s3, s41, s1
	s_nop 0
	v_permlane32_swap_b32_e32 v114, v66
	v_lshl_add_u64 v[64:65], v[100:101], 2, s[2:3]
	s_mov_b64 s[2:3], 0x4800
	v_add_f32_e32 v66, v114, v66
	v_lshl_add_u64 v[70:71], v[64:65], 0, s[2:3]
	v_add_co_u32_e32 v64, vcc, s7, v64
	v_fmamk_f32 v66, v66, 0x3c800000, v237
	s_nop 0
	v_addc_co_u32_e32 v65, vcc, 0, v65, vcc
	v_rsq_f32_e32 v68, v66
	global_load_dwordx4 v[64:67], v[64:65], off offset:2048
	global_load_dwordx4 v[206:209], v[70:71], off offset:32
	global_load_dwordx2 v[210:211], v[72:73], off offset:16
	global_load_dwordx2 v[212:213], v[98:99], off offset:16
	global_load_dwordx4 v[214:217], v[70:71], off offset:64
	global_load_dwordx2 v[218:219], v[72:73], off offset:32
	global_load_dwordx2 v[220:221], v[98:99], off offset:32
	global_load_dwordx4 v[222:225], v[70:71], off offset:96
	global_load_dwordx2 v[226:227], v[72:73], off offset:48
	global_load_dwordx2 v[228:229], v[98:99], off offset:48
	s_movk_i32 s6, 0x1200
	s_waitcnt vmcnt(11)
	v_lshlrev_b32_e32 v82, 16, v74
	v_and_b32_e32 v83, 0xffff0000, v74
	v_lshlrev_b32_e32 v74, 16, v75
	s_waitcnt vmcnt(10)
	v_lshlrev_b32_e32 v78, 16, v76
	v_mul_f32_e32 v69, 0xbfb8aa3b, v78
	v_exp_f32_e32 v69, v69
	v_and_b32_e32 v79, 0xffff0000, v76
	v_lshlrev_b32_e32 v76, 16, v77
	v_and_b32_e32 v77, 0xffff0000, v77
	v_add_f32_e32 v69, 1.0, v69
	v_rcp_f32_e32 v80, v69
	v_mul_f32_e32 v69, 0xbfb8aa3b, v79
	v_exp_f32_e32 v69, v69
	v_and_b32_e32 v75, 0xffff0000, v75
	v_add_f32_e32 v69, 1.0, v69
	v_rcp_f32_e32 v81, v69
	v_pk_mul_f32 v[82:83], v[68:69], v[82:83] op_sel_hi:[0,1]
	v_pk_mul_f32 v[74:75], v[68:69], v[74:75] op_sel_hi:[0,1]
	s_waitcnt vmcnt(9)
	v_pk_mul_f32 v[64:65], v[64:65], v[82:83]
	v_pk_mul_f32 v[78:79], v[80:81], v[78:79]
	v_pk_mul_f32 v[66:67], v[66:67], v[74:75]
	v_pk_mul_f32 v[64:65], v[64:65], v[78:79]
	s_nop 0
	v_cvt_pk_bf16_f32 v64, v64, v65
	v_mul_f32_e32 v65, 0xbfb8aa3b, v76
	v_exp_f32_e32 v65, v65
	s_nop 0
	v_add_f32_e32 v65, 1.0, v65
	v_rcp_f32_e32 v78, v65
	v_mul_f32_e32 v65, 0xbfb8aa3b, v77
	v_exp_f32_e32 v65, v65
	s_nop 0
	v_add_f32_e32 v65, 1.0, v65
	v_rcp_f32_e32 v79, v65
	s_nop 0
	v_pk_mul_f32 v[74:75], v[78:79], v[76:77]
	s_nop 0
	v_pk_mul_f32 v[66:67], v[66:67], v[74:75]
	s_nop 0
	v_cvt_pk_bf16_f32 v65, v66, v67
	global_store_dwordx2 v[104:105], v[64:65], off offset:1536
	s_nop 0
	s_waitcnt vmcnt(8)
	v_lshlrev_b32_e32 v78, 16, v210
	v_mul_f32_e32 v69, 0xbfb8aa3b, v78
	v_exp_f32_e32 v69, v69
	v_and_b32_e32 v79, 0xffff0000, v210
	s_waitcnt vmcnt(7)
	v_lshlrev_b32_e32 v82, 16, v212
	v_and_b32_e32 v83, 0xffff0000, v212
	v_add_f32_e32 v69, 1.0, v69
	v_rcp_f32_e32 v80, v69
	v_mul_f32_e32 v69, 0xbfb8aa3b, v79
	v_exp_f32_e32 v69, v69
	v_lshlrev_b32_e32 v74, 16, v211
	v_and_b32_e32 v75, 0xffff0000, v211
	v_lshlrev_b32_e32 v76, 16, v213
	v_add_f32_e32 v69, 1.0, v69
	v_rcp_f32_e32 v81, v69
	v_pk_mul_f32 v[82:83], v[68:69], v[82:83] op_sel_hi:[0,1]
	v_pk_mul_f32 v[64:65], v[206:207], v[82:83]
	v_and_b32_e32 v77, 0xffff0000, v213
	v_pk_mul_f32 v[78:79], v[80:81], v[78:79]
	v_pk_mul_f32 v[76:77], v[68:69], v[76:77] op_sel_hi:[0,1]
	v_pk_mul_f32 v[64:65], v[64:65], v[78:79]
	v_pk_mul_f32 v[66:67], v[208:209], v[76:77]
	v_cvt_pk_bf16_f32 v64, v64, v65
	v_mul_f32_e32 v65, 0xbfb8aa3b, v74
	v_exp_f32_e32 v65, v65
	s_nop 0
	v_add_f32_e32 v65, 1.0, v65
	v_rcp_f32_e32 v78, v65
	v_mul_f32_e32 v65, 0xbfb8aa3b, v75
	v_exp_f32_e32 v65, v65
	s_nop 0
	v_add_f32_e32 v65, 1.0, v65
	v_rcp_f32_e32 v79, v65
	s_nop 0
	v_pk_mul_f32 v[74:75], v[78:79], v[74:75]
	s_nop 0
	v_pk_mul_f32 v[66:67], v[66:67], v[74:75]
	s_nop 0
	v_cvt_pk_bf16_f32 v65, v66, v67
	global_store_dwordx2 v[98:99], v[64:65], off offset:16
	s_nop 0
	s_waitcnt vmcnt(6)
	v_lshlrev_b32_e32 v78, 16, v218
	v_mul_f32_e32 v69, 0xbfb8aa3b, v78
	v_exp_f32_e32 v69, v69
	v_and_b32_e32 v79, 0xffff0000, v218
	s_waitcnt vmcnt(5)
	v_lshlrev_b32_e32 v82, 16, v220
	v_and_b32_e32 v83, 0xffff0000, v220
	v_add_f32_e32 v69, 1.0, v69
	v_rcp_f32_e32 v80, v69
	v_mul_f32_e32 v69, 0xbfb8aa3b, v79
	v_exp_f32_e32 v69, v69
	v_lshlrev_b32_e32 v74, 16, v219
	v_and_b32_e32 v75, 0xffff0000, v219
	v_lshlrev_b32_e32 v76, 16, v221
	v_add_f32_e32 v69, 1.0, v69
	v_rcp_f32_e32 v81, v69
	v_pk_mul_f32 v[82:83], v[68:69], v[82:83] op_sel_hi:[0,1]
	v_pk_mul_f32 v[64:65], v[214:215], v[82:83]
	v_and_b32_e32 v77, 0xffff0000, v221
	v_pk_mul_f32 v[78:79], v[80:81], v[78:79]
	v_pk_mul_f32 v[76:77], v[68:69], v[76:77] op_sel_hi:[0,1]
	v_pk_mul_f32 v[64:65], v[64:65], v[78:79]
	v_pk_mul_f32 v[66:67], v[216:217], v[76:77]
	v_cvt_pk_bf16_f32 v64, v64, v65
	v_mul_f32_e32 v65, 0xbfb8aa3b, v74
	v_exp_f32_e32 v65, v65
	s_nop 0
	v_add_f32_e32 v65, 1.0, v65
	v_rcp_f32_e32 v78, v65
	v_mul_f32_e32 v65, 0xbfb8aa3b, v75
	v_exp_f32_e32 v65, v65
	s_nop 0
	v_add_f32_e32 v65, 1.0, v65
	v_rcp_f32_e32 v79, v65
	s_nop 0
	v_pk_mul_f32 v[74:75], v[78:79], v[74:75]
	s_nop 0
	v_pk_mul_f32 v[66:67], v[66:67], v[74:75]
	s_nop 0
	v_cvt_pk_bf16_f32 v65, v66, v67
	global_store_dwordx2 v[98:99], v[64:65], off offset:32
	s_nop 0
	s_waitcnt vmcnt(4)
	v_lshlrev_b32_e32 v78, 16, v226
	v_mul_f32_e32 v69, 0xbfb8aa3b, v78
	v_exp_f32_e32 v69, v69
	v_and_b32_e32 v79, 0xffff0000, v226
	s_waitcnt vmcnt(3)
	v_lshlrev_b32_e32 v82, 16, v228
	v_and_b32_e32 v83, 0xffff0000, v228
	v_add_f32_e32 v69, 1.0, v69
	v_rcp_f32_e32 v80, v69
	v_mul_f32_e32 v69, 0xbfb8aa3b, v79
	v_exp_f32_e32 v69, v69
	v_lshlrev_b32_e32 v74, 16, v227
	v_and_b32_e32 v75, 0xffff0000, v227
	v_lshlrev_b32_e32 v76, 16, v229
	v_add_f32_e32 v69, 1.0, v69
	v_rcp_f32_e32 v81, v69
	v_pk_mul_f32 v[82:83], v[68:69], v[82:83] op_sel_hi:[0,1]
	v_pk_mul_f32 v[64:65], v[222:223], v[82:83]
	v_and_b32_e32 v77, 0xffff0000, v229
	v_pk_mul_f32 v[78:79], v[80:81], v[78:79]
	v_pk_mul_f32 v[76:77], v[68:69], v[76:77] op_sel_hi:[0,1]
	v_pk_mul_f32 v[64:65], v[64:65], v[78:79]
	v_pk_mul_f32 v[66:67], v[224:225], v[76:77]
	v_cvt_pk_bf16_f32 v64, v64, v65
	v_mul_f32_e32 v65, 0xbfb8aa3b, v74
	v_exp_f32_e32 v65, v65
	s_nop 0
	v_add_f32_e32 v65, 1.0, v65
	v_rcp_f32_e32 v78, v65
	v_mul_f32_e32 v65, 0xbfb8aa3b, v75
	v_exp_f32_e32 v65, v65
	s_nop 0
	v_add_f32_e32 v65, 1.0, v65
	v_rcp_f32_e32 v79, v65
	s_nop 0
	v_pk_mul_f32 v[74:75], v[78:79], v[74:75]
	s_nop 0
	v_pk_mul_f32 v[66:67], v[66:67], v[74:75]
	s_nop 0
	v_cvt_pk_bf16_f32 v65, v66, v67
	global_store_dwordx2 v[98:99], v[64:65], off offset:48
	global_load_dwordx2 v[74:75], v[98:99], off offset:64
	global_load_dwordx2 v[76:77], v[72:73], off offset:64
	global_load_dwordx4 v[64:67], v[70:71], off offset:128
	global_load_dwordx2 v[212:213], v[98:99], off offset:80
	global_load_dwordx2 v[210:211], v[72:73], off offset:80
	global_load_dwordx4 v[206:209], v[70:71], off offset:160
	global_load_dwordx2 v[220:221], v[98:99], off offset:96
	global_load_dwordx2 v[218:219], v[72:73], off offset:96
	global_load_dwordx4 v[214:217], v[70:71], off offset:192
	global_load_dwordx2 v[228:229], v[98:99], off offset:112
	global_load_dwordx2 v[226:227], v[72:73], off offset:112
	global_load_dwordx4 v[222:225], v[70:71], off offset:224
	s_waitcnt vmcnt(11)
	v_lshlrev_b32_e32 v82, 16, v74
	s_waitcnt vmcnt(10)
	v_lshlrev_b32_e32 v78, 16, v76
	v_mul_f32_e32 v69, 0xbfb8aa3b, v78
	v_exp_f32_e32 v69, v69
	v_and_b32_e32 v79, 0xffff0000, v76
	v_and_b32_e32 v83, 0xffff0000, v74
	v_lshlrev_b32_e32 v76, 16, v77
	v_add_f32_e32 v69, 1.0, v69
	v_rcp_f32_e32 v80, v69
	v_mul_f32_e32 v69, 0xbfb8aa3b, v79
	v_exp_f32_e32 v69, v69
	v_and_b32_e32 v77, 0xffff0000, v77
	v_lshlrev_b32_e32 v74, 16, v75
	v_and_b32_e32 v75, 0xffff0000, v75
	v_add_f32_e32 v69, 1.0, v69
	v_rcp_f32_e32 v81, v69
	v_pk_mul_f32 v[82:83], v[68:69], v[82:83] op_sel_hi:[0,1]
	s_waitcnt vmcnt(9)
	v_pk_mul_f32 v[64:65], v[64:65], v[82:83]
	v_pk_mul_f32 v[74:75], v[68:69], v[74:75] op_sel_hi:[0,1]
	v_pk_mul_f32 v[78:79], v[80:81], v[78:79]
	v_pk_mul_f32 v[66:67], v[66:67], v[74:75]
	v_pk_mul_f32 v[64:65], v[64:65], v[78:79]
	s_nop 0
	v_cvt_pk_bf16_f32 v64, v64, v65
	v_mul_f32_e32 v65, 0xbfb8aa3b, v76
	v_exp_f32_e32 v65, v65
	s_nop 0
	v_add_f32_e32 v65, 1.0, v65
	v_rcp_f32_e32 v78, v65
	v_mul_f32_e32 v65, 0xbfb8aa3b, v77
	v_exp_f32_e32 v65, v65
	s_nop 0
	v_add_f32_e32 v65, 1.0, v65
	v_rcp_f32_e32 v79, v65
	s_nop 0
	v_pk_mul_f32 v[74:75], v[78:79], v[76:77]
	s_nop 0
	v_pk_mul_f32 v[66:67], v[66:67], v[74:75]
	s_nop 0
	v_cvt_pk_bf16_f32 v65, v66, v67
	global_store_dwordx2 v[98:99], v[64:65], off offset:64
	s_nop 0
	s_waitcnt vmcnt(9)
	v_lshlrev_b32_e32 v82, 16, v212
	s_waitcnt vmcnt(8)
	v_lshlrev_b32_e32 v78, 16, v210
	v_mul_f32_e32 v69, 0xbfb8aa3b, v78
	v_exp_f32_e32 v69, v69
	v_and_b32_e32 v79, 0xffff0000, v210
	v_and_b32_e32 v83, 0xffff0000, v212
	v_lshlrev_b32_e32 v76, 16, v211
	v_add_f32_e32 v69, 1.0, v69
	v_rcp_f32_e32 v80, v69
	v_mul_f32_e32 v69, 0xbfb8aa3b, v79
	v_exp_f32_e32 v69, v69
	v_and_b32_e32 v77, 0xffff0000, v211
	v_lshlrev_b32_e32 v74, 16, v213
	v_and_b32_e32 v75, 0xffff0000, v213
	v_add_f32_e32 v69, 1.0, v69
	v_rcp_f32_e32 v81, v69
	v_pk_mul_f32 v[82:83], v[68:69], v[82:83] op_sel_hi:[0,1]
	s_waitcnt vmcnt(7)
	v_pk_mul_f32 v[64:65], v[206:207], v[82:83]
	v_pk_mul_f32 v[74:75], v[68:69], v[74:75] op_sel_hi:[0,1]
	v_pk_mul_f32 v[78:79], v[80:81], v[78:79]
	v_pk_mul_f32 v[66:67], v[208:209], v[74:75]
	v_pk_mul_f32 v[64:65], v[64:65], v[78:79]
	s_nop 0
	v_cvt_pk_bf16_f32 v64, v64, v65
	v_mul_f32_e32 v65, 0xbfb8aa3b, v76
	v_exp_f32_e32 v65, v65
	s_nop 0
	v_add_f32_e32 v65, 1.0, v65
	v_rcp_f32_e32 v78, v65
	v_mul_f32_e32 v65, 0xbfb8aa3b, v77
	v_exp_f32_e32 v65, v65
	s_nop 0
	v_add_f32_e32 v65, 1.0, v65
	v_rcp_f32_e32 v79, v65
	s_nop 0
	v_pk_mul_f32 v[74:75], v[78:79], v[76:77]
	s_nop 0
	v_pk_mul_f32 v[66:67], v[66:67], v[74:75]
	s_nop 0
	v_cvt_pk_bf16_f32 v65, v66, v67
	global_store_dwordx2 v[98:99], v[64:65], off offset:80
	s_nop 0
	s_waitcnt vmcnt(7)
	v_lshlrev_b32_e32 v82, 16, v220
	s_waitcnt vmcnt(6)
	v_lshlrev_b32_e32 v78, 16, v218
	v_mul_f32_e32 v69, 0xbfb8aa3b, v78
	v_exp_f32_e32 v69, v69
	v_and_b32_e32 v79, 0xffff0000, v218
	v_and_b32_e32 v83, 0xffff0000, v220
	v_lshlrev_b32_e32 v76, 16, v219
	v_add_f32_e32 v69, 1.0, v69
	v_rcp_f32_e32 v80, v69
	v_mul_f32_e32 v69, 0xbfb8aa3b, v79
	v_exp_f32_e32 v69, v69
	v_and_b32_e32 v77, 0xffff0000, v219
	v_lshlrev_b32_e32 v74, 16, v221
	v_and_b32_e32 v75, 0xffff0000, v221
	v_add_f32_e32 v69, 1.0, v69
	v_rcp_f32_e32 v81, v69
	v_pk_mul_f32 v[82:83], v[68:69], v[82:83] op_sel_hi:[0,1]
	s_waitcnt vmcnt(5)
	v_pk_mul_f32 v[64:65], v[214:215], v[82:83]
	v_pk_mul_f32 v[74:75], v[68:69], v[74:75] op_sel_hi:[0,1]
	v_pk_mul_f32 v[78:79], v[80:81], v[78:79]
	v_pk_mul_f32 v[66:67], v[216:217], v[74:75]
	v_pk_mul_f32 v[64:65], v[64:65], v[78:79]
	s_nop 0
	v_cvt_pk_bf16_f32 v64, v64, v65
	v_mul_f32_e32 v65, 0xbfb8aa3b, v76
	v_exp_f32_e32 v65, v65
	s_nop 0
	v_add_f32_e32 v65, 1.0, v65
	v_rcp_f32_e32 v78, v65
	v_mul_f32_e32 v65, 0xbfb8aa3b, v77
	v_exp_f32_e32 v65, v65
	s_nop 0
	v_add_f32_e32 v65, 1.0, v65
	v_rcp_f32_e32 v79, v65
	s_nop 0
	v_pk_mul_f32 v[74:75], v[78:79], v[76:77]
	s_nop 0
	v_pk_mul_f32 v[66:67], v[66:67], v[74:75]
	s_nop 0
	v_cvt_pk_bf16_f32 v65, v66, v67
	global_store_dwordx2 v[98:99], v[64:65], off offset:96
	s_nop 0
	s_nop 0
	s_waitcnt vmcnt(5)
	v_lshlrev_b32_e32 v78, 16, v228
	s_waitcnt vmcnt(4)
	v_lshlrev_b32_e32 v74, 16, v226
	v_mul_f32_e32 v69, 0xbfb8aa3b, v74
	v_exp_f32_e32 v69, v69
	v_and_b32_e32 v75, 0xffff0000, v226
	v_lshlrev_b32_e32 v66, 16, v227
	v_and_b32_e32 v79, 0xffff0000, v228
	v_add_f32_e32 v69, 1.0, v69
	v_rcp_f32_e32 v76, v69
	v_mul_f32_e32 v69, 0xbfb8aa3b, v75
	v_exp_f32_e32 v69, v69
	v_and_b32_e32 v67, 0xffff0000, v227
	v_add_f32_e32 v69, 1.0, v69
	v_rcp_f32_e32 v77, v69
	v_pk_mul_f32 v[78:79], v[68:69], v[78:79] op_sel_hi:[0,1]
	v_mul_f32_e32 v69, 0xbfb8aa3b, v66
	v_exp_f32_e32 v69, v69
	s_waitcnt vmcnt(3)
	v_pk_mul_f32 v[70:71], v[222:223], v[78:79]
	v_pk_mul_f32 v[74:75], v[76:77], v[74:75]
	v_add_f32_e32 v69, 1.0, v69
	v_pk_mul_f32 v[70:71], v[70:71], v[74:75]
	v_lshlrev_b32_e32 v74, 16, v229
	v_cvt_pk_bf16_f32 v64, v70, v71
	v_rcp_f32_e32 v70, v69
	v_mul_f32_e32 v69, 0xbfb8aa3b, v67
	v_exp_f32_e32 v69, v69
	v_and_b32_e32 v75, 0xffff0000, v229
	v_add_f32_e32 v69, 1.0, v69
	v_rcp_f32_e32 v71, v69
	v_pk_mul_f32 v[68:69], v[68:69], v[74:75] op_sel_hi:[0,1]
	v_pk_mul_f32 v[68:69], v[224:225], v[68:69]
	v_pk_mul_f32 v[66:67], v[70:71], v[66:67]
	s_nop 0
	v_pk_mul_f32 v[66:67], v[68:69], v[66:67]
	s_nop 0
	v_cvt_pk_bf16_f32 v65, v66, v67
	global_store_dwordx2 v[98:99], v[64:65], off offset:112
	s_add_u32 s2, s12, 0xb200000
	v_and_b32_e32 v114, 31, v94
	v_ashrrev_i32_e32 v115, 5, v94
	s_addc_u32 s3, s13, 0
	v_mov_b64_e32 v[96:97], s[2:3]
	v_mad_i64_i32 v[64:65], s[2:3], v93, s6, v[96:97]
	v_ashrrev_i32_e32 v95, 31, v94
	v_lshl_add_u64 v[64:65], v[64:65], 0, v[90:91]
	v_lshl_add_u64 v[64:65], v[94:95], 1, v[64:65]
	v_add_co_u32_e32 v76, vcc, s37, v64
	s_movk_i32 s2, 0x5000
	s_nop 0
	v_addc_co_u32_e32 v77, vcc, 0, v65, vcc
	global_load_ushort v95, v[76:77], off offset:3072
	global_load_ushort v107, v[76:77], off offset:1536
	v_add_co_u32_e32 v66, vcc, s20, v64
	v_lshl_add_u32 v88, v94, 1, v92
	s_nop 0
	v_addc_co_u32_e32 v67, vcc, 0, v65, vcc
	v_add_co_u32_e32 v68, vcc, s2, v64
	s_movk_i32 s2, 0x7000
	s_nop 0
	v_addc_co_u32_e32 v69, vcc, 0, v65, vcc
	v_add_co_u32_e32 v70, vcc, s2, v64
	s_mov_b32 s2, 0x10000
	s_nop 0
	v_addc_co_u32_e32 v71, vcc, 0, v65, vcc
	v_add_co_u32_e32 v80, vcc, s28, v64
	s_waitcnt vmcnt(0)
	v_lshlrev_b32_e32 v107, 16, v107
	v_addc_co_u32_e32 v81, vcc, 0, v65, vcc
	v_add_co_u32_e32 v82, vcc, s29, v64
	v_readlane_b32 s28, v255, 28
	s_nop 0
	v_addc_co_u32_e32 v83, vcc, 0, v65, vcc
	v_add_co_u32_e32 v84, vcc, s18, v64
	v_readlane_b32 s29, v255, 29
	s_nop 0
	v_addc_co_u32_e32 v85, vcc, 0, v65, vcc
	v_add_co_u32_e32 v86, vcc, s2, v64
	s_mov_b32 s2, 0x14000
	s_nop 0
	v_addc_co_u32_e32 v87, vcc, 0, v65, vcc
	v_add_co_u32_e32 v72, vcc, s51, v64
	s_nop 1
	v_addc_co_u32_e32 v73, vcc, 0, v65, vcc
	v_add_co_u32_e32 v74, vcc, s2, v64
	s_mov_b32 s2, 0x1a000
	s_nop 0
	v_addc_co_u32_e32 v75, vcc, 0, v65, vcc
	v_add_co_u32_e32 v78, vcc, s30, v64
	s_nop 1
	v_addc_co_u32_e32 v79, vcc, 0, v65, vcc
	v_add_co_u32_e32 v98, vcc, s31, v64
	s_mov_b64 s[30:31], 0x4800
	s_nop 0
	v_addc_co_u32_e32 v99, vcc, 0, v65, vcc
	v_add_co_u32_e32 v100, vcc, s34, v64
	s_nop 1
	v_addc_co_u32_e32 v101, vcc, 0, v65, vcc
	v_add_co_u32_e32 v102, vcc, s35, v64
	s_mov_b64 s[34:35], 0x1200
	s_nop 0
	v_addc_co_u32_e32 v103, vcc, 0, v65, vcc
	v_add_co_u32_e32 v104, vcc, s19, v64
	v_readlane_b32 s18, v255, 26
	s_nop 0
	v_addc_co_u32_e32 v105, vcc, 0, v65, vcc
	v_add_co_u32_e32 v118, vcc, s36, v64
	v_readlane_b32 s36, v255, 30
	s_nop 0
	v_addc_co_u32_e32 v119, vcc, 0, v65, vcc
	v_add_co_u32_e32 v108, vcc, s21, v64
	v_readlane_b32 s19, v255, 27
	s_nop 0
	v_addc_co_u32_e32 v109, vcc, 0, v65, vcc
	global_load_ushort v111, v[108:109], off offset:512
	global_load_ushort v106, v[108:109], off offset:1024
	global_load_ushort v113, v[108:109], off offset:2048
	s_nop 0
	global_load_ushort v108, v[76:77], off offset:2048
	global_load_ushort v110, v[118:119], off offset:1536
	global_load_ushort v120, v[118:119], off offset:2560
	global_load_ushort v121, v[102:103], off offset:3584
	global_load_ushort v122, v[104:105], off offset:512
	global_load_ushort v152, v[118:119], off offset:1024
	global_load_ushort v153, v[104:105], off offset:1536
	global_load_ushort v154, v[104:105], off
	global_load_ushort v158, v[102:103], off offset:3072
	global_load_ushort v160, v[102:103], off
	global_load_ushort v165, v[100:101], off offset:3584
	v_lshlrev_b32_e32 v76, 16, v95
	v_max_f32_e32 v76, v76, v76
	v_med3_f32 v76, v76, s9, v244
	v_mul_f32_e32 v76, 0xbfb8aa3b, v76
	v_exp_f32_e32 v95, v76
	v_add_co_u32_e32 v76, vcc, s42, v64
	global_load_ushort v123, v[78:79], off offset:512
	global_load_ushort v124, v[98:99], off offset:1536
	global_load_ushort v126, v[100:101], off offset:2560
	global_load_ushort v166, v[100:101], off offset:2048
	global_load_ushort v168, v[98:99], off offset:2560
	global_load_ushort v171, v[98:99], off offset:1024
	global_load_ushort v167, v[78:79], off offset:1536
	global_load_ushort v163, v[78:79], off
	v_add_f32_e32 v109, 1.0, v95
	v_addc_co_u32_e32 v77, vcc, 0, v65, vcc
	v_rcp_f32_e32 v109, v109
	v_add_co_u32_e32 v134, vcc, s17, v64
	v_readlane_b32 s37, v255, 31
	s_nop 0
	v_addc_co_u32_e32 v135, vcc, 0, v65, vcc
	v_add_co_u32_e32 v132, vcc, s16, v64
	v_fma_f32 v112, v117, v109, v116
	s_nop 0
	v_addc_co_u32_e32 v133, vcc, 0, v65, vcc
	v_max_f32_e32 v150, 0xda24260, v112
	v_add_co_u32_e32 v118, vcc, s2, v64
	v_mul_f32_e32 v95, v95, v109
	v_rcp_f32_e32 v109, v150
	v_addc_co_u32_e32 v119, vcc, 0, v65, vcc
	s_mov_b32 s2, 0x18000
	v_add_co_u32_e32 v136, vcc, s2, v64
	s_mov_b32 s2, 0x16000
	s_nop 0
	v_addc_co_u32_e32 v137, vcc, 0, v65, vcc
	v_mul_f32_e32 v95, v117, v95
	v_mul_f32_e32 v107, v150, v107
	v_add_co_u32_e32 v78, vcc, s2, v64
	v_bfe_u32 v112, v107, 16, 1
	v_mul_f32_e32 v95, v95, v109
	v_addc_co_u32_e32 v79, vcc, 0, v65, vcc
	v_add3_u32 v151, v107, v112, s10
	v_bfe_u32 v107, v95, 16, 1
	v_add_co_u32_e32 v138, vcc, s43, v64
	v_add3_u32 v112, v95, v107, s10
	s_nop 0
	v_addc_co_u32_e32 v139, vcc, 0, v65, vcc
	global_load_ushort v125, v[84:85], off offset:512
	global_load_ushort v127, v[86:87], off offset:1536
	global_load_ushort v128, v[72:73], off offset:2560
	global_load_ushort v129, v[74:75], off offset:3584
	global_load_ushort v157, v[74:75], off offset:3072
	global_load_ushort v155, v[74:75], off
	global_load_ushort v109, v[72:73], off offset:3584
	global_load_ushort v107, v[72:73], off offset:2048
	global_load_ushort v172, v[76:77], off offset:1024
	global_load_ushort v173, v[134:135], off offset:3584
	global_load_ushort v174, v[132:133], off offset:2560
	global_load_ushort v175, v[118:119], off offset:1536
	global_load_ushort v131, v[118:119], off offset:2048
	s_nop 0
	global_load_ushort v132, v[132:133], off offset:3072
	s_nop 0
	global_load_ushort v176, v[134:135], off offset:512
	global_load_ushort v133, v[76:77], off
	global_load_ushort v177, v[118:119], off offset:3072
	global_load_ushort v170, v[136:137], off offset:2048
	global_load_ushort v169, v[136:137], off offset:512
	global_load_ushort v164, v[78:79], off offset:1024
	global_load_ushort v162, v[138:139], off offset:3584
	global_load_ushort v159, v[138:139], off offset:512
	global_load_ushort v135, v[78:79], off
	s_nop 0
	global_load_ushort v137, v[136:137], off offset:1024
	v_add_co_u32_e32 v144, vcc, s44, v64
	global_load_ushort v130, v[64:65], off offset:2560
	global_load_ushort v134, v[66:67], off offset:3584
	global_load_ushort v136, v[68:69], off offset:512
	global_load_ushort v138, v[70:71], off offset:1536
	global_load_ushort v139, v[80:81], off offset:2560
	global_load_ushort v141, v[82:83], off offset:3584
	global_load_ushort v142, v[84:85], off offset:-4096
	global_load_ushort v140, v[68:69], off offset:-4096
	v_addc_co_u32_e32 v145, vcc, 0, v65, vcc
	v_add_co_u32_e32 v100, vcc, s45, v64
	v_readlane_b32 s42, v255, 32
	s_nop 0
	v_addc_co_u32_e32 v101, vcc, 0, v65, vcc
	v_add_co_u32_e32 v102, vcc, s46, v64
	v_readlane_b32 s43, v255, 33
	s_nop 0
	v_addc_co_u32_e32 v103, vcc, 0, v65, vcc
	v_add_co_u32_e32 v104, vcc, s47, v64
	v_readlane_b32 s46, v255, 38
	s_nop 0
	v_addc_co_u32_e32 v105, vcc, 0, v65, vcc
	v_add_co_u32_e32 v98, vcc, s15, v64
	s_waitcnt vmcnt(53)
	v_lshlrev_b32_e32 v111, 16, v111
	v_addc_co_u32_e32 v99, vcc, 0, v65, vcc
	s_waitcnt vmcnt(51)
	v_lshlrev_b32_e32 v113, 16, v113
	s_waitcnt vmcnt(48)
	v_lshlrev_b32_e32 v72, 16, v120
	v_max_f32_e32 v72, v72, v72
	v_med3_f32 v72, v72, s9, v244
	v_mul_f32_e32 v72, 0xbfb8aa3b, v72
	v_exp_f32_e32 v95, v72
	v_add_co_u32_e32 v74, vcc, s14, v64
	v_max_f32_e32 v113, v113, v113
	v_add_f32_e32 v118, 1.0, v95
	v_rcp_f32_e32 v118, v118
	v_addc_co_u32_e32 v75, vcc, 0, v65, vcc
	v_med3_f32 v113, v113, s9, v244
	v_fma_f32 v119, v117, v118, v116
	v_mul_f32_e32 v119, v150, v119
	v_max_f32_e32 v119, 0xda24260, v119
	v_add_co_u32_e32 v76, vcc, s27, v64
	v_rcp_f32_e32 v120, v119
	v_mul_f32_e32 v113, 0xbfb8aa3b, v113
	v_addc_co_u32_e32 v77, vcc, 0, v65, vcc
	v_exp_f32_e32 v113, v113
	v_add_co_u32_e32 v78, vcc, s7, v64
	v_mul_f32_e32 v95, v95, v118
	s_nop 0
	v_addc_co_u32_e32 v79, vcc, 0, v65, vcc
	v_mul_f32_e32 v95, v117, v95
	v_add_co_u32_e32 v72, vcc, s5, v64
	v_mul_f32_e32 v95, v95, v120
	s_nop 0
	v_addc_co_u32_e32 v73, vcc, 0, v65, vcc
	global_load_ushort v156, v[144:145], off offset:2560
	global_load_ushort v148, v[144:145], off offset:3072
	global_load_ushort v149, v[100:101], off offset:2048
	global_load_ushort v147, v[102:103], off offset:1024
	global_load_ushort v146, v[98:99], off offset:3072
	s_nop 0
	global_load_ushort v144, v[74:75], off offset:2048
	global_load_ushort v145, v[76:77], off offset:1024
	global_load_ushort v143, v[72:73], off offset:3072
	v_bfe_u32 v118, v95, 16, 1
	v_add_f32_e32 v120, 1.0, v113
	v_add3_u32 v95, v95, v118, s10
	s_waitcnt vmcnt(53)
	v_lshlrev_b32_e32 v118, 16, v152
	v_rcp_f32_e32 v120, v120
	v_mul_f32_e32 v118, v119, v118
	v_bfe_u32 v150, v118, 16, 1
	v_add3_u32 v118, v118, v150, s10
	ds_write_b16_d16_hi v88, v118 offset:4320
	v_fma_f32 v118, v117, v120, v116
	v_mul_f32_e32 v118, v119, v118
	v_mul_f32_e32 v113, v113, v120
	s_waitcnt vmcnt(52)
	v_lshlrev_b32_e32 v120, 16, v153
	v_max_f32_e32 v118, 0xda24260, v118
	v_max_f32_e32 v120, v120, v120
	v_rcp_f32_e32 v119, v118
	v_med3_f32 v120, v120, s9, v244
	v_mul_f32_e32 v120, 0xbfb8aa3b, v120
	v_exp_f32_e32 v120, v120
	v_mul_f32_e32 v113, v117, v113
	v_mul_f32_e32 v113, v113, v119
	v_bfe_u32 v119, v113, 16, 1
	ds_write_b16_d16_hi v88, v151 offset:4464
	v_add3_u32 v151, v113, v119, s10
	v_add_f32_e32 v113, 1.0, v120
	v_rcp_f32_e32 v113, v113
	v_mul_f32_e32 v111, v118, v111
	v_bfe_u32 v119, v111, 16, 1
	v_add3_u32 v111, v111, v119, s10
	ds_write_b16_d16_hi v88, v111 offset:4176
	v_fma_f32 v111, v117, v113, v116
	s_waitcnt vmcnt(31)
	v_lshlrev_b32_e32 v119, 16, v172
	v_mul_f32_e32 v111, v118, v111
	v_max_f32_e32 v119, v119, v119
	v_max_f32_e32 v111, 0xda24260, v111
	v_med3_f32 v119, v119, s9, v244
	v_rcp_f32_e32 v118, v111
	v_mul_f32_e32 v119, 0xbfb8aa3b, v119
	v_exp_f32_e32 v119, v119
	v_mul_f32_e32 v113, v120, v113
	v_mul_f32_e32 v113, v117, v113
	v_mul_f32_e32 v113, v113, v118
	v_bfe_u32 v118, v113, 16, 1
	v_add_f32_e32 v120, 1.0, v119
	v_add3_u32 v118, v113, v118, s10
	v_lshlrev_b32_e32 v113, 16, v154
	v_rcp_f32_e32 v120, v120
	v_mul_f32_e32 v113, v111, v113
	v_bfe_u32 v150, v113, 16, 1
	v_add3_u32 v113, v113, v150, s10
	ds_write_b16_d16_hi v88, v113 offset:4032
	v_fma_f32 v113, v117, v120, v116
	v_mul_f32_e32 v111, v111, v113
	v_mul_f32_e32 v119, v119, v120
	s_waitcnt vmcnt(25)
	v_lshlrev_b32_e32 v120, 16, v176
	v_max_f32_e32 v111, 0xda24260, v111
	v_max_f32_e32 v120, v120, v120
	v_rcp_f32_e32 v113, v111
	v_med3_f32 v120, v120, s9, v244
	v_mul_f32_e32 v120, 0xbfb8aa3b, v120
	v_exp_f32_e32 v120, v120
	v_mul_f32_e32 v119, v117, v119
	v_mul_f32_e32 v113, v119, v113
	v_bfe_u32 v119, v113, 16, 1
	v_add3_u32 v152, v113, v119, s10
	v_add_f32_e32 v119, 1.0, v120
	v_lshlrev_b32_e32 v113, 16, v173
	v_rcp_f32_e32 v119, v119
	v_mul_f32_e32 v113, v111, v113
	v_bfe_u32 v150, v113, 16, 1
	v_add3_u32 v113, v113, v150, s10
	ds_write_b16_d16_hi v88, v113 offset:3888
	v_fma_f32 v113, v117, v119, v116
	v_mul_f32_e32 v119, v120, v119
	v_lshlrev_b32_e32 v120, 16, v160
	v_mul_f32_e32 v111, v111, v113
	v_max_f32_e32 v120, v120, v120
	v_max_f32_e32 v111, 0xda24260, v111
	v_med3_f32 v120, v120, s9, v244
	v_rcp_f32_e32 v113, v111
	v_mul_f32_e32 v120, 0xbfb8aa3b, v120
	v_exp_f32_e32 v120, v120
	v_mul_f32_e32 v119, v117, v119
	v_mul_f32_e32 v113, v119, v113
	v_bfe_u32 v119, v113, 16, 1
	v_add_f32_e32 v150, 1.0, v120
	v_add3_u32 v119, v113, v119, s10
	v_lshlrev_b32_e32 v113, 16, v158
	v_rcp_f32_e32 v150, v150
	v_mul_f32_e32 v113, v111, v113
	v_bfe_u32 v153, v113, 16, 1
	v_add3_u32 v113, v113, v153, s10
	ds_write_b16_d16_hi v88, v113 offset:3744
	v_fma_f32 v113, v117, v150, v116
	v_mul_f32_e32 v111, v111, v113
	v_mul_f32_e32 v120, v120, v150
	v_lshlrev_b32_e32 v150, 16, v165
	v_max_f32_e32 v111, 0xda24260, v111
	v_max_f32_e32 v150, v150, v150
	v_rcp_f32_e32 v113, v111
	v_med3_f32 v150, v150, s9, v244
	v_mul_f32_e32 v150, 0xbfb8aa3b, v150
	v_exp_f32_e32 v150, v150
	v_mul_f32_e32 v120, v117, v120
	v_mul_f32_e32 v113, v120, v113
	v_bfe_u32 v120, v113, 16, 1
	v_add3_u32 v153, v113, v120, s10
	v_add_f32_e32 v120, 1.0, v150
	v_lshlrev_b32_e32 v113, 16, v174
	v_rcp_f32_e32 v120, v120
	v_mul_f32_e32 v113, v111, v113
	v_bfe_u32 v154, v113, 16, 1
	v_add3_u32 v113, v113, v154, s10
	ds_write_b16_d16_hi v88, v113 offset:3600
	v_fma_f32 v113, v117, v120, v116
	v_mul_f32_e32 v111, v111, v113
	v_max_f32_e32 v111, 0xda24260, v111
	v_rcp_f32_e32 v113, v111
	v_mul_f32_e32 v120, v150, v120
	v_mul_f32_e32 v120, v117, v120
	v_readlane_b32 s47, v255, 39
	v_mul_f32_e32 v113, v120, v113
	v_bfe_u32 v120, v113, 16, 1
	v_add3_u32 v120, v113, v120, s10
	v_lshlrev_b32_e32 v113, 16, v166
	v_mul_f32_e32 v113, v111, v113
	v_bfe_u32 v150, v113, 16, 1
	v_add3_u32 v113, v113, v150, s10
	ds_write_b16_d16_hi v88, v112 offset:9072
	ds_write_b16_d16_hi v88, v95 offset:8928
	ds_write_b16_d16_hi v88, v151 offset:8784
	ds_write_b16_d16_hi v88, v118 offset:8640
	ds_write_b16_d16_hi v88, v152 offset:8496
	ds_write_b16_d16_hi v88, v119 offset:8352
	ds_write_b16_d16_hi v88, v153 offset:8208
	ds_write_b16_d16_hi v88, v113 offset:3456
	ds_write_b16_d16_hi v88, v120 offset:8064
	s_waitcnt vmcnt(23)
	v_lshlrev_b32_e32 v113, 16, v177
	v_max_f32_e32 v113, v113, v113
	v_med3_f32 v113, v113, s9, v244
	v_mul_f32_e32 v113, 0xbfb8aa3b, v113
	v_exp_f32_e32 v113, v113
	v_lshlrev_b32_e32 v107, 16, v107
	v_add_f32_e32 v150, 1.0, v113
	v_rcp_f32_e32 v150, v150
	s_nop 0
	v_fma_f32 v154, v117, v150, v116
	v_mul_f32_e32 v111, v111, v154
	v_max_f32_e32 v111, 0xda24260, v111
	v_mul_f32_e32 v113, v113, v150
	v_rcp_f32_e32 v150, v111
	v_mul_f32_e32 v113, v117, v113
	v_mul_f32_e32 v113, v113, v150
	v_bfe_u32 v150, v113, 16, 1
	v_add3_u32 v154, v113, v150, s10
	v_lshlrev_b32_e32 v113, 16, v175
	v_mul_f32_e32 v113, v111, v113
	v_bfe_u32 v150, v113, 16, 1
	v_add3_u32 v113, v113, v150, s10
	ds_write_b16_d16_hi v88, v113 offset:3312
	ds_write_b16_d16_hi v88, v154 offset:7920
	v_lshlrev_b32_e32 v113, 16, v168
	v_max_f32_e32 v113, v113, v113
	v_med3_f32 v113, v113, s9, v244
	v_mul_f32_e32 v113, 0xbfb8aa3b, v113
	v_exp_f32_e32 v113, v113
	s_nop 0
	v_add_f32_e32 v150, 1.0, v113
	v_rcp_f32_e32 v150, v150
	s_nop 0
	v_fma_f32 v158, v117, v150, v116
	v_mul_f32_e32 v111, v111, v158
	v_max_f32_e32 v172, 0xda24260, v111
	v_rcp_f32_e32 v111, v172
	v_mul_f32_e32 v113, v113, v150
	v_mul_f32_e32 v113, v117, v113
	v_mul_f32_e32 v111, v113, v111
	v_bfe_u32 v113, v111, 16, 1
	v_add3_u32 v150, v111, v113, s10
	v_lshlrev_b32_e32 v111, 16, v171
	v_mul_f32_e32 v111, v172, v111
	v_bfe_u32 v113, v111, 16, 1
	v_add3_u32 v171, v111, v113, s10
	global_load_ushort v168, v[100:101], off offset:3072
	global_load_ushort v166, v[100:101], off offset:1536
	global_load_ushort v165, v[86:87], off offset:2560
	global_load_ushort v160, v[86:87], off offset:1024
	global_load_ushort v158, v[102:103], off offset:2048
	global_load_ushort v113, v[102:103], off offset:512
	global_load_ushort v111, v[84:85], off offset:1536
	s_nop 0
	global_load_ushort v103, v[84:85], off
	global_load_ushort v102, v[104:105], off offset:1024
	v_add_co_u32_e32 v84, vcc, s50, v64
	s_nop 1
	v_addc_co_u32_e32 v85, vcc, 0, v65, vcc
	global_load_ushort v101, v[84:85], off offset:3584
	global_load_ushort v100, v[84:85], off offset:512
	global_load_ushort v87, v[82:83], off offset:3072
	global_load_ushort v86, v[82:83], off
	s_nop 0
	global_load_ushort v83, v[98:99], off offset:2560
	global_load_ushort v82, v[80:81], off offset:3584
	s_nop 0
	global_load_ushort v81, v[80:81], off offset:2048
	s_waitcnt vmcnt(38)
	v_lshlrev_b32_e32 v80, 16, v170
	v_max_f32_e32 v80, v80, v80
	v_med3_f32 v80, v80, s9, v244
	v_mul_f32_e32 v80, 0xbfb8aa3b, v80
	v_exp_f32_e32 v80, v80
	ds_write_b16_d16_hi v88, v171 offset:3168
	ds_write_b16_d16_hi v88, v150 offset:7776
	v_add_f32_e32 v84, 1.0, v80
	v_rcp_f32_e32 v84, v84
	s_nop 0
	v_fma_f32 v85, v117, v84, v116
	v_mul_f32_e32 v80, v80, v84
	v_mul_f32_e32 v84, v172, v85
	v_max_f32_e32 v84, 0xda24260, v84
	v_rcp_f32_e32 v85, v84
	v_mul_f32_e32 v80, v117, v80
	v_mul_f32_e32 v80, v80, v85
	v_bfe_u32 v85, v80, 16, 1
	v_add3_u32 v85, v80, v85, s10
	s_waitcnt vmcnt(37)
	v_lshlrev_b32_e32 v80, 16, v169
	v_mul_f32_e32 v80, v84, v80
	v_bfe_u32 v98, v80, 16, 1
	v_add3_u32 v80, v80, v98, s10
	ds_write_b16_d16_hi v88, v80 offset:3024
	ds_write_b16_d16_hi v88, v85 offset:7632
	v_lshlrev_b32_e32 v80, 16, v167
	v_max_f32_e32 v80, v80, v80
	v_med3_f32 v80, v80, s9, v244
	v_mul_f32_e32 v80, 0xbfb8aa3b, v80
	v_exp_f32_e32 v80, v80
	s_nop 0
	v_add_f32_e32 v98, 1.0, v80
	v_rcp_f32_e32 v98, v98
	s_nop 0
	v_fma_f32 v99, v117, v98, v116
	v_mul_f32_e32 v84, v84, v99
	v_max_f32_e32 v84, 0xda24260, v84
	v_mul_f32_e32 v80, v80, v98
	v_rcp_f32_e32 v98, v84
	v_mul_f32_e32 v80, v117, v80
	v_mul_f32_e32 v80, v80, v98
	v_bfe_u32 v98, v80, 16, 1
	v_add3_u32 v80, v80, v98, s10
	v_lshlrev_b32_e32 v98, 16, v163
	v_mul_f32_e32 v98, v84, v98
	v_bfe_u32 v99, v98, 16, 1
	v_add3_u32 v98, v98, v99, s10
	ds_write_b16_d16_hi v88, v98 offset:2880
	ds_write_b16_d16_hi v88, v80 offset:7488
	s_waitcnt vmcnt(36)
	v_lshlrev_b32_e32 v98, 16, v164
	v_max_f32_e32 v98, v98, v98
	v_med3_f32 v98, v98, s9, v244
	v_mul_f32_e32 v98, 0xbfb8aa3b, v98
	v_exp_f32_e32 v98, v98
	s_nop 0
	v_add_f32_e32 v99, 1.0, v98
	v_rcp_f32_e32 v99, v99
	s_nop 0
	v_fma_f32 v104, v117, v99, v116
	v_mul_f32_e32 v84, v84, v104
	v_max_f32_e32 v84, 0xda24260, v84
	v_mul_f32_e32 v98, v98, v99
	v_rcp_f32_e32 v99, v84
	v_mul_f32_e32 v98, v117, v98
	v_mul_f32_e32 v98, v98, v99
	v_bfe_u32 v99, v98, 16, 1
	v_add3_u32 v99, v98, v99, s10
	s_waitcnt vmcnt(35)
	v_lshlrev_b32_e32 v98, 16, v162
	v_mul_f32_e32 v98, v84, v98
	v_bfe_u32 v104, v98, 16, 1
	v_add3_u32 v98, v98, v104, s10
	ds_write_b16_d16_hi v88, v98 offset:2736
	ds_write_b16_d16_hi v88, v99 offset:7344
	s_waitcnt vmcnt(34)
	v_lshlrev_b32_e32 v98, 16, v159
	v_max_f32_e32 v98, v98, v98
	v_med3_f32 v98, v98, s9, v244
	v_mul_f32_e32 v98, 0xbfb8aa3b, v98
	v_exp_f32_e32 v98, v98
	s_nop 0
	v_add_f32_e32 v104, 1.0, v98
	v_rcp_f32_e32 v104, v104
	s_nop 0
	v_fma_f32 v105, v117, v104, v116
	v_mul_f32_e32 v84, v84, v105
	v_mul_f32_e32 v98, v98, v104
	v_max_f32_e32 v104, 0xda24260, v84
	v_rcp_f32_e32 v84, v104
	v_mul_f32_e32 v98, v117, v98
	v_mul_f32_e32 v84, v98, v84
	v_bfe_u32 v98, v84, 16, 1
	v_add3_u32 v84, v84, v98, s10
	v_lshlrev_b32_e32 v98, 16, v157
	v_mul_f32_e32 v98, v104, v98
	v_bfe_u32 v105, v98, 16, 1
	v_add3_u32 v98, v98, v105, s10
	ds_write_b16_d16_hi v88, v98 offset:2592
	ds_write_b16_d16_hi v88, v84 offset:7200
	v_lshlrev_b32_e32 v98, 16, v155
	v_max_f32_e32 v98, v98, v98
	v_med3_f32 v98, v98, s9, v244
	v_mul_f32_e32 v98, 0xbfb8aa3b, v98
	v_exp_f32_e32 v98, v98
	s_nop 0
	v_add_f32_e32 v105, 1.0, v98
	v_rcp_f32_e32 v105, v105
	s_nop 0
	v_fma_f32 v155, v117, v105, v116
	v_mul_f32_e32 v104, v104, v155
	v_max_f32_e32 v104, 0xda24260, v104
	v_mul_f32_e32 v98, v98, v105
	v_rcp_f32_e32 v105, v104
	v_mul_f32_e32 v98, v117, v98
	v_mul_f32_e32 v98, v98, v105
	v_bfe_u32 v105, v98, 16, 1
	v_add3_u32 v105, v98, v105, s10
	s_waitcnt vmcnt(23)
	v_lshlrev_b32_e32 v98, 16, v156
	v_mul_f32_e32 v98, v104, v98
	v_bfe_u32 v155, v98, 16, 1
	v_add3_u32 v98, v98, v155, s10
	ds_write_b16_d16_hi v88, v98 offset:2448
	ds_write_b16_d16_hi v88, v105 offset:7056
	v_lshlrev_b32_e32 v98, 16, v109
	v_max_f32_e32 v98, v98, v98
	v_med3_f32 v98, v98, s9, v244
	v_mul_f32_e32 v98, 0xbfb8aa3b, v98
	v_exp_f32_e32 v98, v98
	s_nop 0
	v_add_f32_e32 v109, 1.0, v98
	v_rcp_f32_e32 v109, v109
	s_nop 0
	v_fma_f32 v155, v117, v109, v116
	v_mul_f32_e32 v104, v104, v155
	v_max_f32_e32 v104, 0xda24260, v104
	v_mul_f32_e32 v98, v98, v109
	v_rcp_f32_e32 v109, v104
	v_mul_f32_e32 v98, v117, v98
	v_mul_f32_e32 v107, v104, v107
	v_mul_f32_e32 v98, v98, v109
	v_bfe_u32 v109, v98, 16, 1
	v_add3_u32 v98, v98, v109, s10
	v_bfe_u32 v109, v107, 16, 1
	v_add3_u32 v107, v107, v109, s10
	ds_write_b16_d16_hi v88, v107 offset:2304
	ds_write_b16_d16_hi v88, v98 offset:6912
	s_waitcnt vmcnt(15)
	v_lshlrev_b32_e32 v107, 16, v168
	v_max_f32_e32 v107, v107, v107
	v_med3_f32 v107, v107, s9, v244
	v_mul_f32_e32 v107, 0xbfb8aa3b, v107
	v_exp_f32_e32 v107, v107
	s_nop 0
	v_add_f32_e32 v109, 1.0, v107
	v_rcp_f32_e32 v109, v109
	s_nop 0
	v_fma_f32 v155, v117, v109, v116
	v_mul_f32_e32 v104, v104, v155
	v_max_f32_e32 v104, 0xda24260, v104
	v_mul_f32_e32 v107, v107, v109
	v_rcp_f32_e32 v109, v104
	v_mul_f32_e32 v107, v117, v107
	v_mul_f32_e32 v107, v107, v109
	v_bfe_u32 v109, v107, 16, 1
	v_add3_u32 v107, v107, v109, s10
	s_waitcnt vmcnt(14)
	v_lshlrev_b32_e32 v109, 16, v166
	v_mul_f32_e32 v109, v104, v109
	v_bfe_u32 v155, v109, 16, 1
	v_add3_u32 v109, v109, v155, s10
	ds_write_b16_d16_hi v88, v109 offset:2160
	ds_write_b16_d16_hi v88, v107 offset:6768
	s_waitcnt vmcnt(13)
	v_lshlrev_b32_e32 v109, 16, v165
	v_max_f32_e32 v109, v109, v109
	v_med3_f32 v109, v109, s9, v244
	v_mul_f32_e32 v109, 0xbfb8aa3b, v109
	v_exp_f32_e32 v109, v109
	global_load_ushort v172, v[74:75], off offset:3072
	global_load_ushort v170, v[74:75], off offset:1536
	global_load_ushort v171, v[70:71], off offset:2560
	global_load_ushort v168, v[70:71], off offset:1024
	global_load_ushort v169, v[76:77], off offset:2048
	global_load_ushort v166, v[76:77], off offset:512
	global_load_ushort v167, v[68:69], off offset:1536
	global_load_ushort v162, v[68:69], off
	global_load_ushort v164, v[78:79], off offset:1024
	v_add_co_u32_e32 v68, vcc, s11, v64
	v_add_f32_e32 v155, 1.0, v109
	v_rcp_f32_e32 v155, v155
	v_addc_co_u32_e32 v69, vcc, 0, v65, vcc
	v_fma_f32 v156, v117, v155, v116
	v_mul_f32_e32 v104, v104, v156
	v_max_f32_e32 v173, 0xda24260, v104
	v_rcp_f32_e32 v104, v173
	v_mul_f32_e32 v109, v109, v155
	v_mul_f32_e32 v109, v117, v109
	v_mul_f32_e32 v104, v109, v104
	v_bfe_u32 v109, v104, 16, 1
	v_add3_u32 v104, v104, v109, s10
	s_waitcnt vmcnt(21)
	v_lshlrev_b32_e32 v109, 16, v160
	v_mul_f32_e32 v109, v173, v109
	v_bfe_u32 v155, v109, 16, 1
	v_add3_u32 v109, v109, v155, s10
	global_load_ushort v163, v[68:69], off offset:3584
	global_load_ushort v165, v[68:69], off offset:512
	global_load_ushort v159, v[66:67], off offset:3072
	global_load_ushort v160, v[66:67], off
	global_load_ushort v156, v[72:73], off offset:2560
	global_load_ushort v157, v[64:65], off offset:3584
	global_load_ushort v155, v[64:65], off offset:2048
	s_waitcnt vmcnt(27)
	v_lshlrev_b32_e32 v64, 16, v158
	v_max_f32_e32 v64, v64, v64
	v_med3_f32 v64, v64, s9, v244
	v_mul_f32_e32 v64, 0xbfb8aa3b, v64
	v_exp_f32_e32 v64, v64
	ds_write_b16_d16_hi v88, v109 offset:2016
	ds_write_b16_d16_hi v88, v104 offset:6624
	v_add_f32_e32 v65, 1.0, v64
	v_rcp_f32_e32 v65, v65
	s_nop 0
	v_fma_f32 v66, v117, v65, v116
	v_mul_f32_e32 v64, v64, v65
	v_mul_f32_e32 v65, v173, v66
	v_max_f32_e32 v65, 0xda24260, v65
	v_rcp_f32_e32 v66, v65
	v_mul_f32_e32 v64, v117, v64
	v_mul_f32_e32 v64, v64, v66
	v_bfe_u32 v66, v64, 16, 1
	v_add3_u32 v64, v64, v66, s10
	s_waitcnt vmcnt(26)
	v_lshlrev_b32_e32 v66, 16, v113
	v_mul_f32_e32 v66, v65, v66
	v_bfe_u32 v67, v66, 16, 1
	v_add3_u32 v66, v66, v67, s10
	ds_write_b16_d16_hi v88, v66 offset:1872
	ds_write_b16_d16_hi v88, v64 offset:6480
	s_waitcnt vmcnt(25)
	v_lshlrev_b32_e32 v66, 16, v111
	v_max_f32_e32 v66, v66, v66
	v_med3_f32 v66, v66, s9, v244
	v_mul_f32_e32 v66, 0xbfb8aa3b, v66
	v_exp_f32_e32 v66, v66
	s_nop 0
	v_add_f32_e32 v67, 1.0, v66
	v_rcp_f32_e32 v67, v67
	s_nop 0
	v_fma_f32 v68, v117, v67, v116
	v_mul_f32_e32 v65, v65, v68
	v_max_f32_e32 v65, 0xda24260, v65
	v_mul_f32_e32 v66, v66, v67
	v_rcp_f32_e32 v67, v65
	v_mul_f32_e32 v66, v117, v66
	v_mul_f32_e32 v66, v66, v67
	v_bfe_u32 v67, v66, 16, 1
	v_add3_u32 v158, v66, v67, s10
	s_waitcnt vmcnt(24)
	v_lshlrev_b32_e32 v66, 16, v103
	v_mul_f32_e32 v66, v65, v66
	v_bfe_u32 v67, v66, 16, 1
	v_add3_u32 v66, v66, v67, s10
	ds_write_b16_d16_hi v88, v66 offset:1728
	ds_write_b16_d16_hi v88, v158 offset:6336
	s_waitcnt vmcnt(23)
	v_lshlrev_b32_e32 v66, 16, v102
	v_max_f32_e32 v66, v66, v66
	v_med3_f32 v66, v66, s9, v244
	v_mul_f32_e32 v66, 0xbfb8aa3b, v66
	v_exp_f32_e32 v66, v66
	s_nop 0
	v_add_f32_e32 v67, 1.0, v66
	v_rcp_f32_e32 v67, v67
	s_nop 0
	v_fma_f32 v68, v117, v67, v116
	v_mul_f32_e32 v65, v65, v68
	v_max_f32_e32 v65, 0xda24260, v65
	v_mul_f32_e32 v66, v66, v67
	v_rcp_f32_e32 v67, v65
	v_mul_f32_e32 v66, v117, v66
	v_mul_f32_e32 v66, v66, v67
	v_bfe_u32 v67, v66, 16, 1
	v_add3_u32 v66, v66, v67, s10
	s_waitcnt vmcnt(22)
	v_lshlrev_b32_e32 v67, 16, v101
	v_mul_f32_e32 v67, v65, v67
	v_bfe_u32 v68, v67, 16, 1
	v_add3_u32 v67, v67, v68, s10
	ds_write_b16_d16_hi v88, v67 offset:1584
	ds_write_b16_d16_hi v88, v66 offset:6192
	s_waitcnt vmcnt(21)
	v_lshlrev_b32_e32 v67, 16, v100
	v_max_f32_e32 v67, v67, v67
	v_med3_f32 v67, v67, s9, v244
	v_mul_f32_e32 v67, 0xbfb8aa3b, v67
	v_exp_f32_e32 v67, v67
	s_nop 0
	v_add_f32_e32 v68, 1.0, v67
	v_rcp_f32_e32 v68, v68
	s_nop 0
	v_fma_f32 v69, v117, v68, v116
	v_mul_f32_e32 v65, v65, v69
	v_max_f32_e32 v65, 0xda24260, v65
	v_mul_f32_e32 v67, v67, v68
	v_rcp_f32_e32 v68, v65
	v_mul_f32_e32 v67, v117, v67
	v_mul_f32_e32 v67, v67, v68
	v_bfe_u32 v68, v67, 16, 1
	v_add3_u32 v100, v67, v68, s10
	s_waitcnt vmcnt(20)
	v_lshlrev_b32_e32 v67, 16, v87
	v_mul_f32_e32 v67, v65, v67
	v_bfe_u32 v68, v67, 16, 1
	v_add3_u32 v67, v67, v68, s10
	ds_write_b16_d16_hi v88, v67 offset:1440
	ds_write_b16_d16_hi v88, v100 offset:6048
	s_waitcnt vmcnt(19)
	v_lshlrev_b32_e32 v67, 16, v86
	v_max_f32_e32 v67, v67, v67
	v_med3_f32 v67, v67, s9, v244
	v_mul_f32_e32 v67, 0xbfb8aa3b, v67
	v_exp_f32_e32 v67, v67
	s_nop 0
	v_add_f32_e32 v68, 1.0, v67
	v_rcp_f32_e32 v68, v68
	s_nop 0
	v_fma_f32 v69, v117, v68, v116
	v_mul_f32_e32 v65, v65, v69
	v_max_f32_e32 v65, 0xda24260, v65
	v_mul_f32_e32 v67, v67, v68
	v_rcp_f32_e32 v68, v65
	v_mul_f32_e32 v67, v117, v67
	v_mul_f32_e32 v67, v67, v68
	v_bfe_u32 v68, v67, 16, 1
	v_add3_u32 v67, v67, v68, s10
	s_waitcnt vmcnt(18)
	v_lshlrev_b32_e32 v68, 16, v83
	v_mul_f32_e32 v68, v65, v68
	v_bfe_u32 v69, v68, 16, 1
	v_add3_u32 v68, v68, v69, s10
	ds_write_b16_d16_hi v88, v68 offset:1296
	ds_write_b16_d16_hi v88, v67 offset:5904
	s_waitcnt vmcnt(17)
	v_lshlrev_b32_e32 v68, 16, v82
	v_max_f32_e32 v68, v68, v68
	v_med3_f32 v68, v68, s9, v244
	v_mul_f32_e32 v68, 0xbfb8aa3b, v68
	v_exp_f32_e32 v68, v68
	s_nop 0
	v_add_f32_e32 v69, 1.0, v68
	v_rcp_f32_e32 v69, v69
	s_nop 0
	v_fma_f32 v70, v117, v69, v116
	v_mul_f32_e32 v65, v65, v70
	v_max_f32_e32 v76, 0xda24260, v65
	v_rcp_f32_e32 v65, v76
	v_mul_f32_e32 v68, v68, v69
	v_mul_f32_e32 v68, v117, v68
	v_mul_f32_e32 v65, v68, v65
	v_bfe_u32 v68, v65, 16, 1
	v_add3_u32 v82, v65, v68, s10
	s_waitcnt vmcnt(16)
	v_lshlrev_b32_e32 v65, 16, v81
	v_mul_f32_e32 v65, v76, v65
	v_bfe_u32 v68, v65, 16, 1
	v_add3_u32 v65, v65, v68, s10
	ds_write_b16_d16_hi v88, v65 offset:1152
	ds_write_b16_d16_hi v88, v82 offset:5760
	s_waitcnt vmcnt(15)
	v_lshlrev_b32_e32 v72, 16, v172
	v_max_f32_e32 v72, v72, v72
	v_med3_f32 v72, v72, s9, v244
	v_mul_f32_e32 v72, 0xbfb8aa3b, v72
	v_exp_f32_e32 v86, v72
	v_and_b32_e32 v111, 0xffff0000, v66
	v_lshl_or_b32 v66, v106, 16, v122
	v_and_b32_e32 v113, 0xffff0000, v67
	v_add_f32_e32 v77, 1.0, v86
	v_rcp_f32_e32 v102, v77
	v_lshl_or_b32 v67, v108, 16, v110
	v_and_b32_e32 v81, 0xffff0000, v112
	v_lshl_or_b32 v75, v149, 16, v127
	v_fma_f32 v106, v117, v102, v116
	v_mul_f32_e32 v76, v76, v106
	v_max_f32_e32 v106, 0xda24260, v76
	v_rcp_f32_e32 v108, v106
	v_mul_f32_e32 v86, v86, v102
	v_mul_f32_e32 v86, v117, v86
	v_lshl_or_b32 v65, v133, 16, v121
	v_mul_f32_e32 v86, v86, v108
	v_bfe_u32 v102, v86, 16, 1
	v_add3_u32 v86, v86, v102, s10
	s_waitcnt vmcnt(13)
	v_lshlrev_b32_e32 v102, 16, v171
	v_max_f32_e32 v102, v102, v102
	v_med3_f32 v102, v102, s9, v244
	v_mul_f32_e32 v102, 0xbfb8aa3b, v102
	v_exp_f32_e32 v102, v102
	v_lshlrev_b32_e32 v108, 16, v170
	v_mul_f32_e32 v108, v106, v108
	v_bfe_u32 v112, v108, 16, 1
	v_add_f32_e32 v110, 1.0, v102
	v_rcp_f32_e32 v110, v110
	v_add3_u32 v108, v108, v112, s10
	ds_write_b16_d16_hi v88, v108 offset:1008
	v_and_b32_e32 v127, 0xffff0000, v86
	v_fma_f32 v108, v117, v110, v116
	v_mul_f32_e32 v106, v106, v108
	v_max_f32_e32 v106, 0xda24260, v106
	v_rcp_f32_e32 v108, v106
	ds_write_b16_d16_hi v88, v86 offset:5616
	v_mul_f32_e32 v86, v102, v110
	v_mul_f32_e32 v86, v117, v86
	v_mul_f32_e32 v86, v86, v108
	s_waitcnt vmcnt(11)
	v_lshlrev_b32_e32 v108, 16, v169
	v_max_f32_e32 v108, v108, v108
	v_med3_f32 v108, v108, s9, v244
	v_mul_f32_e32 v108, 0xbfb8aa3b, v108
	v_exp_f32_e32 v108, v108
	v_bfe_u32 v102, v86, 16, 1
	v_add3_u32 v86, v86, v102, s10
	v_lshlrev_b32_e32 v102, 16, v168
	v_add_f32_e32 v110, 1.0, v108
	v_rcp_f32_e32 v110, v110
	v_mul_f32_e32 v102, v106, v102
	v_bfe_u32 v112, v102, 16, 1
	v_add3_u32 v102, v102, v112, s10
	ds_write_b16_d16_hi v88, v102 offset:864
	v_fma_f32 v102, v117, v110, v116
	v_mul_f32_e32 v102, v106, v102
	v_max_f32_e32 v102, 0xda24260, v102
	v_rcp_f32_e32 v106, v102
	v_mul_f32_e32 v108, v108, v110
	v_mul_f32_e32 v108, v117, v108
	s_waitcnt vmcnt(10)
	v_lshlrev_b32_e32 v110, 16, v166
	v_mul_f32_e32 v106, v108, v106
	v_bfe_u32 v108, v106, 16, 1
	v_add3_u32 v106, v106, v108, s10
	s_waitcnt vmcnt(9)
	v_lshlrev_b32_e32 v108, 16, v167
	v_max_f32_e32 v108, v108, v108
	v_med3_f32 v108, v108, s9, v244
	v_mul_f32_e32 v108, 0xbfb8aa3b, v108
	v_exp_f32_e32 v108, v108
	v_mul_f32_e32 v110, v102, v110
	v_bfe_u32 v121, v110, 16, 1
	v_add3_u32 v110, v110, v121, s10
	v_add_f32_e32 v112, 1.0, v108
	v_rcp_f32_e32 v112, v112
	ds_write_b16_d16_hi v88, v110 offset:720
	v_lshl_or_b32 v74, v147, 16, v125
	v_and_b32_e32 v125, 0xffff0000, v106
	v_fma_f32 v110, v117, v112, v116
	v_mul_f32_e32 v102, v102, v110
	v_max_f32_e32 v102, 0xda24260, v102
	v_rcp_f32_e32 v110, v102
	ds_write_b16_d16_hi v88, v106 offset:5328
	v_mul_f32_e32 v106, v108, v112
	v_mul_f32_e32 v106, v117, v106
	v_mul_f32_e32 v106, v106, v110
	s_waitcnt vmcnt(7)
	v_lshlrev_b32_e32 v110, 16, v164
	v_max_f32_e32 v110, v110, v110
	v_med3_f32 v110, v110, s9, v244
	v_mul_f32_e32 v110, 0xbfb8aa3b, v110
	v_exp_f32_e32 v110, v110
	v_bfe_u32 v108, v106, 16, 1
	v_add3_u32 v106, v106, v108, s10
	v_lshlrev_b32_e32 v108, 16, v162
	v_add_f32_e32 v112, 1.0, v110
	v_rcp_f32_e32 v112, v112
	v_mul_f32_e32 v108, v102, v108
	v_bfe_u32 v121, v108, 16, 1
	v_add3_u32 v108, v108, v121, s10
	ds_write_b16_d16_hi v88, v108 offset:576
	v_fma_f32 v108, v117, v112, v116
	v_mul_f32_e32 v102, v102, v108
	v_max_f32_e32 v102, 0xda24260, v102
	v_rcp_f32_e32 v108, v102
	v_mul_f32_e32 v110, v110, v112
	v_mul_f32_e32 v110, v117, v110
	s_waitcnt vmcnt(6)
	v_lshlrev_b32_e32 v112, 16, v163
	v_mul_f32_e32 v108, v110, v108
	v_bfe_u32 v110, v108, 16, 1
	v_add3_u32 v108, v108, v110, s10
	s_waitcnt vmcnt(5)
	v_lshlrev_b32_e32 v110, 16, v165
	v_max_f32_e32 v110, v110, v110
	v_med3_f32 v110, v110, s9, v244
	v_mul_f32_e32 v110, 0xbfb8aa3b, v110
	v_exp_f32_e32 v110, v110
	v_mul_f32_e32 v112, v102, v112
	v_bfe_u32 v122, v112, 16, 1
	v_add3_u32 v112, v112, v122, s10
	v_add_f32_e32 v121, 1.0, v110
	v_rcp_f32_e32 v121, v121
	ds_write_b16_d16_hi v88, v112 offset:432
	v_lshl_or_b32 v69, v135, 16, v129
	v_and_b32_e32 v129, 0xffff0000, v108
	v_fma_f32 v112, v117, v121, v116
	v_mul_f32_e32 v102, v102, v112
	v_max_f32_e32 v102, 0xda24260, v102
	v_rcp_f32_e32 v112, v102
	ds_write_b16_d16_hi v88, v108 offset:5040
	v_mul_f32_e32 v108, v110, v121
	v_mul_f32_e32 v108, v117, v108
	v_mul_f32_e32 v108, v108, v112
	s_waitcnt vmcnt(3)
	v_lshlrev_b32_e32 v112, 16, v160
	v_max_f32_e32 v112, v112, v112
	v_med3_f32 v112, v112, s9, v244
	v_mul_f32_e32 v112, 0xbfb8aa3b, v112
	v_exp_f32_e32 v112, v112
	v_bfe_u32 v110, v108, 16, 1
	v_add3_u32 v108, v108, v110, s10
	v_lshlrev_b32_e32 v110, 16, v159
	v_add_f32_e32 v121, 1.0, v112
	v_rcp_f32_e32 v121, v121
	v_mul_f32_e32 v110, v102, v110
	v_bfe_u32 v122, v110, 16, 1
	v_add3_u32 v110, v110, v122, s10
	ds_write_b16_d16_hi v88, v110 offset:288
	v_fma_f32 v110, v117, v121, v116
	v_mul_f32_e32 v102, v102, v110
	v_max_f32_e32 v102, 0xda24260, v102
	v_rcp_f32_e32 v110, v102
	v_mul_f32_e32 v112, v112, v121
	v_mul_f32_e32 v112, v117, v112
	s_waitcnt vmcnt(2)
	v_lshlrev_b32_e32 v121, 16, v156
	v_mul_f32_e32 v110, v112, v110
	v_bfe_u32 v112, v110, 16, 1
	v_add3_u32 v110, v110, v112, s10
	s_waitcnt vmcnt(1)
	v_lshlrev_b32_e32 v112, 16, v157
	v_max_f32_e32 v112, v112, v112
	v_med3_f32 v112, v112, s9, v244
	v_mul_f32_e32 v112, 0xbfb8aa3b, v112
	v_exp_f32_e32 v112, v112
	v_mul_f32_e32 v121, v102, v121
	v_lshl_or_b32 v70, v137, 16, v123
	v_and_b32_e32 v123, 0xffff0000, v110
	v_add_f32_e32 v122, 1.0, v112
	v_rcp_f32_e32 v122, v122
	ds_write_b16_d16_hi v88, v110 offset:4752
	v_lshl_or_b32 v71, v131, 16, v124
	v_bfe_u32 v124, v121, 16, 1
	v_fmac_f32_e32 v116, v117, v122
	v_mul_f32_e32 v102, v102, v116
	v_max_f32_e32 v116, 0xda24260, v102
	v_rcp_f32_e32 v102, v116
	v_mul_f32_e32 v110, v112, v122
	v_mul_f32_e32 v110, v117, v110
	v_readlane_b32 s9, v255, 34
	v_mul_f32_e32 v102, v110, v102
	v_bfe_u32 v110, v102, 16, 1
	v_add3_u32 v102, v102, v110, s10
	s_waitcnt vmcnt(0)
	v_lshlrev_b32_e32 v110, 16, v155
	v_mul_f32_e32 v110, v116, v110
	v_bfe_u32 v112, v110, 16, 1
	v_add3_u32 v121, v121, v124, s10
	v_add3_u32 v110, v110, v112, s10
	v_readlane_b32 s10, v255, 36
	v_and_b32_e32 v109, 0xffff0000, v64
	v_and_b32_e32 v107, 0xffff0000, v107
	v_and_b32_e32 v105, 0xffff0000, v105
	v_and_b32_e32 v103, 0xffff0000, v99
	v_and_b32_e32 v101, 0xffff0000, v85
	v_and_b32_e32 v99, 0xffff0000, v154
	v_and_b32_e32 v87, 0xffff0000, v153
	v_and_b32_e32 v85, 0xffff0000, v152
	v_and_b32_e32 v83, 0xffff0000, v151
	v_lshl_or_b32 v64, v132, 16, v126
	v_lshl_or_b32 v68, v148, 16, v128
	v_lshl_or_b32 v73, v142, 16, v141
	v_lshl_or_b32 v72, v146, 16, v139
	v_lshl_or_b32 v79, v144, 16, v138
	v_lshl_or_b32 v78, v145, 16, v136
	v_lshl_or_b32 v77, v140, 16, v134
	v_lshl_or_b32 v76, v143, 16, v130
	ds_write_b16_d16_hi v88, v86 offset:5472
	ds_write_b16_d16_hi v88, v106 offset:5184
	ds_write_b16_d16_hi v88, v108 offset:4896
	ds_write_b16_d16_hi v88, v121 offset:144
	ds_write_b16_d16_hi v88, v110
	ds_write_b16_d16_hi v88, v102 offset:4608
	v_and_b32_e32 v122, 0xffff0000, v102
	v_and_b32_e32 v128, 0xffff0000, v108
	v_and_b32_e32 v124, 0xffff0000, v106
	v_and_b32_e32 v126, 0xffff0000, v86
	v_pk_mul_f32 v[122:123], v[116:117], v[122:123] op_sel_hi:[0,1]
	v_pk_mul_f32 v[128:129], v[116:117], v[128:129] op_sel_hi:[0,1]
	v_pk_mul_f32 v[124:125], v[116:117], v[124:125] op_sel_hi:[0,1]
	v_pk_mul_f32 v[126:127], v[116:117], v[126:127] op_sel_hi:[0,1]
	v_and_b32_e32 v112, 0xffff0000, v82
	v_and_b32_e32 v110, 0xffff0000, v100
	v_and_b32_e32 v108, 0xffff0000, v158
	v_and_b32_e32 v106, 0xffff0000, v104
	v_and_b32_e32 v104, 0xffff0000, v98
	v_and_b32_e32 v102, 0xffff0000, v84
	v_and_b32_e32 v100, 0xffff0000, v80
	v_and_b32_e32 v98, 0xffff0000, v150
	v_and_b32_e32 v86, 0xffff0000, v120
	v_and_b32_e32 v84, 0xffff0000, v119
	v_and_b32_e32 v82, 0xffff0000, v118
	v_and_b32_e32 v80, 0xffff0000, v95
	v_mad_u64_u32 v[130:131], s[2:3], v94, s4, v[92:93]
	v_cvt_pk_bf16_f32 v122, v122, v123
	v_cvt_pk_bf16_f32 v123, v128, v129
	v_cvt_pk_bf16_f32 v124, v124, v125
	v_cvt_pk_bf16_f32 v125, v126, v127
	v_pk_mul_f32 v[112:113], v[116:117], v[112:113] op_sel_hi:[0,1]
	v_pk_mul_f32 v[110:111], v[116:117], v[110:111] op_sel_hi:[0,1]
	v_pk_mul_f32 v[108:109], v[116:117], v[108:109] op_sel_hi:[0,1]
	v_pk_mul_f32 v[106:107], v[116:117], v[106:107] op_sel_hi:[0,1]
	v_pk_mul_f32 v[104:105], v[116:117], v[104:105] op_sel_hi:[0,1]
	v_pk_mul_f32 v[102:103], v[116:117], v[102:103] op_sel_hi:[0,1]
	v_pk_mul_f32 v[100:101], v[116:117], v[100:101] op_sel_hi:[0,1]
	v_pk_mul_f32 v[98:99], v[116:117], v[98:99] op_sel_hi:[0,1]
	v_pk_mul_f32 v[86:87], v[116:117], v[86:87] op_sel_hi:[0,1]
	v_pk_mul_f32 v[84:85], v[116:117], v[84:85] op_sel_hi:[0,1]
	v_pk_mul_f32 v[82:83], v[116:117], v[82:83] op_sel_hi:[0,1]
	v_pk_mul_f32 v[80:81], v[116:117], v[80:81] op_sel_hi:[0,1]
	ds_write_b128 v130, v[122:125] offset:9216
	v_cvt_pk_bf16_f32 v122, v112, v113
	v_cvt_pk_bf16_f32 v123, v110, v111
	v_cvt_pk_bf16_f32 v124, v108, v109
	v_cvt_pk_bf16_f32 v125, v106, v107
	v_cvt_pk_bf16_f32 v104, v104, v105
	v_cvt_pk_bf16_f32 v105, v102, v103
	v_cvt_pk_bf16_f32 v106, v100, v101
	v_cvt_pk_bf16_f32 v107, v98, v99
	v_cvt_pk_bf16_f32 v98, v86, v87
	v_cvt_pk_bf16_f32 v99, v84, v85
	v_cvt_pk_bf16_f32 v100, v82, v83
	v_cvt_pk_bf16_f32 v101, v80, v81
	v_lshl_add_u32 v80, v94, 2, v92
	ds_write_b128 v130, v[122:125] offset:9232
	ds_write_b128 v130, v[104:107] offset:9248
	ds_write_b128 v130, v[98:101] offset:9264
	ds_write_b32 v80, v116 offset:19456
	ds_write_b128 v130, v[76:79] offset:14336
	ds_write_b128 v130, v[72:75] offset:14352
	ds_write_b128 v130, v[68:71] offset:14368
	ds_write_b128 v130, v[64:67] offset:14384
	s_waitcnt lgkmcnt(0)
	v_or_b32_e32 v88, v93, v114
	v_lshlrev_b64 v[64:65], 11, v[88:89]
	v_lshlrev_b32_e32 v98, 2, v115
	v_lshl_add_u64 v[64:65], s[12:13], 0, v[64:65]
	v_ashrrev_i32_e32 v99, 31, v98
	v_lshl_add_u64 v[64:65], v[64:65], 0, v[90:91]
	v_lshlrev_b64 v[100:101], 1, v[98:99]
	v_lshl_add_u64 v[102:103], v[64:65], 0, v[100:101]
	s_mov_b64 s[2:3], 0x16f00600
	v_lshl_add_u64 v[94:95], v[102:103], 0, s[2:3]
	global_load_dwordx2 v[196:197], v[94:95], off
	global_load_dwordx2 v[198:199], v[94:95], off offset:16
	global_load_dwordx2 v[200:201], v[94:95], off offset:32
	global_load_dwordx2 v[202:203], v[94:95], off offset:48
	global_load_dwordx2 v[230:231], v[94:95], off offset:64
	global_load_dwordx2 v[232:233], v[94:95], off offset:80
	global_load_dwordx2 v[234:235], v[94:95], off offset:96
	global_load_dwordx2 v[240:241], v[94:95], off offset:112
	s_movk_i32 s2, 0x90
	v_mad_u32_u24 v89, v114, s2, v92
	v_lshl_add_u32 v93, v115, 4, v89
	ds_read_b128 v[64:67], v93 offset:4608
	ds_read_b128 v[68:71], v93
	ds_read_b128 v[80:83], v93 offset:32
	ds_read_b128 v[84:87], v93 offset:4640
	s_waitcnt lgkmcnt(2)
	v_mfma_f32_32x32x16_bf16 v[64:79], v[64:67], v[68:71], 0
	v_cmp_ge_i32_e32 vcc, v98, v114
	v_cvt_pk_bf16_f32 v32, v32, v33
	v_cvt_pk_bf16_f32 v33, v34, v35
	v_cvt_pk_bf16_f32 v34, v36, v37
	v_cvt_pk_bf16_f32 v35, v38, v39
	v_cvt_pk_bf16_f32 v36, v48, v49
	v_cvt_pk_bf16_f32 v37, v50, v51
	s_waitcnt lgkmcnt(0)
	v_mfma_f32_32x32x16_bf16 v[64:79], v[84:87], v[80:83], v[64:79]
	ds_read_b128 v[80:83], v93 offset:4672
	ds_read_b128 v[84:87], v93 offset:64
	v_cvt_pk_bf16_f32 v38, v52, v53
	v_cvt_pk_bf16_f32 v39, v54, v55
	s_mov_b32 s2, 0x16f00000
	s_waitcnt lgkmcnt(0)
	v_mfma_f32_32x32x16_bf16 v[64:79], v[80:83], v[84:87], v[64:79]
	ds_read_b128 v[80:83], v93 offset:4704
	ds_read_b128 v[84:87], v93 offset:96
	s_waitcnt lgkmcnt(0)
	v_mfma_f32_32x32x16_bf16 v[64:79], v[80:83], v[84:87], v[64:79]
	v_or_b32_e32 v80, 1, v98
	s_nop 10
	v_cndmask_b32_e32 v64, 0, v64, vcc
	v_cmp_ge_i32_e32 vcc, v80, v114
	v_or_b32_e32 v80, 2, v98
	s_nop 0
	v_cndmask_b32_e32 v65, 0, v65, vcc
	v_cmp_ge_i32_e32 vcc, v80, v114
	v_or_b32_e32 v80, 3, v98
	s_nop 0
	v_cndmask_b32_e32 v66, 0, v66, vcc
	v_cmp_ge_i32_e32 vcc, v80, v114
	v_add_u32_e32 v80, 8, v98
	s_nop 0
	v_cndmask_b32_e32 v67, 0, v67, vcc
	v_cmp_ge_i32_e32 vcc, v80, v114
	v_add_u32_e32 v80, 9, v98
	v_cvt_pk_bf16_f32 v81, v66, v67
	v_cndmask_b32_e32 v68, 0, v68, vcc
	v_cmp_ge_i32_e32 vcc, v80, v114
	v_add_u32_e32 v80, 10, v98
	s_nop 0
	v_cndmask_b32_e32 v69, 0, v69, vcc
	v_cmp_ge_i32_e32 vcc, v80, v114
	v_add_u32_e32 v80, 11, v98
	v_cvt_pk_bf16_f32 v82, v68, v69
	v_cndmask_b32_e32 v70, 0, v70, vcc
	v_cmp_ge_i32_e32 vcc, v80, v114
	v_add_u32_e32 v80, 16, v98
	s_nop 0
	v_cndmask_b32_e32 v71, 0, v71, vcc
	v_cmp_ge_i32_e32 vcc, v80, v114
	v_add_u32_e32 v80, 17, v98
	v_cvt_pk_bf16_f32 v83, v70, v71
	v_cndmask_b32_e32 v72, 0, v72, vcc
	v_cmp_ge_i32_e32 vcc, v80, v114
	v_add_u32_e32 v80, 18, v98
	s_nop 0
	v_cndmask_b32_e32 v73, 0, v73, vcc
	v_cmp_ge_i32_e32 vcc, v80, v114
	v_add_u32_e32 v80, 19, v98
	v_cvt_pk_bf16_f32 v84, v72, v73
	v_cndmask_b32_e32 v74, 0, v74, vcc
	v_cmp_ge_i32_e32 vcc, v80, v114
	v_add_u32_e32 v80, 24, v98
	s_nop 0
	v_cndmask_b32_e32 v75, 0, v75, vcc
	v_cmp_ge_i32_e32 vcc, v80, v114
	v_add_u32_e32 v80, 25, v98
	v_cvt_pk_bf16_f32 v85, v74, v75
	v_cndmask_b32_e32 v76, 0, v76, vcc
	v_cmp_ge_i32_e32 vcc, v80, v114
	v_add_u32_e32 v80, 26, v98
	s_nop 0
	v_cndmask_b32_e32 v77, 0, v77, vcc
	v_cmp_ge_i32_e32 vcc, v80, v114
	v_add_u32_e32 v80, 27, v98
	v_cvt_pk_bf16_f32 v86, v76, v77
	v_cndmask_b32_e32 v78, 0, v78, vcc
	v_cmp_ge_i32_e32 vcc, v80, v114
	v_cvt_pk_bf16_f32 v80, v64, v65
	v_lshlrev_b32_e32 v64, 3, v115
	v_mul_u32_u24_e32 v65, 0x50, v114
	v_add3_u32 v92, v92, v64, v65
	v_add_u32_e32 v68, 0x3800, v92
	v_add_u32_e32 v89, v89, v64
	ds_read2_b64 v[64:67], v68 offset1:2
	ds_read2_b64 v[104:107], v68 offset0:4 offset1:6
	v_cndmask_b32_e32 v79, 0, v79, vcc
	v_cvt_pk_bf16_f32 v87, v78, v79
	s_waitcnt lgkmcnt(1)
	v_mfma_f32_32x32x16_bf16 v[64:79], v[64:67], v[80:83], 0
	v_add_co_u32_e32 v48, vcc, s2, v102
	s_nop 1
	v_addc_co_u32_e32 v49, vcc, 0, v103, vcc
	s_waitcnt lgkmcnt(0)
	v_mfma_f32_32x32x16_bf16 v[64:79], v[104:107], v[84:87], v[64:79]
	ds_read2_b64 v[104:107], v89 offset1:2
	ds_read2_b64 v[108:111], v89 offset0:4 offset1:6
	s_waitcnt lgkmcnt(1)
	v_mfma_f32_32x32x16_bf16 v[64:79], v[32:35], v[104:107], v[64:79]
	v_cvt_pk_bf16_f32 v32, v40, v41
	v_cvt_pk_bf16_f32 v33, v42, v43
	v_cvt_pk_bf16_f32 v34, v44, v45
	v_cvt_pk_bf16_f32 v35, v46, v47
	s_waitcnt lgkmcnt(0)
	s_nop 0
	v_mfma_f32_32x32x16_bf16 v[64:79], v[32:35], v[108:111], v[64:79]
	ds_read2_b64 v[32:35], v89 offset0:8 offset1:10
	s_waitcnt lgkmcnt(0)
	v_mfma_f32_32x32x16_bf16 v[64:79], v[36:39], v[32:35], v[64:79]
	ds_read2_b64 v[32:35], v89 offset0:12 offset1:14
	v_cvt_pk_bf16_f32 v36, v56, v57
	v_cvt_pk_bf16_f32 v37, v58, v59
	v_cvt_pk_bf16_f32 v38, v60, v61
	v_cvt_pk_bf16_f32 v39, v62, v63
	s_waitcnt lgkmcnt(0)
	s_nop 0
	v_mfma_f32_32x32x16_bf16 v[64:79], v[36:39], v[32:35], v[64:79]
	s_waitcnt vmcnt(7)
	v_lshlrev_b32_e32 v34, 16, v196
	v_and_b32_e32 v35, 0xffff0000, v196
	v_lshlrev_b32_e32 v32, 16, v197
	v_and_b32_e32 v33, 0xffff0000, v197
	s_nop 5
	v_pk_add_f32 v[34:35], v[64:65], v[34:35]
	v_pk_add_f32 v[32:33], v[66:67], v[32:33]
	v_mul_f32_e32 v36, v35, v35
	v_mul_f32_e32 v38, v33, v33
	v_pk_fma_f32 v[36:37], v[34:35], v[34:35], v[36:37] op_sel_hi:[1,1,0]
	v_pk_fma_f32 v[38:39], v[32:33], v[32:33], v[38:39] op_sel_hi:[1,1,0]
	v_cvt_pk_bf16_f32 v34, v34, v35
	v_cvt_pk_bf16_f32 v35, v32, v33
	v_pk_add_f32 v[36:37], v[36:37], v[38:39]
	global_store_dwordx2 v[48:49], v[34:35], off offset:1536
	s_waitcnt vmcnt(7)
	v_lshlrev_b32_e32 v34, 16, v198
	v_and_b32_e32 v35, 0xffff0000, v198
	v_lshlrev_b32_e32 v32, 16, v199
	v_and_b32_e32 v33, 0xffff0000, v199
	v_pk_add_f32 v[34:35], v[68:69], v[34:35]
	v_pk_add_f32 v[32:33], v[70:71], v[32:33]
	v_mul_f32_e32 v38, v35, v35
	v_mul_f32_e32 v40, v33, v33
	v_pk_fma_f32 v[38:39], v[34:35], v[34:35], v[38:39] op_sel_hi:[1,1,0]
	v_pk_fma_f32 v[40:41], v[32:33], v[32:33], v[40:41] op_sel_hi:[1,1,0]
	v_cvt_pk_bf16_f32 v34, v34, v35
	v_cvt_pk_bf16_f32 v35, v32, v33
	v_pk_add_f32 v[38:39], v[38:39], v[40:41]
	global_store_dwordx2 v[94:95], v[34:35], off offset:16
	v_pk_add_f32 v[36:37], v[36:37], v[38:39]
	s_waitcnt vmcnt(7)
	v_lshlrev_b32_e32 v34, 16, v200
	v_and_b32_e32 v35, 0xffff0000, v200
	v_pk_add_f32 v[34:35], v[72:73], v[34:35]
	v_lshlrev_b32_e32 v32, 16, v201
	v_and_b32_e32 v33, 0xffff0000, v201
	v_pk_add_f32 v[38:39], v[74:75], v[32:33]
	v_mul_f32_e32 v32, v35, v35
	v_pk_fma_f32 v[32:33], v[34:35], v[34:35], v[32:33] op_sel_hi:[1,1,0]
	v_cvt_pk_bf16_f32 v34, v34, v35
	v_cvt_pk_bf16_f32 v35, v38, v39
	global_store_dwordx2 v[94:95], v[34:35], off offset:32
	v_mul_f32_e32 v40, v39, v39
	v_pk_fma_f32 v[40:41], v[38:39], v[38:39], v[40:41] op_sel_hi:[1,1,0]
	s_nop 0
	v_pk_add_f32 v[32:33], v[32:33], v[40:41]
	s_nop 0
	v_pk_add_f32 v[32:33], v[36:37], v[32:33]
	s_waitcnt vmcnt(7)
	v_lshlrev_b32_e32 v36, 16, v202
	v_and_b32_e32 v37, 0xffff0000, v202
	v_lshlrev_b32_e32 v34, 16, v203
	v_and_b32_e32 v35, 0xffff0000, v203
	v_pk_add_f32 v[36:37], v[76:77], v[36:37]
	v_pk_add_f32 v[34:35], v[78:79], v[34:35]
	v_mul_f32_e32 v38, v37, v37
	v_mul_f32_e32 v40, v35, v35
	v_pk_fma_f32 v[38:39], v[36:37], v[36:37], v[38:39] op_sel_hi:[1,1,0]
	v_pk_fma_f32 v[40:41], v[34:35], v[34:35], v[40:41] op_sel_hi:[1,1,0]
	s_nop 0
	v_pk_add_f32 v[38:39], v[38:39], v[40:41]
	s_nop 0
	v_pk_add_f32 v[58:59], v[32:33], v[38:39]
	v_cvt_pk_bf16_f32 v32, v36, v37
	v_cvt_pk_bf16_f32 v33, v34, v35
	global_store_dwordx2 v[94:95], v[32:33], off offset:48
	v_add_u32_e32 v36, 0x4000, v92
	ds_read2_b64 v[32:35], v36 offset0:64 offset1:66
	ds_read2_b64 v[50:53], v36 offset0:68 offset1:70
	v_cvt_pk_bf16_f32 v0, v0, v1
	v_cvt_pk_bf16_f32 v1, v2, v3
	v_cvt_pk_bf16_f32 v2, v4, v5
	s_waitcnt lgkmcnt(1)
	v_mfma_f32_32x32x16_bf16 v[32:47], v[32:35], v[80:83], 0
	v_cvt_pk_bf16_f32 v3, v6, v7
	v_cvt_pk_bf16_f32 v4, v16, v17
	v_cvt_pk_bf16_f32 v5, v18, v19
	v_cvt_pk_bf16_f32 v6, v20, v21
	v_cvt_pk_bf16_f32 v7, v22, v23
	s_waitcnt lgkmcnt(0)
	v_mfma_f32_32x32x16_bf16 v[32:47], v[50:53], v[84:87], v[32:47]
	ds_read2_b64 v[50:53], v89 offset1:2
	ds_read2_b64 v[54:57], v89 offset0:4 offset1:6
	s_waitcnt lgkmcnt(1)
	v_mfma_f32_32x32x16_bf16 v[32:47], v[0:3], v[50:53], v[32:47]
	v_cvt_pk_bf16_f32 v0, v8, v9
	v_cvt_pk_bf16_f32 v1, v10, v11
	v_cvt_pk_bf16_f32 v2, v12, v13
	v_cvt_pk_bf16_f32 v3, v14, v15
	s_waitcnt lgkmcnt(0)
	s_nop 0
	v_mfma_f32_32x32x16_bf16 v[32:47], v[0:3], v[54:57], v[32:47]
	ds_read2_b64 v[0:3], v89 offset0:8 offset1:10
	s_waitcnt lgkmcnt(0)
	v_mfma_f32_32x32x16_bf16 v[32:47], v[4:7], v[0:3], v[32:47]
	ds_read2_b64 v[0:3], v89 offset0:12 offset1:14
	v_cvt_pk_bf16_f32 v4, v24, v25
	v_cvt_pk_bf16_f32 v5, v26, v27
	v_cvt_pk_bf16_f32 v6, v28, v29
	v_cvt_pk_bf16_f32 v7, v30, v31
	s_waitcnt lgkmcnt(0)
	s_nop 0
	v_mfma_f32_32x32x16_bf16 v[32:47], v[4:7], v[0:3], v[32:47]
	s_waitcnt vmcnt(7)
	v_lshlrev_b32_e32 v2, 16, v230
	v_and_b32_e32 v3, 0xffff0000, v230
	v_lshlrev_b32_e32 v0, 16, v231
	v_and_b32_e32 v1, 0xffff0000, v231
	s_nop 5
	v_pk_add_f32 v[2:3], v[32:33], v[2:3]
	v_pk_add_f32 v[0:1], v[34:35], v[0:1]
	v_mul_f32_e32 v4, v3, v3
	v_mul_f32_e32 v6, v1, v1
	v_pk_fma_f32 v[4:5], v[2:3], v[2:3], v[4:5] op_sel_hi:[1,1,0]
	v_pk_fma_f32 v[6:7], v[0:1], v[0:1], v[6:7] op_sel_hi:[1,1,0]
	v_cvt_pk_bf16_f32 v2, v2, v3
	v_cvt_pk_bf16_f32 v3, v0, v1
	v_pk_add_f32 v[4:5], v[4:5], v[6:7]
	global_store_dwordx2 v[94:95], v[2:3], off offset:64
	v_pk_add_f32 v[4:5], v[58:59], v[4:5]
	s_waitcnt vmcnt(7)
	v_lshlrev_b32_e32 v2, 16, v232
	v_and_b32_e32 v3, 0xffff0000, v232
	v_lshlrev_b32_e32 v0, 16, v233
	v_and_b32_e32 v1, 0xffff0000, v233
	v_pk_add_f32 v[2:3], v[36:37], v[2:3]
	v_pk_add_f32 v[0:1], v[38:39], v[0:1]
	v_mul_f32_e32 v6, v3, v3
	v_mul_f32_e32 v8, v1, v1
	v_pk_fma_f32 v[6:7], v[2:3], v[2:3], v[6:7] op_sel_hi:[1,1,0]
	v_pk_fma_f32 v[8:9], v[0:1], v[0:1], v[8:9] op_sel_hi:[1,1,0]
	v_cvt_pk_bf16_f32 v2, v2, v3
	v_cvt_pk_bf16_f32 v3, v0, v1
	v_pk_add_f32 v[6:7], v[6:7], v[8:9]
	global_store_dwordx2 v[94:95], v[2:3], off offset:80
	v_pk_add_f32 v[4:5], v[4:5], v[6:7]
	s_waitcnt vmcnt(7)
	v_lshlrev_b32_e32 v2, 16, v234
	v_and_b32_e32 v3, 0xffff0000, v234
	v_lshlrev_b32_e32 v0, 16, v235
	v_and_b32_e32 v1, 0xffff0000, v235
	v_pk_add_f32 v[2:3], v[40:41], v[2:3]
	v_pk_add_f32 v[6:7], v[42:43], v[0:1]
	v_mov_b32_e32 v0, v2
	v_mov_b32_e32 v8, v3
	v_cvt_pk_bf16_f32 v2, v2, v3
	v_cvt_pk_bf16_f32 v3, v6, v7
	global_store_dwordx2 v[94:95], v[2:3], off offset:96
	v_mov_b32_e32 v9, v7
	v_mov_b32_e32 v1, v6
	v_pk_mul_f32 v[8:9], v[8:9], v[8:9]
	s_nop 0
	v_pk_fma_f32 v[0:1], v[0:1], v[0:1], v[8:9]
	s_nop 0
	v_pk_add_f32 v[0:1], v[0:1], v[0:1] op_sel:[0,1] op_sel_hi:[1,0]
	s_nop 0
	v_pk_add_f32 v[0:1], v[4:5], v[0:1]
	s_waitcnt vmcnt(7)
	v_lshlrev_b32_e32 v4, 16, v240
	v_and_b32_e32 v5, 0xffff0000, v240
	v_lshlrev_b32_e32 v2, 16, v241
	v_and_b32_e32 v3, 0xffff0000, v241
	v_pk_add_f32 v[4:5], v[44:45], v[4:5]
	v_pk_add_f32 v[2:3], v[46:47], v[2:3]
	v_mov_b32_e32 v8, v5
	v_mov_b32_e32 v9, v3
	v_mov_b32_e32 v6, v4
	v_mov_b32_e32 v7, v2
	v_pk_mul_f32 v[8:9], v[8:9], v[8:9]
	v_cvt_pk_bf16_f32 v4, v4, v5
	v_pk_fma_f32 v[6:7], v[6:7], v[6:7], v[8:9]
	v_cvt_pk_bf16_f32 v5, v2, v3
	v_pk_add_f32 v[6:7], v[6:7], v[6:7] op_sel:[0,1] op_sel_hi:[1,0]
	global_store_dwordx2 v[94:95], v[4:5], off offset:112
	v_pk_add_f32 v[0:1], v[0:1], v[6:7]
	s_waitcnt lgkmcnt(0)
	s_nop 0
	v_mov_b32_e32 v1, v0
	s_nop 1
	v_permlane32_swap_b32_e32 v0, v1
	v_add_f32_e32 v0, v0, v1
	v_fmamk_f32 v0, v0, 0x3c800000, v237
	v_rsq_f32_e32 v4, v0
	v_mad_i64_i32 v[0:1], s[2:3], v88, s6, v[96:97]
	v_lshl_add_u64 v[0:1], v[0:1], 0, v[90:91]
	v_lshl_add_u64 v[0:1], v[0:1], 0, v[100:101]
	v_lshl_add_u64 v[8:9], v[0:1], 0, s[48:49]
	v_add_co_u32_e32 v0, vcc, s5, v0
	global_load_dwordx2 v[10:11], v[48:49], off offset:1536
	s_nop 0
	v_addc_co_u32_e32 v1, vcc, 0, v1, vcc
	global_load_dwordx2 v[12:13], v[0:1], off
	s_add_u32 s2, s12, s0
	s_addc_u32 s3, s13, s1
	v_lshl_add_u64 v[0:1], v[98:99], 2, s[2:3]
	v_lshl_add_u64 v[6:7], v[0:1], 0, s[30:31]
	v_add_co_u32_e32 v0, vcc, s7, v0
	v_readlane_b32 s48, v254, 11
	s_nop 0
	v_addc_co_u32_e32 v1, vcc, 0, v1, vcc
	global_load_dwordx4 v[0:3], v[0:1], off offset:2048
	global_load_dwordx4 v[206:209], v[6:7], off offset:32
	global_load_dwordx2 v[210:211], v[8:9], off offset:16
	global_load_dwordx2 v[212:213], v[94:95], off offset:16
	global_load_dwordx4 v[214:217], v[6:7], off offset:64
	global_load_dwordx2 v[218:219], v[8:9], off offset:32
	global_load_dwordx2 v[220:221], v[94:95], off offset:32
	global_load_dwordx4 v[222:225], v[6:7], off offset:96
	global_load_dwordx2 v[226:227], v[8:9], off offset:48
	global_load_dwordx2 v[228:229], v[94:95], off offset:48
	v_readlane_b32 s49, v254, 12
	s_waitcnt vmcnt(11)
	v_lshlrev_b32_e32 v18, 16, v10
	v_and_b32_e32 v19, 0xffff0000, v10
	v_lshlrev_b32_e32 v10, 16, v11
	s_waitcnt vmcnt(10)
	v_lshlrev_b32_e32 v14, 16, v12
	v_mul_f32_e32 v5, 0xbfb8aa3b, v14
	v_exp_f32_e32 v5, v5
	v_and_b32_e32 v15, 0xffff0000, v12
	v_lshlrev_b32_e32 v12, 16, v13
	v_and_b32_e32 v13, 0xffff0000, v13
	v_add_f32_e32 v5, 1.0, v5
	v_rcp_f32_e32 v16, v5
	v_mul_f32_e32 v5, 0xbfb8aa3b, v15
	v_exp_f32_e32 v5, v5
	v_and_b32_e32 v11, 0xffff0000, v11
	v_add_f32_e32 v5, 1.0, v5
	v_rcp_f32_e32 v17, v5
	v_pk_mul_f32 v[18:19], v[4:5], v[18:19] op_sel_hi:[0,1]
	s_waitcnt vmcnt(9)
	v_pk_mul_f32 v[0:1], v[0:1], v[18:19]
	v_pk_mul_f32 v[10:11], v[4:5], v[10:11] op_sel_hi:[0,1]
	v_pk_mul_f32 v[14:15], v[16:17], v[14:15]
	v_pk_mul_f32 v[2:3], v[2:3], v[10:11]
	v_pk_mul_f32 v[0:1], v[0:1], v[14:15]
	s_nop 0
	v_cvt_pk_bf16_f32 v0, v0, v1
	v_mul_f32_e32 v1, 0xbfb8aa3b, v12
	v_exp_f32_e32 v1, v1
	s_nop 0
	v_add_f32_e32 v1, 1.0, v1
	v_rcp_f32_e32 v14, v1
	v_mul_f32_e32 v1, 0xbfb8aa3b, v13
	v_exp_f32_e32 v1, v1
	s_nop 0
	v_add_f32_e32 v1, 1.0, v1
	v_rcp_f32_e32 v15, v1
	s_nop 0
	v_pk_mul_f32 v[10:11], v[14:15], v[12:13]
	s_nop 0
	v_pk_mul_f32 v[2:3], v[2:3], v[10:11]
	s_nop 0
	v_cvt_pk_bf16_f32 v1, v2, v3
	global_store_dwordx2 v[48:49], v[0:1], off offset:1536
	s_nop 0
	s_waitcnt vmcnt(8)
	v_lshlrev_b32_e32 v14, 16, v210
	v_mul_f32_e32 v5, 0xbfb8aa3b, v14
	v_exp_f32_e32 v5, v5
	v_and_b32_e32 v15, 0xffff0000, v210
	s_waitcnt vmcnt(7)
	v_lshlrev_b32_e32 v18, 16, v212
	v_and_b32_e32 v19, 0xffff0000, v212
	v_add_f32_e32 v5, 1.0, v5
	v_rcp_f32_e32 v16, v5
	v_mul_f32_e32 v5, 0xbfb8aa3b, v15
	v_exp_f32_e32 v5, v5
	v_lshlrev_b32_e32 v10, 16, v211
	v_and_b32_e32 v11, 0xffff0000, v211
	v_lshlrev_b32_e32 v12, 16, v213
	v_add_f32_e32 v5, 1.0, v5
	v_rcp_f32_e32 v17, v5
	v_pk_mul_f32 v[18:19], v[4:5], v[18:19] op_sel_hi:[0,1]
	v_pk_mul_f32 v[0:1], v[206:207], v[18:19]
	v_and_b32_e32 v13, 0xffff0000, v213
	v_pk_mul_f32 v[14:15], v[16:17], v[14:15]
	v_pk_mul_f32 v[12:13], v[4:5], v[12:13] op_sel_hi:[0,1]
	v_pk_mul_f32 v[0:1], v[0:1], v[14:15]
	v_pk_mul_f32 v[2:3], v[208:209], v[12:13]
	v_cvt_pk_bf16_f32 v0, v0, v1
	v_mul_f32_e32 v1, 0xbfb8aa3b, v10
	v_exp_f32_e32 v1, v1
	s_nop 0
	v_add_f32_e32 v1, 1.0, v1
	v_rcp_f32_e32 v14, v1
	v_mul_f32_e32 v1, 0xbfb8aa3b, v11
	v_exp_f32_e32 v1, v1
	s_nop 0
	v_add_f32_e32 v1, 1.0, v1
	v_rcp_f32_e32 v15, v1
	s_nop 0
	v_pk_mul_f32 v[10:11], v[14:15], v[10:11]
	s_nop 0
	v_pk_mul_f32 v[2:3], v[2:3], v[10:11]
	s_nop 0
	v_cvt_pk_bf16_f32 v1, v2, v3
	global_store_dwordx2 v[94:95], v[0:1], off offset:16
	s_nop 0
	s_waitcnt vmcnt(6)
	v_lshlrev_b32_e32 v14, 16, v218
	v_mul_f32_e32 v5, 0xbfb8aa3b, v14
	v_exp_f32_e32 v5, v5
	v_and_b32_e32 v15, 0xffff0000, v218
	s_waitcnt vmcnt(5)
	v_lshlrev_b32_e32 v18, 16, v220
	v_and_b32_e32 v19, 0xffff0000, v220
	v_add_f32_e32 v5, 1.0, v5
	v_rcp_f32_e32 v16, v5
	v_mul_f32_e32 v5, 0xbfb8aa3b, v15
	v_exp_f32_e32 v5, v5
	v_lshlrev_b32_e32 v10, 16, v219
	v_and_b32_e32 v11, 0xffff0000, v219
	v_lshlrev_b32_e32 v12, 16, v221
	v_add_f32_e32 v5, 1.0, v5
	v_rcp_f32_e32 v17, v5
	v_pk_mul_f32 v[18:19], v[4:5], v[18:19] op_sel_hi:[0,1]
	v_pk_mul_f32 v[0:1], v[214:215], v[18:19]
	v_and_b32_e32 v13, 0xffff0000, v221
	v_pk_mul_f32 v[14:15], v[16:17], v[14:15]
	v_pk_mul_f32 v[12:13], v[4:5], v[12:13] op_sel_hi:[0,1]
	v_pk_mul_f32 v[0:1], v[0:1], v[14:15]
	v_pk_mul_f32 v[2:3], v[216:217], v[12:13]
	v_cvt_pk_bf16_f32 v0, v0, v1
	v_mul_f32_e32 v1, 0xbfb8aa3b, v10
	v_exp_f32_e32 v1, v1
	s_nop 0
	v_add_f32_e32 v1, 1.0, v1
	v_rcp_f32_e32 v14, v1
	v_mul_f32_e32 v1, 0xbfb8aa3b, v11
	v_exp_f32_e32 v1, v1
	s_nop 0
	v_add_f32_e32 v1, 1.0, v1
	v_rcp_f32_e32 v15, v1
	s_nop 0
	v_pk_mul_f32 v[10:11], v[14:15], v[10:11]
	s_nop 0
	v_pk_mul_f32 v[2:3], v[2:3], v[10:11]
	s_nop 0
	v_cvt_pk_bf16_f32 v1, v2, v3
	global_store_dwordx2 v[94:95], v[0:1], off offset:32
	s_nop 0
	s_waitcnt vmcnt(4)
	v_lshlrev_b32_e32 v14, 16, v226
	v_mul_f32_e32 v5, 0xbfb8aa3b, v14
	v_exp_f32_e32 v5, v5
	v_and_b32_e32 v15, 0xffff0000, v226
	s_waitcnt vmcnt(3)
	v_lshlrev_b32_e32 v18, 16, v228
	v_and_b32_e32 v19, 0xffff0000, v228
	v_add_f32_e32 v5, 1.0, v5
	v_rcp_f32_e32 v16, v5
	v_mul_f32_e32 v5, 0xbfb8aa3b, v15
	v_exp_f32_e32 v5, v5
	v_lshlrev_b32_e32 v10, 16, v227
	v_and_b32_e32 v11, 0xffff0000, v227
	v_lshlrev_b32_e32 v12, 16, v229
	v_add_f32_e32 v5, 1.0, v5
	v_rcp_f32_e32 v17, v5
	v_pk_mul_f32 v[18:19], v[4:5], v[18:19] op_sel_hi:[0,1]
	v_pk_mul_f32 v[0:1], v[222:223], v[18:19]
	v_and_b32_e32 v13, 0xffff0000, v229
	v_pk_mul_f32 v[14:15], v[16:17], v[14:15]
	v_pk_mul_f32 v[12:13], v[4:5], v[12:13] op_sel_hi:[0,1]
	v_pk_mul_f32 v[0:1], v[0:1], v[14:15]
	v_pk_mul_f32 v[2:3], v[224:225], v[12:13]
	v_cvt_pk_bf16_f32 v0, v0, v1
	v_mul_f32_e32 v1, 0xbfb8aa3b, v10
	v_exp_f32_e32 v1, v1
	s_nop 0
	v_add_f32_e32 v1, 1.0, v1
	v_rcp_f32_e32 v14, v1
	v_mul_f32_e32 v1, 0xbfb8aa3b, v11
	v_exp_f32_e32 v1, v1
	s_nop 0
	v_add_f32_e32 v1, 1.0, v1
	v_rcp_f32_e32 v15, v1
	s_nop 0
	v_pk_mul_f32 v[10:11], v[14:15], v[10:11]
	s_nop 0
	v_pk_mul_f32 v[2:3], v[2:3], v[10:11]
	s_nop 0
	v_cvt_pk_bf16_f32 v1, v2, v3
	global_store_dwordx2 v[94:95], v[0:1], off offset:48
	global_load_dwordx2 v[10:11], v[94:95], off offset:64
	global_load_dwordx2 v[12:13], v[8:9], off offset:64
	global_load_dwordx4 v[0:3], v[6:7], off offset:128
	global_load_dwordx2 v[212:213], v[94:95], off offset:80
	global_load_dwordx2 v[210:211], v[8:9], off offset:80
	global_load_dwordx4 v[206:209], v[6:7], off offset:160
	global_load_dwordx2 v[220:221], v[94:95], off offset:96
	global_load_dwordx2 v[218:219], v[8:9], off offset:96
	global_load_dwordx4 v[214:217], v[6:7], off offset:192
	global_load_dwordx2 v[228:229], v[94:95], off offset:112
	global_load_dwordx2 v[226:227], v[8:9], off offset:112
	global_load_dwordx4 v[222:225], v[6:7], off offset:224
	s_waitcnt vmcnt(11)
	v_lshlrev_b32_e32 v18, 16, v10
	s_waitcnt vmcnt(10)
	v_lshlrev_b32_e32 v14, 16, v12
	v_mul_f32_e32 v5, 0xbfb8aa3b, v14
	v_exp_f32_e32 v5, v5
	v_and_b32_e32 v15, 0xffff0000, v12
	v_and_b32_e32 v19, 0xffff0000, v10
	v_lshlrev_b32_e32 v12, 16, v13
	v_add_f32_e32 v5, 1.0, v5
	v_rcp_f32_e32 v16, v5
	v_mul_f32_e32 v5, 0xbfb8aa3b, v15
	v_exp_f32_e32 v5, v5
	v_and_b32_e32 v13, 0xffff0000, v13
	v_lshlrev_b32_e32 v10, 16, v11
	v_and_b32_e32 v11, 0xffff0000, v11
	v_add_f32_e32 v5, 1.0, v5
	v_rcp_f32_e32 v17, v5
	v_pk_mul_f32 v[18:19], v[4:5], v[18:19] op_sel_hi:[0,1]
	s_waitcnt vmcnt(9)
	v_pk_mul_f32 v[0:1], v[0:1], v[18:19]
	v_pk_mul_f32 v[10:11], v[4:5], v[10:11] op_sel_hi:[0,1]
	v_pk_mul_f32 v[14:15], v[16:17], v[14:15]
	v_pk_mul_f32 v[2:3], v[2:3], v[10:11]
	v_pk_mul_f32 v[0:1], v[0:1], v[14:15]
	s_nop 0
	v_cvt_pk_bf16_f32 v0, v0, v1
	v_mul_f32_e32 v1, 0xbfb8aa3b, v12
	v_exp_f32_e32 v1, v1
	s_nop 0
	v_add_f32_e32 v1, 1.0, v1
	v_rcp_f32_e32 v14, v1
	v_mul_f32_e32 v1, 0xbfb8aa3b, v13
	v_exp_f32_e32 v1, v1
	s_nop 0
	v_add_f32_e32 v1, 1.0, v1
	v_rcp_f32_e32 v15, v1
	s_nop 0
	v_pk_mul_f32 v[10:11], v[14:15], v[12:13]
	s_nop 0
	v_pk_mul_f32 v[2:3], v[2:3], v[10:11]
	s_nop 0
	v_cvt_pk_bf16_f32 v1, v2, v3
	global_store_dwordx2 v[94:95], v[0:1], off offset:64
	s_nop 0
	s_waitcnt vmcnt(9)
	v_lshlrev_b32_e32 v18, 16, v212
	s_waitcnt vmcnt(8)
	v_lshlrev_b32_e32 v14, 16, v210
	v_mul_f32_e32 v5, 0xbfb8aa3b, v14
	v_exp_f32_e32 v5, v5
	v_and_b32_e32 v15, 0xffff0000, v210
	v_and_b32_e32 v19, 0xffff0000, v212
	v_lshlrev_b32_e32 v12, 16, v211
	v_add_f32_e32 v5, 1.0, v5
	v_rcp_f32_e32 v16, v5
	v_mul_f32_e32 v5, 0xbfb8aa3b, v15
	v_exp_f32_e32 v5, v5
	v_and_b32_e32 v13, 0xffff0000, v211
	v_lshlrev_b32_e32 v10, 16, v213
	v_and_b32_e32 v11, 0xffff0000, v213
	v_add_f32_e32 v5, 1.0, v5
	v_rcp_f32_e32 v17, v5
	v_pk_mul_f32 v[18:19], v[4:5], v[18:19] op_sel_hi:[0,1]
	s_waitcnt vmcnt(7)
	v_pk_mul_f32 v[0:1], v[206:207], v[18:19]
	v_pk_mul_f32 v[10:11], v[4:5], v[10:11] op_sel_hi:[0,1]
	v_pk_mul_f32 v[14:15], v[16:17], v[14:15]
	v_pk_mul_f32 v[2:3], v[208:209], v[10:11]
	v_pk_mul_f32 v[0:1], v[0:1], v[14:15]
	s_nop 0
	v_cvt_pk_bf16_f32 v0, v0, v1
	v_mul_f32_e32 v1, 0xbfb8aa3b, v12
	v_exp_f32_e32 v1, v1
	s_nop 0
	v_add_f32_e32 v1, 1.0, v1
	v_rcp_f32_e32 v14, v1
	v_mul_f32_e32 v1, 0xbfb8aa3b, v13
	v_exp_f32_e32 v1, v1
	s_nop 0
	v_add_f32_e32 v1, 1.0, v1
	v_rcp_f32_e32 v15, v1
	s_nop 0
	v_pk_mul_f32 v[10:11], v[14:15], v[12:13]
	s_nop 0
	v_pk_mul_f32 v[2:3], v[2:3], v[10:11]
	s_nop 0
	v_cvt_pk_bf16_f32 v1, v2, v3
	global_store_dwordx2 v[94:95], v[0:1], off offset:80
	s_nop 0
	s_waitcnt vmcnt(7)
	v_lshlrev_b32_e32 v18, 16, v220
	s_waitcnt vmcnt(6)
	v_lshlrev_b32_e32 v14, 16, v218
	v_mul_f32_e32 v5, 0xbfb8aa3b, v14
	v_exp_f32_e32 v5, v5
	v_and_b32_e32 v15, 0xffff0000, v218
	v_and_b32_e32 v19, 0xffff0000, v220
	v_lshlrev_b32_e32 v12, 16, v219
	v_add_f32_e32 v5, 1.0, v5
	v_rcp_f32_e32 v16, v5
	v_mul_f32_e32 v5, 0xbfb8aa3b, v15
	v_exp_f32_e32 v5, v5
	v_and_b32_e32 v13, 0xffff0000, v219
	v_lshlrev_b32_e32 v10, 16, v221
	v_and_b32_e32 v11, 0xffff0000, v221
	v_add_f32_e32 v5, 1.0, v5
	v_rcp_f32_e32 v17, v5
	v_pk_mul_f32 v[18:19], v[4:5], v[18:19] op_sel_hi:[0,1]
	s_waitcnt vmcnt(5)
	v_pk_mul_f32 v[0:1], v[214:215], v[18:19]
	v_pk_mul_f32 v[10:11], v[4:5], v[10:11] op_sel_hi:[0,1]
	v_pk_mul_f32 v[14:15], v[16:17], v[14:15]
	v_pk_mul_f32 v[2:3], v[216:217], v[10:11]
	v_pk_mul_f32 v[0:1], v[0:1], v[14:15]
	s_nop 0
	v_cvt_pk_bf16_f32 v0, v0, v1
	v_mul_f32_e32 v1, 0xbfb8aa3b, v12
	v_exp_f32_e32 v1, v1
	s_nop 0
	v_add_f32_e32 v1, 1.0, v1
	v_rcp_f32_e32 v14, v1
	v_mul_f32_e32 v1, 0xbfb8aa3b, v13
	v_exp_f32_e32 v1, v1
	s_nop 0
	v_add_f32_e32 v1, 1.0, v1
	v_rcp_f32_e32 v15, v1
	s_nop 0
	v_pk_mul_f32 v[10:11], v[14:15], v[12:13]
	s_nop 0
	v_pk_mul_f32 v[2:3], v[2:3], v[10:11]
	s_nop 0
	v_cvt_pk_bf16_f32 v1, v2, v3
	global_store_dwordx2 v[94:95], v[0:1], off offset:96
	s_nop 0
	s_nop 0
	s_waitcnt vmcnt(5)
	v_lshlrev_b32_e32 v14, 16, v228
	s_waitcnt vmcnt(4)
	v_lshlrev_b32_e32 v10, 16, v226
	v_mul_f32_e32 v5, 0xbfb8aa3b, v10
	v_exp_f32_e32 v5, v5
	v_and_b32_e32 v11, 0xffff0000, v226
	v_lshlrev_b32_e32 v2, 16, v227
	v_and_b32_e32 v15, 0xffff0000, v228
	v_add_f32_e32 v5, 1.0, v5
	v_rcp_f32_e32 v12, v5
	v_mul_f32_e32 v5, 0xbfb8aa3b, v11
	v_exp_f32_e32 v5, v5
	v_and_b32_e32 v3, 0xffff0000, v227
	v_add_f32_e32 v5, 1.0, v5
	v_rcp_f32_e32 v13, v5
	v_pk_mul_f32 v[14:15], v[4:5], v[14:15] op_sel_hi:[0,1]
	v_mul_f32_e32 v5, 0xbfb8aa3b, v2
	v_exp_f32_e32 v5, v5
	s_waitcnt vmcnt(3)
	v_pk_mul_f32 v[6:7], v[222:223], v[14:15]
	v_pk_mul_f32 v[10:11], v[12:13], v[10:11]
	v_add_f32_e32 v5, 1.0, v5
	v_pk_mul_f32 v[6:7], v[6:7], v[10:11]
	v_lshlrev_b32_e32 v10, 16, v229
	v_cvt_pk_bf16_f32 v0, v6, v7
	v_rcp_f32_e32 v6, v5
	v_mul_f32_e32 v5, 0xbfb8aa3b, v3
	v_exp_f32_e32 v5, v5
	v_and_b32_e32 v11, 0xffff0000, v229
	v_add_f32_e32 v5, 1.0, v5
	v_rcp_f32_e32 v7, v5
	v_pk_mul_f32 v[4:5], v[4:5], v[10:11] op_sel_hi:[0,1]
	v_pk_mul_f32 v[4:5], v[224:225], v[4:5]
	v_pk_mul_f32 v[2:3], v[6:7], v[2:3]
	s_nop 0
	v_pk_mul_f32 v[2:3], v[4:5], v[2:3]
	s_nop 0
	v_cvt_pk_bf16_f32 v1, v2, v3
	global_store_dwordx2 v[94:95], v[0:1], off offset:112
	s_branch .LBB0_338
